# k20_gemmloops
# speedup vs baseline: 1.0043x; 1.0043x over previous
; DI f32x16 mfma32(bf16x8 a, bf16x8 b, f32x16 c) { return __builtin_amdgcn_mfma_f32_32x32x16_bf16(a, b, c, 0, 0, 0); }
; template <int NT, class Epi>
; DI void gemm_tile(const u16* __restrict__ A, int lda, const u16* __restrict__ Bt, int ldb, int K, int m0, int n0, const Epi& epi, char* smem) {
;     ...
;   for (int kt = 0; kt < nk; ++kt) {
; #pragma unroll
;     for (int i = 0; i < 4; ++i) *(u32x4*)(As + (lrow + 32 * i) * 72 + lch * 8) = ra[i];
; #pragma unroll
;     for (int i = 0; i < NB8; ++i) *(u32x4*)(Bs + (lrow + 32 * i) * 72 + lch * 8) = rb[i];
;     __syncthreads();
;     if (kt + 1 < nk) {
;       const int k0 = (kt + 1) * 64;
; #pragma unroll
;       for (int i = 0; i < 4; ++i) ra[i] = *(const u32x4*)(Ap + (size_t)(32 * i) * lda + k0);
; #pragma unroll
;       for (int i = 0; i < NB8; ++i) rb[i] = *(const u32x4*)(Bp + (size_t)(32 * i) * ldb + k0);
;     }
; #pragma unroll
;     for (int ks = 0; ks < 4; ++ks) {
;       bf16x8 a[2], b[NT];
; #pragma unroll
;       for (int mt = 0; mt < 2; ++mt) a[mt] = *(const bf16x8*)(As + (wm * 64 + mt * 32 + r) * 72 + ks * 16 + h * 8);
; #pragma unroll
;       for (int nt = 0; nt < NT; ++nt) b[nt] = *(const bf16x8*)(Bs + (wn * 32 * NT + nt * 32 + r) * 72 + ks * 16 + h * 8);
; #pragma unroll
;       for (int mt = 0; mt < 2; ++mt)
; #pragma unroll
;         for (int nt = 0; nt < NT; ++nt) acc[mt][nt] = mfma32(a[mt], b[nt], acc[mt][nt]);
;     }
;     __syncthreads();
;   }
.LBB0_97:
	s_waitcnt vmcnt(11)
	ds_write_b128 v185, v[128:131]
	s_waitcnt vmcnt(10)
	ds_write_b128 v185, v[132:135] offset:4608
	s_waitcnt vmcnt(9)
	ds_write_b128 v185, v[136:139] offset:9216
	s_waitcnt vmcnt(8)
	ds_write_b128 v185, v[140:143] offset:13824
	s_waitcnt vmcnt(7)
	ds_write_b128 v185, v[144:147] offset:18432
	s_waitcnt vmcnt(6)
	ds_write_b128 v185, v[148:151] offset:23040
	s_waitcnt vmcnt(5)
	ds_write_b128 v185, v[152:155] offset:27648
	s_waitcnt vmcnt(4)
	ds_write_b128 v185, v[156:159] offset:32256
	s_waitcnt vmcnt(3)
	ds_write_b128 v185, v[160:163] offset:36864
	s_waitcnt vmcnt(2)
	ds_write_b128 v185, v[164:167] offset:41472
	s_waitcnt vmcnt(1)
	ds_write_b128 v185, v[168:171] offset:46080
	s_waitcnt vmcnt(0)
	ds_write_b128 v185, v[172:175] offset:50688
	s_waitcnt lgkmcnt(0)
	s_barrier
	s_add_u32 s92, s8, s39
	s_addc_u32 s93, s9, 0
	v_lshl_add_u64 v[238:239], v[200:201], 0, s[92:93]
	global_load_dwordx4 v[128:131], v[238:239], off offset:128
	s_add_u32 s92, s8, s40
	s_addc_u32 s93, s9, 0
	v_lshl_add_u64 v[238:239], v[200:201], 0, s[92:93]
	global_load_dwordx4 v[132:135], v[238:239], off offset:128
	s_add_u32 s92, s8, s41
	s_addc_u32 s93, s9, 0
	v_lshl_add_u64 v[238:239], v[200:201], 0, s[92:93]
	global_load_dwordx4 v[136:139], v[238:239], off offset:128
	s_add_u32 s92, s8, s42
	s_addc_u32 s93, s9, 0
	v_lshl_add_u64 v[238:239], v[200:201], 0, s[92:93]
	global_load_dwordx4 v[140:143], v[238:239], off offset:128
	s_add_u32 s92, s8, s43
	s_addc_u32 s93, s9, 0
	v_lshl_add_u64 v[238:239], v[202:203], 0, s[92:93]
	global_load_dwordx4 v[144:147], v[238:239], off offset:128
	s_add_u32 s92, s8, s44
	s_addc_u32 s93, s9, 0
	v_lshl_add_u64 v[238:239], v[202:203], 0, s[92:93]
	global_load_dwordx4 v[148:151], v[238:239], off offset:128
	s_add_u32 s92, s8, s45
	s_addc_u32 s93, s9, 0
	v_lshl_add_u64 v[238:239], v[202:203], 0, s[92:93]
	global_load_dwordx4 v[152:155], v[238:239], off offset:128
	s_add_u32 s92, s8, s58
	s_addc_u32 s93, s9, 0
	v_lshl_add_u64 v[238:239], v[202:203], 0, s[92:93]
	global_load_dwordx4 v[156:159], v[238:239], off offset:128
	s_add_u32 s92, s8, s59
	s_addc_u32 s93, s9, 0
	v_lshl_add_u64 v[238:239], v[202:203], 0, s[92:93]
	global_load_dwordx4 v[160:163], v[238:239], off offset:128
	s_add_u32 s92, s8, s60
	s_addc_u32 s93, s9, 0
	v_lshl_add_u64 v[238:239], v[202:203], 0, s[92:93]
	global_load_dwordx4 v[164:167], v[238:239], off offset:128
	s_add_u32 s92, s8, s61
	s_addc_u32 s93, s9, 0
	v_lshl_add_u64 v[238:239], v[202:203], 0, s[92:93]
	global_load_dwordx4 v[168:171], v[238:239], off offset:128
	s_add_u32 s92, s8, s62
	s_addc_u32 s93, s9, 0
	v_lshl_add_u64 v[238:239], v[202:203], 0, s[92:93]
	global_load_dwordx4 v[172:175], v[238:239], off offset:128
	s_add_u32 s8, s8, 0x80
	s_addc_u32 s9, s9, 0
	s_cmpk_lg_i32 s8, 0x780
	ds_read_b128 v[204:207], v187
	ds_read_b128 v[252:255], v189 offset:18432
	ds_read_b128 v[248:251], v189 offset:23040
	ds_read_b128 v[244:247], v189 offset:27648
	ds_read_b128 v[240:243], v189 offset:32256
	ds_read_b128 v[208:211], v187 offset:4608
	s_waitcnt lgkmcnt(4)
	v_mfma_f32_32x32x16_bf16 v[112:127], v[204:207], v[252:255], v[112:127]
	s_waitcnt lgkmcnt(3)
	v_mfma_f32_32x32x16_bf16 v[96:111], v[204:207], v[248:251], v[96:111]
	s_waitcnt lgkmcnt(2)
	v_mfma_f32_32x32x16_bf16 v[80:95], v[204:207], v[244:247], v[80:95]
	s_waitcnt lgkmcnt(1)
	v_mfma_f32_32x32x16_bf16 v[64:79], v[204:207], v[240:243], v[64:79]
	ds_read_b128 v[204:207], v187 offset:32
	s_waitcnt lgkmcnt(1)
	v_mfma_f32_32x32x16_bf16 v[48:63], v[208:211], v[252:255], v[48:63]
	ds_read_b128 v[252:255], v189 offset:18464
	v_mfma_f32_32x32x16_bf16 v[32:47], v[208:211], v[248:251], v[32:47]
	ds_read_b128 v[248:251], v189 offset:23072
	v_mfma_f32_32x32x16_bf16 v[16:31], v[208:211], v[244:247], v[16:31]
	ds_read_b128 v[244:247], v189 offset:27680
	v_mfma_f32_32x32x16_bf16 v[0:15], v[208:211], v[240:243], v[0:15]
	ds_read_b128 v[240:243], v189 offset:32288
	ds_read_b128 v[208:211], v187 offset:4640
	s_waitcnt lgkmcnt(4)
	v_mfma_f32_32x32x16_bf16 v[112:127], v[204:207], v[252:255], v[112:127]
	s_waitcnt lgkmcnt(3)
	v_mfma_f32_32x32x16_bf16 v[96:111], v[204:207], v[248:251], v[96:111]
	s_waitcnt lgkmcnt(2)
	v_mfma_f32_32x32x16_bf16 v[80:95], v[204:207], v[244:247], v[80:95]
	s_waitcnt lgkmcnt(1)
	v_mfma_f32_32x32x16_bf16 v[64:79], v[204:207], v[240:243], v[64:79]
	ds_read_b128 v[204:207], v187 offset:64
	s_waitcnt lgkmcnt(1)
	v_mfma_f32_32x32x16_bf16 v[48:63], v[208:211], v[252:255], v[48:63]
	ds_read_b128 v[252:255], v189 offset:18496
	v_mfma_f32_32x32x16_bf16 v[32:47], v[208:211], v[248:251], v[32:47]
	ds_read_b128 v[248:251], v189 offset:23104
	v_mfma_f32_32x32x16_bf16 v[16:31], v[208:211], v[244:247], v[16:31]
	ds_read_b128 v[244:247], v189 offset:27712
	v_mfma_f32_32x32x16_bf16 v[0:15], v[208:211], v[240:243], v[0:15]
	ds_read_b128 v[240:243], v189 offset:32320
	ds_read_b128 v[208:211], v187 offset:4672
	s_waitcnt lgkmcnt(4)
	v_mfma_f32_32x32x16_bf16 v[112:127], v[204:207], v[252:255], v[112:127]
	s_waitcnt lgkmcnt(3)
	v_mfma_f32_32x32x16_bf16 v[96:111], v[204:207], v[248:251], v[96:111]
	s_waitcnt lgkmcnt(2)
	v_mfma_f32_32x32x16_bf16 v[80:95], v[204:207], v[244:247], v[80:95]
	s_waitcnt lgkmcnt(1)
	v_mfma_f32_32x32x16_bf16 v[64:79], v[204:207], v[240:243], v[64:79]
	ds_read_b128 v[204:207], v187 offset:96
	s_waitcnt lgkmcnt(1)
	v_mfma_f32_32x32x16_bf16 v[48:63], v[208:211], v[252:255], v[48:63]
	ds_read_b128 v[252:255], v189 offset:18528
	v_mfma_f32_32x32x16_bf16 v[32:47], v[208:211], v[248:251], v[32:47]
	ds_read_b128 v[248:251], v189 offset:23136
	v_mfma_f32_32x32x16_bf16 v[16:31], v[208:211], v[244:247], v[16:31]
	ds_read_b128 v[244:247], v189 offset:27744
	v_mfma_f32_32x32x16_bf16 v[0:15], v[208:211], v[240:243], v[0:15]
	ds_read_b128 v[240:243], v189 offset:32352
	ds_read_b128 v[208:211], v187 offset:4704
	s_waitcnt lgkmcnt(4)
	v_mfma_f32_32x32x16_bf16 v[112:127], v[204:207], v[252:255], v[112:127]
	s_waitcnt lgkmcnt(3)
	v_mfma_f32_32x32x16_bf16 v[96:111], v[204:207], v[248:251], v[96:111]
	s_waitcnt lgkmcnt(2)
	v_mfma_f32_32x32x16_bf16 v[80:95], v[204:207], v[244:247], v[80:95]
	s_waitcnt lgkmcnt(1)
	v_mfma_f32_32x32x16_bf16 v[64:79], v[204:207], v[240:243], v[64:79]
	s_waitcnt lgkmcnt(0)
	v_mfma_f32_32x32x16_bf16 v[48:63], v[208:211], v[252:255], v[48:63]
	v_mfma_f32_32x32x16_bf16 v[32:47], v[208:211], v[248:251], v[32:47]
	v_mfma_f32_32x32x16_bf16 v[16:31], v[208:211], v[244:247], v[16:31]
	s_barrier
; DI int crow(int i, int h) { return (i & 3) + 8 * (i >> 2) + 4 * h; }
; DI f32x16 mfma32(bf16x8 a, bf16x8 b, f32x16 c) { return __builtin_amdgcn_mfma_f32_32x32x16_bf16(a, b, c, 0, 0, 0); }
; template <int NT, class Epi>
; DI void gemm_tile(const u16* __restrict__ A, int lda, const u16* __restrict__ Bt, int ldb, int K, int m0, int n0, const Epi& epi, char* smem) {
;     ...
; #pragma unroll
;     for (int ks = 0; ks < 4; ++ks) {
;       bf16x8 a[2], b[NT];
; #pragma unroll
;       for (int mt = 0; mt < 2; ++mt) a[mt] = *(const bf16x8*)(As + (wm * 64 + mt * 32 + r) * 72 + ks * 16 + h * 8);
; #pragma unroll
;       for (int nt = 0; nt < NT; ++nt) b[nt] = *(const bf16x8*)(Bs + (wn * 32 * NT + nt * 32 + r) * 72 + ks * 16 + h * 8);
; #pragma unroll
;       for (int mt = 0; mt < 2; ++mt)
; #pragma unroll
;         for (int nt = 0; nt < NT; ++nt) acc[mt][nt] = mfma32(a[mt], b[nt], acc[mt][nt]);
;     }
;     __syncthreads();
;   DI void operator()(const f32x16& acc, int row0, int col0, int lane) const {
;     if (col0 >= 1440) return;
;     const int r = lane & 31, h = lane >> 5, col = col0 + r;
;     const float sc = col0 < 512 ? QS_SWA : 1.f;
; #pragma unroll
;     for (int i = 0; i < 16; ++i) C[(size_t)(row0 + crow(i, h)) * 1440 + col] = f2bf(acc[i] * sc);
;   }
	v_mfma_f32_32x32x16_bf16 v[0:15], v[208:211], v[240:243], v[0:15]
	s_cbranch_scc1 .LBB0_97
	s_waitcnt vmcnt(11)
	ds_write_b128 v185, v[128:131]
	s_waitcnt vmcnt(10)
	ds_write_b128 v185, v[132:135] offset:4608
	s_waitcnt vmcnt(9)
	ds_write_b128 v185, v[136:139] offset:9216
	s_waitcnt vmcnt(8)
	ds_write_b128 v185, v[140:143] offset:13824
	s_waitcnt vmcnt(7)
	ds_write_b128 v185, v[144:147] offset:18432
	s_waitcnt vmcnt(6)
	ds_write_b128 v185, v[148:151] offset:23040
	s_waitcnt vmcnt(5)
	ds_write_b128 v185, v[152:155] offset:27648
	s_waitcnt vmcnt(4)
	ds_write_b128 v185, v[156:159] offset:32256
	s_waitcnt vmcnt(3)
	ds_write_b128 v185, v[160:163] offset:36864
	s_waitcnt vmcnt(2)
	ds_write_b128 v185, v[164:167] offset:41472
	s_waitcnt vmcnt(1)
	ds_write_b128 v185, v[168:171] offset:46080
	s_waitcnt vmcnt(0)
	ds_write_b128 v185, v[172:175] offset:50688
	s_waitcnt lgkmcnt(0)
	s_barrier
	ds_read_b128 v[128:131], v187 offset:4608
	ds_read_b128 v[132:135], v189 offset:23040
	ds_read_b128 v[136:139], v189 offset:27648
	ds_read_b128 v[140:143], v189 offset:32256
	ds_read_b128 v[144:147], v187
	ds_read_b128 v[148:151], v187 offset:32
	ds_read_b128 v[152:155], v189 offset:18432
	ds_read_b128 v[156:159], v189 offset:18464
	s_waitcnt lgkmcnt(1)
	v_mfma_f32_32x32x16_bf16 v[112:127], v[144:147], v[152:155], v[112:127]
	s_and_b32 s8, 0xffff, s10
	s_cmp_lt_u32 s8, 2
	s_cselect_b64 vcc, -1, 0
	v_mfma_f32_32x32x16_bf16 v[80:95], v[144:147], v[136:139], v[80:95]
	v_mfma_f32_32x32x16_bf16 v[16:31], v[128:131], v[136:139], v[16:31]
	v_mfma_f32_32x32x16_bf16 v[96:111], v[144:147], v[132:135], v[96:111]
	v_mfma_f32_32x32x16_bf16 v[64:79], v[144:147], v[140:143], v[64:79]
	v_mfma_f32_32x32x16_bf16 v[48:63], v[128:131], v[152:155], v[48:63]
	v_mfma_f32_32x32x16_bf16 v[32:47], v[128:131], v[132:135], v[32:47]
	v_mfma_f32_32x32x16_bf16 v[0:15], v[128:131], v[140:143], v[0:15]
	ds_read_b128 v[128:131], v187 offset:4640
	ds_read_b128 v[132:135], v189 offset:23072
	ds_read_b128 v[136:139], v189 offset:27680
	ds_read_b128 v[140:143], v189 offset:32288
	s_waitcnt lgkmcnt(4)
	v_mfma_f32_32x32x16_bf16 v[112:127], v[148:151], v[156:159], v[112:127]
	s_waitcnt lgkmcnt(1)
	v_mfma_f32_32x32x16_bf16 v[80:95], v[148:151], v[136:139], v[80:95]
	v_mfma_f32_32x32x16_bf16 v[16:31], v[128:131], v[136:139], v[16:31]
	v_mfma_f32_32x32x16_bf16 v[96:111], v[148:151], v[132:135], v[96:111]
	s_waitcnt lgkmcnt(0)
	v_mfma_f32_32x32x16_bf16 v[64:79], v[148:151], v[140:143], v[64:79]
	v_mfma_f32_32x32x16_bf16 v[48:63], v[128:131], v[156:159], v[48:63]
	v_mfma_f32_32x32x16_bf16 v[32:47], v[128:131], v[132:135], v[32:47]
	v_mfma_f32_32x32x16_bf16 v[0:15], v[128:131], v[140:143], v[0:15]
	ds_read_b128 v[128:131], v187 offset:64
	ds_read_b128 v[132:135], v187 offset:4672
	ds_read_b128 v[136:139], v189 offset:18496
	ds_read_b128 v[140:143], v189 offset:23104
	ds_read_b128 v[144:147], v189 offset:27712
	ds_read_b128 v[148:151], v189 offset:32320
	s_waitcnt lgkmcnt(3)
	v_mfma_f32_32x32x16_bf16 v[112:127], v[128:131], v[136:139], v[112:127]
	s_waitcnt lgkmcnt(1)
	v_mfma_f32_32x32x16_bf16 v[80:95], v[128:131], v[144:147], v[80:95]
	v_mfma_f32_32x32x16_bf16 v[16:31], v[132:135], v[144:147], v[16:31]
	v_mfma_f32_32x32x16_bf16 v[96:111], v[128:131], v[140:143], v[96:111]
	s_waitcnt lgkmcnt(0)
	v_mfma_f32_32x32x16_bf16 v[64:79], v[128:131], v[148:151], v[64:79]
	v_mfma_f32_32x32x16_bf16 v[48:63], v[132:135], v[136:139], v[48:63]
	v_mfma_f32_32x32x16_bf16 v[32:47], v[132:135], v[140:143], v[32:47]
	v_mfma_f32_32x32x16_bf16 v[0:15], v[132:135], v[148:151], v[0:15]
	ds_read_b128 v[128:131], v187 offset:96
	ds_read_b128 v[132:135], v187 offset:4704
	ds_read_b128 v[136:139], v189 offset:18528
	ds_read_b128 v[140:143], v189 offset:23136
	ds_read_b128 v[144:147], v189 offset:27744
	ds_read_b128 v[148:151], v189 offset:32352
	s_waitcnt lgkmcnt(0)
	s_barrier
	v_mfma_f32_32x32x16_bf16 v[112:127], v[128:131], v[136:139], v[112:127]
	v_mfma_f32_32x32x16_bf16 v[80:95], v[128:131], v[144:147], v[80:95]
	v_mfma_f32_32x32x16_bf16 v[16:31], v[132:135], v[144:147], v[16:31]
	v_or_b32_e32 v146, s12, v179
	v_add_u32_e32 v147, s11, v181
	v_or_b32_e32 v144, 9, v147
	v_or_b32_e32 v145, 10, v147
	v_or_b32_e32 v174, 16, v147
	v_or_b32_e32 v175, 17, v147
	v_or_b32_e32 v200, 18, v147
	v_mfma_f32_32x32x16_bf16 v[96:111], v[128:131], v[140:143], v[96:111]
	v_or_b32_e32 v201, 19, v147
	v_or_b32_e32 v202, 24, v147
	v_or_b32_e32 v203, 25, v147
	v_or_b32_e32 v204, 26, v147
	v_or_b32_e32 v205, 27, v147
	v_mul_hi_u32_u24_e32 v153, 0xb40, v144
	v_mul_u32_u24_e32 v152, 0xb40, v144
	v_mfma_f32_32x32x16_bf16 v[64:79], v[128:131], v[148:151], v[64:79]
	v_or_b32_e32 v128, v146, v177
	v_lshlrev_b32_e32 v192, 1, v128
	v_lshl_add_u64 v[128:129], s[52:53], 0, v[192:193]
	v_mul_hi_u32_u24_e32 v131, 0xb40, v147
	v_mul_u32_u24_e32 v130, 0xb40, v147
	v_mul_hi_u32_u24_e32 v155, 0xb40, v145
	v_mul_u32_u24_e32 v154, 0xb40, v145
	v_mfma_f32_32x32x16_bf16 v[0:15], v[132:135], v[148:151], v[0:15]
	v_cndmask_b32_e32 v148, 1.0, v191, vcc
	v_mul_f32_e32 v112, v148, v112
	v_cvt_pk_bf16_f32 v112, v112, s0
	v_or_b32_e32 v149, 11, v147
	v_mul_hi_u32_u24_e32 v157, 0xb40, v149
	v_mul_u32_u24_e32 v156, 0xb40, v149
	v_mul_hi_u32_u24_e32 v159, 0xb40, v174
	v_mfma_f32_32x32x16_bf16 v[48:63], v[132:135], v[136:139], v[48:63]
	v_mad_u64_u32 v[138:139], s[8:9], v147, s63, v[128:129]
	global_store_short v[138:139], v112, off
	v_mul_f32_e32 v112, v148, v113
	v_cvt_pk_bf16_f32 v138, v112, s0
	v_mul_u32_u24_e32 v158, 0xb40, v174
	v_mul_hi_u32_u24_e32 v161, 0xb40, v175
	v_mfma_f32_32x32x16_bf16 v[32:47], v[132:135], v[140:143], v[32:47]
	v_or_b32_e32 v140, 1, v147
; DI int crow(int i, int h) { return (i & 3) + 8 * (i >> 2) + 4 * h; }
; template <int NT, class Epi>
; DI void gemm_tile(const u16* __restrict__ A, int lda, const u16* __restrict__ Bt, int ldb, int K, int m0, int n0, const Epi& epi, char* smem) {
;     ...
; #pragma unroll
;   for (int mt = 0; mt < 2; ++mt)
; #pragma unroll
;     for (int nt = 0; nt < NT; ++nt) epi(acc[mt][nt], m0 + wm * 64 + mt * 32, n0 + wn * 32 * NT + nt * 32, lane);
;   DI void operator()(const f32x16& acc, int row0, int col0, int lane) const {
;     if (col0 >= 1440) return;
;     const int r = lane & 31, h = lane >> 5, col = col0 + r;
;     const float sc = col0 < 512 ? QS_SWA : 1.f;
; #pragma unroll
;     for (int i = 0; i < 16; ++i) C[(size_t)(row0 + crow(i, h)) * 1440 + col] = f2bf(acc[i] * sc);
;   }
	v_mad_u64_u32 v[112:113], s[8:9], v140, s63, v[128:129]
	v_or_b32_e32 v141, 2, v147
	global_store_short v[112:113], v138, off
	v_mul_f32_e32 v112, v148, v114
	v_cvt_pk_bf16_f32 v114, v112, s0
	v_mad_u64_u32 v[112:113], s[8:9], v141, s63, v[128:129]
	v_or_b32_e32 v142, 3, v147
	global_store_short v[112:113], v114, off
	v_mul_f32_e32 v112, v148, v115
	v_cvt_pk_bf16_f32 v114, v112, s0
	v_mad_u64_u32 v[112:113], s[8:9], v142, s63, v[128:129]
	v_or_b32_e32 v143, 8, v147
	global_store_short v[112:113], v114, off
	v_mul_f32_e32 v112, v148, v116
	v_cvt_pk_bf16_f32 v114, v112, s0
	v_mad_u64_u32 v[112:113], s[8:9], v143, s63, v[128:129]
	global_store_short v[112:113], v114, off
	v_mul_f32_e32 v112, v148, v117
	v_cvt_pk_bf16_f32 v114, v112, s0
	v_mad_u64_u32 v[112:113], s[8:9], v144, s63, v[128:129]
	global_store_short v[112:113], v114, off
	v_mul_f32_e32 v112, v148, v118
	v_cvt_pk_bf16_f32 v114, v112, s0
	v_mad_u64_u32 v[112:113], s[8:9], v145, s63, v[128:129]
	global_store_short v[112:113], v114, off
	v_mul_f32_e32 v112, v148, v119
	v_cvt_pk_bf16_f32 v114, v112, s0
	v_mad_u64_u32 v[112:113], s[8:9], v149, s63, v[128:129]
	global_store_short v[112:113], v114, off
	v_mul_f32_e32 v112, v148, v120
	v_cvt_pk_bf16_f32 v114, v112, s0
	v_mad_u64_u32 v[112:113], s[8:9], v174, s63, v[128:129]
	global_store_short v[112:113], v114, off
	v_mul_f32_e32 v112, v148, v121
	v_cvt_pk_bf16_f32 v114, v112, s0
	v_mad_u64_u32 v[112:113], s[8:9], v175, s63, v[128:129]
	global_store_short v[112:113], v114, off
	v_mul_f32_e32 v112, v148, v122
	v_cvt_pk_bf16_f32 v114, v112, s0
	v_mad_u64_u32 v[112:113], s[8:9], v200, s63, v[128:129]
	global_store_short v[112:113], v114, off
	v_mul_f32_e32 v112, v148, v123
	v_cvt_pk_bf16_f32 v114, v112, s0
	v_mad_u64_u32 v[112:113], s[8:9], v201, s63, v[128:129]
	global_store_short v[112:113], v114, off
	v_mul_f32_e32 v112, v148, v124
	v_cvt_pk_bf16_f32 v114, v112, s0
	v_mad_u64_u32 v[112:113], s[8:9], v202, s63, v[128:129]
	global_store_short v[112:113], v114, off
	v_mul_f32_e32 v112, v148, v125
	v_cvt_pk_bf16_f32 v114, v112, s0
	v_mad_u64_u32 v[112:113], s[8:9], v203, s63, v[128:129]
	global_store_short v[112:113], v114, off
	v_mul_f32_e32 v112, v148, v126
	v_cvt_pk_bf16_f32 v114, v112, s0
	v_mad_u64_u32 v[112:113], s[8:9], v204, s63, v[128:129]
	global_store_short v[112:113], v114, off
	v_mul_f32_e32 v112, v148, v127
	v_cvt_pk_bf16_f32 v114, v112, s0
	v_mad_u64_u32 v[112:113], s[8:9], v205, s63, v[128:129]
	global_store_short v[112:113], v114, off
	v_or_b32_e32 v112, 32, v146
	v_mul_hi_u32_u24_e32 v133, 0xb40, v140
	v_mul_u32_u24_e32 v132, 0xb40, v140
	v_mul_hi_u32_u24_e32 v135, 0xb40, v141
	v_mul_u32_u24_e32 v134, 0xb40, v141
	v_mul_hi_u32_u24_e32 v137, 0xb40, v142
	v_mul_u32_u24_e32 v136, 0xb40, v142
	v_mul_hi_u32_u24_e32 v151, 0xb40, v143
	v_mul_u32_u24_e32 v150, 0xb40, v143
	v_mul_u32_u24_e32 v160, 0xb40, v175
	v_mul_hi_u32_u24_e32 v163, 0xb40, v200
	v_mul_u32_u24_e32 v162, 0xb40, v200
	v_mul_hi_u32_u24_e32 v165, 0xb40, v201
	v_mul_u32_u24_e32 v164, 0xb40, v201
	v_mul_hi_u32_u24_e32 v167, 0xb40, v202
	v_mul_u32_u24_e32 v166, 0xb40, v202
	v_mul_hi_u32_u24_e32 v169, 0xb40, v203
	v_mul_u32_u24_e32 v168, 0xb40, v203
	v_mul_hi_u32_u24_e32 v171, 0xb40, v204
	v_mul_u32_u24_e32 v170, 0xb40, v204
	v_mul_hi_u32_u24_e32 v173, 0xb40, v205
	v_mul_u32_u24_e32 v172, 0xb40, v205
	v_or_b32_e32 v149, v112, v177
	v_cmp_gt_u32_e32 vcc, s71, v146
	v_lshl_add_u64 v[144:145], s[52:53], 0, v[130:131]
	v_lshl_add_u64 v[142:143], s[52:53], 0, v[132:133]
	v_lshl_add_u64 v[140:141], s[52:53], 0, v[134:135]
	v_lshl_add_u64 v[138:139], s[52:53], 0, v[136:137]
	v_lshl_add_u64 v[136:137], s[52:53], 0, v[150:151]
	v_lshl_add_u64 v[134:135], s[52:53], 0, v[152:153]
	v_lshl_add_u64 v[132:133], s[52:53], 0, v[154:155]
	v_lshl_add_u64 v[130:131], s[52:53], 0, v[156:157]
	v_lshl_add_u64 v[126:127], s[52:53], 0, v[158:159]
	v_lshl_add_u64 v[124:125], s[52:53], 0, v[160:161]
	v_lshl_add_u64 v[122:123], s[52:53], 0, v[162:163]
	v_lshl_add_u64 v[120:121], s[52:53], 0, v[164:165]
	v_lshl_add_u64 v[118:119], s[52:53], 0, v[166:167]
	v_lshl_add_u64 v[116:117], s[52:53], 0, v[168:169]
	v_lshl_add_u64 v[114:115], s[52:53], 0, v[170:171]
	v_lshl_add_u64 v[112:113], s[52:53], 0, v[172:173]
	v_lshlrev_b32_e32 v192, 1, v149
	s_and_saveexec_b64 s[10:11], vcc
	s_cbranch_execz .LBB0_100
	v_cmp_gt_u32_e64 s[8:9], s74, v146
	v_lshl_add_u64 v[150:151], v[144:145], 0, v[192:193]
	s_nop 0
	v_cndmask_b32_e64 v149, 1.0, v191, s[8:9]
	v_mul_f32_e32 v96, v149, v96
	v_cvt_pk_bf16_f32 v96, v96, s0
	global_store_short v[150:151], v96, off
	v_mul_f32_e32 v96, v149, v97
	v_cvt_pk_bf16_f32 v150, v96, s0
	v_lshl_add_u64 v[96:97], v[142:143], 0, v[192:193]
	global_store_short v[96:97], v150, off
	v_mul_f32_e32 v96, v149, v98
	v_cvt_pk_bf16_f32 v98, v96, s0
	v_lshl_add_u64 v[96:97], v[140:141], 0, v[192:193]
	global_store_short v[96:97], v98, off
	v_mul_f32_e32 v96, v149, v99
	v_cvt_pk_bf16_f32 v98, v96, s0
	v_lshl_add_u64 v[96:97], v[138:139], 0, v[192:193]
	global_store_short v[96:97], v98, off
	v_mul_f32_e32 v96, v149, v100
	v_cvt_pk_bf16_f32 v98, v96, s0
	v_lshl_add_u64 v[96:97], v[136:137], 0, v[192:193]
	global_store_short v[96:97], v98, off
	v_mul_f32_e32 v96, v149, v101
	v_cvt_pk_bf16_f32 v98, v96, s0
	v_lshl_add_u64 v[96:97], v[134:135], 0, v[192:193]
	global_store_short v[96:97], v98, off
	v_mul_f32_e32 v96, v149, v102
	v_cvt_pk_bf16_f32 v98, v96, s0
	v_lshl_add_u64 v[96:97], v[132:133], 0, v[192:193]
	global_store_short v[96:97], v98, off
	v_mul_f32_e32 v96, v149, v103
	v_cvt_pk_bf16_f32 v98, v96, s0
	v_lshl_add_u64 v[96:97], v[130:131], 0, v[192:193]
	global_store_short v[96:97], v98, off
	v_mul_f32_e32 v96, v149, v104
	v_cvt_pk_bf16_f32 v98, v96, s0
	v_lshl_add_u64 v[96:97], v[126:127], 0, v[192:193]
	global_store_short v[96:97], v98, off
	v_mul_f32_e32 v96, v149, v105
	v_cvt_pk_bf16_f32 v98, v96, s0
	v_lshl_add_u64 v[96:97], v[124:125], 0, v[192:193]
	global_store_short v[96:97], v98, off
	v_mul_f32_e32 v96, v149, v106
	v_cvt_pk_bf16_f32 v98, v96, s0
	v_lshl_add_u64 v[96:97], v[122:123], 0, v[192:193]
	global_store_short v[96:97], v98, off
	v_mul_f32_e32 v96, v149, v107
	v_cvt_pk_bf16_f32 v98, v96, s0
	v_lshl_add_u64 v[96:97], v[120:121], 0, v[192:193]
	global_store_short v[96:97], v98, off
	v_mul_f32_e32 v96, v149, v108
	v_cvt_pk_bf16_f32 v98, v96, s0
	v_lshl_add_u64 v[96:97], v[118:119], 0, v[192:193]
	global_store_short v[96:97], v98, off
	v_mul_f32_e32 v96, v149, v109
	v_cvt_pk_bf16_f32 v98, v96, s0
	v_lshl_add_u64 v[96:97], v[116:117], 0, v[192:193]
	global_store_short v[96:97], v98, off
	v_mul_f32_e32 v96, v149, v110
	v_cvt_pk_bf16_f32 v98, v96, s0
	v_lshl_add_u64 v[96:97], v[114:115], 0, v[192:193]
	global_store_short v[96:97], v98, off
	v_mul_f32_e32 v96, v149, v111
	v_cvt_pk_bf16_f32 v98, v96, s0
	v_lshl_add_u64 v[96:97], v[112:113], 0, v[192:193]
	global_store_short v[96:97], v98, off

; DI f32x16 mfma32(bf16x8 a, bf16x8 b, f32x16 c) { return __builtin_amdgcn_mfma_f32_32x32x16_bf16(a, b, c, 0, 0, 0); }
; template <int NT, class Epi>
; DI void gemm_tile(const u16* __restrict__ A, int lda, const u16* __restrict__ Bt, int ldb, int K, int m0, int n0, const Epi& epi, char* smem) {
;     ...
;   for (int kt = 0; kt < nk; ++kt) {
; #pragma unroll
;     for (int i = 0; i < 4; ++i) *(u32x4*)(As + (lrow + 32 * i) * 72 + lch * 8) = ra[i];
; #pragma unroll
;     for (int i = 0; i < NB8; ++i) *(u32x4*)(Bs + (lrow + 32 * i) * 72 + lch * 8) = rb[i];
;     __syncthreads();
;     if (kt + 1 < nk) {
;       const int k0 = (kt + 1) * 64;
; #pragma unroll
;       for (int i = 0; i < 4; ++i) ra[i] = *(const u32x4*)(Ap + (size_t)(32 * i) * lda + k0);
; #pragma unroll
;       for (int i = 0; i < NB8; ++i) rb[i] = *(const u32x4*)(Bp + (size_t)(32 * i) * ldb + k0);
;     }
; #pragma unroll
;     for (int ks = 0; ks < 4; ++ks) {
;       bf16x8 a[2], b[NT];
; #pragma unroll
;       for (int mt = 0; mt < 2; ++mt) a[mt] = *(const bf16x8*)(As + (wm * 64 + mt * 32 + r) * 72 + ks * 16 + h * 8);
; #pragma unroll
;       for (int nt = 0; nt < NT; ++nt) b[nt] = *(const bf16x8*)(Bs + (wn * 32 * NT + nt * 32 + r) * 72 + ks * 16 + h * 8);
; #pragma unroll
;       for (int mt = 0; mt < 2; ++mt)
; #pragma unroll
;         for (int nt = 0; nt < NT; ++nt) acc[mt][nt] = mfma32(a[mt], b[nt], acc[mt][nt]);
;     }
;     __syncthreads();
;   }
.LBB0_422:
	s_waitcnt vmcnt(11)
	ds_write_b128 v206, v[128:131]
	s_waitcnt vmcnt(10)
	ds_write_b128 v206, v[132:135] offset:4608
	s_waitcnt vmcnt(9)
	ds_write_b128 v206, v[136:139] offset:9216
	s_waitcnt vmcnt(8)
	ds_write_b128 v206, v[140:143] offset:13824
	s_waitcnt vmcnt(7)
	ds_write_b128 v206, v[144:147] offset:18432
	s_waitcnt vmcnt(6)
	ds_write_b128 v206, v[148:151] offset:23040
	s_waitcnt vmcnt(5)
	ds_write_b128 v206, v[152:155] offset:27648
	s_waitcnt vmcnt(4)
	ds_write_b128 v206, v[156:159] offset:32256
	s_waitcnt vmcnt(3)
	ds_write_b128 v206, v[160:163] offset:36864
	s_waitcnt vmcnt(2)
	ds_write_b128 v206, v[164:167] offset:41472
	s_waitcnt vmcnt(1)
	ds_write_b128 v206, v[168:171] offset:46080
	s_waitcnt vmcnt(0)
	ds_write_b128 v206, v[172:175] offset:50688
	s_waitcnt lgkmcnt(0)
	s_barrier
	s_add_u32 s92, s16, s30
	s_addc_u32 s93, s17, 0
	v_lshl_add_u64 v[238:239], v[202:203], 0, s[92:93]
	global_load_dwordx4 v[128:131], v[238:239], off offset:128
	s_add_u32 s92, s16, s31
	s_addc_u32 s93, s17, 0
	v_lshl_add_u64 v[238:239], v[202:203], 0, s[92:93]
	global_load_dwordx4 v[132:135], v[238:239], off offset:128
	s_add_u32 s92, s16, s34
	s_addc_u32 s93, s17, 0
	v_lshl_add_u64 v[238:239], v[202:203], 0, s[92:93]
	global_load_dwordx4 v[136:139], v[238:239], off offset:128
	s_add_u32 s92, s16, s35
	s_addc_u32 s93, s17, 0
	v_lshl_add_u64 v[238:239], v[202:203], 0, s[92:93]
	global_load_dwordx4 v[140:143], v[238:239], off offset:128
	s_add_u32 s92, s16, s38
	s_addc_u32 s93, s17, 0
	v_lshl_add_u64 v[238:239], v[204:205], 0, s[92:93]
	global_load_dwordx4 v[144:147], v[238:239], off offset:128
	s_add_u32 s92, s16, s39
	s_addc_u32 s93, s17, 0
	v_lshl_add_u64 v[238:239], v[204:205], 0, s[92:93]
	global_load_dwordx4 v[148:151], v[238:239], off offset:128
	s_add_u32 s92, s16, s40
	s_addc_u32 s93, s17, 0
	v_lshl_add_u64 v[238:239], v[204:205], 0, s[92:93]
	global_load_dwordx4 v[152:155], v[238:239], off offset:128
	s_add_u32 s92, s16, s41
	s_addc_u32 s93, s17, 0
	v_lshl_add_u64 v[238:239], v[204:205], 0, s[92:93]
	global_load_dwordx4 v[156:159], v[238:239], off offset:128
	s_add_u32 s92, s16, s42
	s_addc_u32 s93, s17, 0
	v_lshl_add_u64 v[238:239], v[204:205], 0, s[92:93]
	global_load_dwordx4 v[160:163], v[238:239], off offset:128
	s_add_u32 s92, s16, s43
	s_addc_u32 s93, s17, 0
	v_lshl_add_u64 v[238:239], v[204:205], 0, s[92:93]
	global_load_dwordx4 v[164:167], v[238:239], off offset:128
	s_add_u32 s92, s16, s44
	s_addc_u32 s93, s17, 0
	v_lshl_add_u64 v[238:239], v[204:205], 0, s[92:93]
	global_load_dwordx4 v[168:171], v[238:239], off offset:128
	s_add_u32 s92, s16, s45
	s_addc_u32 s93, s17, 0
	v_lshl_add_u64 v[238:239], v[204:205], 0, s[92:93]
	global_load_dwordx4 v[172:175], v[238:239], off offset:128
	s_add_u32 s16, s16, 0x80
	s_addc_u32 s17, s17, 0
	s_cmpk_lg_i32 s16, 0x780
	ds_read_b128 v[210:213], v207
	ds_read_b128 v[252:255], v208 offset:18432
	ds_read_b128 v[248:251], v208 offset:23040
	ds_read_b128 v[244:247], v208 offset:27648
	ds_read_b128 v[240:243], v208 offset:32256
	ds_read_b128 v[222:225], v207 offset:4608
	s_waitcnt lgkmcnt(4)
	v_mfma_f32_32x32x16_bf16 v[112:127], v[210:213], v[252:255], v[112:127]
	s_waitcnt lgkmcnt(3)
	v_mfma_f32_32x32x16_bf16 v[96:111], v[210:213], v[248:251], v[96:111]
	s_waitcnt lgkmcnt(2)
	v_mfma_f32_32x32x16_bf16 v[80:95], v[210:213], v[244:247], v[80:95]
	s_waitcnt lgkmcnt(1)
	v_mfma_f32_32x32x16_bf16 v[64:79], v[210:213], v[240:243], v[64:79]
	ds_read_b128 v[210:213], v207 offset:32
	s_waitcnt lgkmcnt(1)
	v_mfma_f32_32x32x16_bf16 v[48:63], v[222:225], v[252:255], v[48:63]
	ds_read_b128 v[252:255], v208 offset:18464
	v_mfma_f32_32x32x16_bf16 v[32:47], v[222:225], v[248:251], v[32:47]
	ds_read_b128 v[248:251], v208 offset:23072
	v_mfma_f32_32x32x16_bf16 v[16:31], v[222:225], v[244:247], v[16:31]
	ds_read_b128 v[244:247], v208 offset:27680
	v_mfma_f32_32x32x16_bf16 v[0:15], v[222:225], v[240:243], v[0:15]
	ds_read_b128 v[240:243], v208 offset:32288
	ds_read_b128 v[222:225], v207 offset:4640
	s_waitcnt lgkmcnt(4)
	v_mfma_f32_32x32x16_bf16 v[112:127], v[210:213], v[252:255], v[112:127]
	s_waitcnt lgkmcnt(3)
	v_mfma_f32_32x32x16_bf16 v[96:111], v[210:213], v[248:251], v[96:111]
	s_waitcnt lgkmcnt(2)
	v_mfma_f32_32x32x16_bf16 v[80:95], v[210:213], v[244:247], v[80:95]
	s_waitcnt lgkmcnt(1)
	v_mfma_f32_32x32x16_bf16 v[64:79], v[210:213], v[240:243], v[64:79]
	ds_read_b128 v[210:213], v207 offset:64
	s_waitcnt lgkmcnt(1)
	v_mfma_f32_32x32x16_bf16 v[48:63], v[222:225], v[252:255], v[48:63]
	ds_read_b128 v[252:255], v208 offset:18496
	v_mfma_f32_32x32x16_bf16 v[32:47], v[222:225], v[248:251], v[32:47]
	ds_read_b128 v[248:251], v208 offset:23104
	v_mfma_f32_32x32x16_bf16 v[16:31], v[222:225], v[244:247], v[16:31]
	ds_read_b128 v[244:247], v208 offset:27712
	v_mfma_f32_32x32x16_bf16 v[0:15], v[222:225], v[240:243], v[0:15]
	ds_read_b128 v[240:243], v208 offset:32320
	ds_read_b128 v[222:225], v207 offset:4672
	s_waitcnt lgkmcnt(4)
	v_mfma_f32_32x32x16_bf16 v[112:127], v[210:213], v[252:255], v[112:127]
	s_waitcnt lgkmcnt(3)
	v_mfma_f32_32x32x16_bf16 v[96:111], v[210:213], v[248:251], v[96:111]
	s_waitcnt lgkmcnt(2)
	v_mfma_f32_32x32x16_bf16 v[80:95], v[210:213], v[244:247], v[80:95]
	s_waitcnt lgkmcnt(1)
	v_mfma_f32_32x32x16_bf16 v[64:79], v[210:213], v[240:243], v[64:79]
	ds_read_b128 v[210:213], v207 offset:96
	s_waitcnt lgkmcnt(1)
	v_mfma_f32_32x32x16_bf16 v[48:63], v[222:225], v[252:255], v[48:63]
	ds_read_b128 v[252:255], v208 offset:18528
	v_mfma_f32_32x32x16_bf16 v[32:47], v[222:225], v[248:251], v[32:47]
	ds_read_b128 v[248:251], v208 offset:23136
	v_mfma_f32_32x32x16_bf16 v[16:31], v[222:225], v[244:247], v[16:31]
	ds_read_b128 v[244:247], v208 offset:27744
	v_mfma_f32_32x32x16_bf16 v[0:15], v[222:225], v[240:243], v[0:15]
	ds_read_b128 v[240:243], v208 offset:32352
	ds_read_b128 v[222:225], v207 offset:4704
	s_waitcnt lgkmcnt(4)
	v_mfma_f32_32x32x16_bf16 v[112:127], v[210:213], v[252:255], v[112:127]
	s_waitcnt lgkmcnt(3)
	v_mfma_f32_32x32x16_bf16 v[96:111], v[210:213], v[248:251], v[96:111]
	s_waitcnt lgkmcnt(2)
	v_mfma_f32_32x32x16_bf16 v[80:95], v[210:213], v[244:247], v[80:95]
	s_waitcnt lgkmcnt(1)
	v_mfma_f32_32x32x16_bf16 v[64:79], v[210:213], v[240:243], v[64:79]
	s_waitcnt lgkmcnt(0)
	v_mfma_f32_32x32x16_bf16 v[48:63], v[222:225], v[252:255], v[48:63]
	v_mfma_f32_32x32x16_bf16 v[32:47], v[222:225], v[248:251], v[32:47]
	v_mfma_f32_32x32x16_bf16 v[16:31], v[222:225], v[244:247], v[16:31]
	s_barrier
; DI int crow(int i, int h) { return (i & 3) + 8 * (i >> 2) + 4 * h; }
; DI f32x16 mfma32(bf16x8 a, bf16x8 b, f32x16 c) { return __builtin_amdgcn_mfma_f32_32x32x16_bf16(a, b, c, 0, 0, 0); }
; template <int NT, class Epi>
; DI void gemm_tile(const u16* __restrict__ A, int lda, const u16* __restrict__ Bt, int ldb, int K, int m0, int n0, const Epi& epi, char* smem) {
;     ...
; #pragma unroll
;     for (int ks = 0; ks < 4; ++ks) {
;       bf16x8 a[2], b[NT];
; #pragma unroll
;       for (int mt = 0; mt < 2; ++mt) a[mt] = *(const bf16x8*)(As + (wm * 64 + mt * 32 + r) * 72 + ks * 16 + h * 8);
; #pragma unroll
;       for (int nt = 0; nt < NT; ++nt) b[nt] = *(const bf16x8*)(Bs + (wn * 32 * NT + nt * 32 + r) * 72 + ks * 16 + h * 8);
; #pragma unroll
;       for (int mt = 0; mt < 2; ++mt)
; #pragma unroll
;         for (int nt = 0; nt < NT; ++nt) acc[mt][nt] = mfma32(a[mt], b[nt], acc[mt][nt]);
;     }
;     __syncthreads();
;   }
; #pragma unroll
;   for (int mt = 0; mt < 2; ++mt)
; #pragma unroll
;     for (int nt = 0; nt < NT; ++nt) epi(acc[mt][nt], m0 + wm * 64 + mt * 32, n0 + wn * 32 * NT + nt * 32, lane);
;   DI void operator()(const f32x16& acc, int row0, int col0, int lane) const {
;     const int r = lane & 31, h = lane >> 5, col = col0 + r;
; #pragma unroll
;     for (int i = 0; i < 16; ++i) { float* q = H + (size_t)(row0 + crow(i, h)) * DM + col; *q = *q + acc[i]; }
;   }
	v_mfma_f32_32x32x16_bf16 v[0:15], v[222:225], v[240:243], v[0:15]
	s_cbranch_scc1 .LBB0_422
	s_waitcnt vmcnt(11)
	ds_write_b128 v206, v[128:131]
	s_waitcnt vmcnt(10)
	ds_write_b128 v206, v[132:135] offset:4608
	s_waitcnt vmcnt(9)
	ds_write_b128 v206, v[136:139] offset:9216
	s_waitcnt vmcnt(8)
	ds_write_b128 v206, v[140:143] offset:13824
	s_waitcnt vmcnt(7)
	ds_write_b128 v206, v[144:147] offset:18432
	s_waitcnt vmcnt(6)
	ds_write_b128 v206, v[148:151] offset:23040
	s_waitcnt vmcnt(5)
	ds_write_b128 v206, v[152:155] offset:27648
	s_waitcnt vmcnt(4)
	ds_write_b128 v206, v[156:159] offset:32256
	s_waitcnt vmcnt(3)
	ds_write_b128 v206, v[160:163] offset:36864
	s_waitcnt vmcnt(2)
	ds_write_b128 v206, v[164:167] offset:41472
	s_waitcnt vmcnt(1)
	ds_write_b128 v206, v[168:171] offset:46080
	s_waitcnt vmcnt(0)
	ds_write_b128 v206, v[172:175] offset:50688
	s_waitcnt lgkmcnt(0)
	s_barrier
	ds_read_b128 v[128:131], v207 offset:4608
	ds_read_b128 v[132:135], v208 offset:23040
	ds_read_b128 v[136:139], v208 offset:27648
	ds_read_b128 v[140:143], v208 offset:32256
	ds_read_b128 v[144:147], v207
	ds_read_b128 v[148:151], v207 offset:32
	ds_read_b128 v[152:155], v208 offset:18432
	ds_read_b128 v[156:159], v208 offset:18464
	s_waitcnt lgkmcnt(1)
	v_mfma_f32_32x32x16_bf16 v[112:127], v[144:147], v[152:155], v[112:127]
	v_add_lshl_u32 v192, v181, s59, 12
	s_add_i32 s58, s58, s78
	s_add_i32 s18, s18, s19
	s_cmpk_lt_u32 s58, 0x100
	v_mfma_f32_32x32x16_bf16 v[96:111], v[144:147], v[132:135], v[96:111]
	v_mfma_f32_32x32x16_bf16 v[80:95], v[144:147], v[136:139], v[80:95]
	v_mfma_f32_32x32x16_bf16 v[64:79], v[144:147], v[140:143], v[64:79]
	v_mfma_f32_32x32x16_bf16 v[48:63], v[128:131], v[152:155], v[48:63]
	v_or_b32_e32 v154, 0x3000, v192
	v_mov_b32_e32 v155, v193
	v_or_b32_e32 v152, 0x8000, v192
	v_mov_b32_e32 v153, v193
	v_mfma_f32_32x32x16_bf16 v[32:47], v[128:131], v[132:135], v[32:47]
	v_mfma_f32_32x32x16_bf16 v[16:31], v[128:131], v[136:139], v[16:31]
	v_mfma_f32_32x32x16_bf16 v[0:15], v[128:131], v[140:143], v[0:15]
	ds_read_b128 v[128:131], v207 offset:4640
	ds_read_b128 v[132:135], v208 offset:23072
	ds_read_b128 v[136:139], v208 offset:27680
	ds_read_b128 v[140:143], v208 offset:32288
	s_waitcnt lgkmcnt(4)
	v_mfma_f32_32x32x16_bf16 v[112:127], v[148:151], v[156:159], v[112:127]
	s_waitcnt lgkmcnt(2)
	v_mfma_f32_32x32x16_bf16 v[96:111], v[148:151], v[132:135], v[96:111]
	s_waitcnt lgkmcnt(1)
	v_mfma_f32_32x32x16_bf16 v[80:95], v[148:151], v[136:139], v[80:95]
	s_waitcnt lgkmcnt(0)
	v_mfma_f32_32x32x16_bf16 v[64:79], v[148:151], v[140:143], v[64:79]
	v_mfma_f32_32x32x16_bf16 v[48:63], v[128:131], v[156:159], v[48:63]
	v_or_b32_e32 v158, 0x1000, v192
	v_mov_b32_e32 v159, v193
	v_or_b32_e32 v156, 0x2000, v192
	v_mov_b32_e32 v157, v193
	v_mfma_f32_32x32x16_bf16 v[32:47], v[128:131], v[132:135], v[32:47]
	v_mfma_f32_32x32x16_bf16 v[16:31], v[128:131], v[136:139], v[16:31]
	v_mfma_f32_32x32x16_bf16 v[0:15], v[128:131], v[140:143], v[0:15]
	ds_read_b128 v[128:131], v207 offset:64
	ds_read_b128 v[132:135], v207 offset:4672
	ds_read_b128 v[136:139], v208 offset:18496
	ds_read_b128 v[140:143], v208 offset:23104
	ds_read_b128 v[144:147], v208 offset:27712
	ds_read_b128 v[148:151], v208 offset:32320
	s_waitcnt lgkmcnt(3)
	v_mfma_f32_32x32x16_bf16 v[112:127], v[128:131], v[136:139], v[112:127]
	s_waitcnt lgkmcnt(2)
	v_mfma_f32_32x32x16_bf16 v[96:111], v[128:131], v[140:143], v[96:111]
	s_waitcnt lgkmcnt(1)
	v_mfma_f32_32x32x16_bf16 v[80:95], v[128:131], v[144:147], v[80:95]
	s_waitcnt lgkmcnt(0)
	v_mfma_f32_32x32x16_bf16 v[64:79], v[128:131], v[148:151], v[64:79]
	v_mfma_f32_32x32x16_bf16 v[48:63], v[132:135], v[136:139], v[48:63]
	v_mfma_f32_32x32x16_bf16 v[32:47], v[132:135], v[140:143], v[32:47]
	v_mfma_f32_32x32x16_bf16 v[16:31], v[132:135], v[144:147], v[16:31]
	v_mfma_f32_32x32x16_bf16 v[0:15], v[132:135], v[148:151], v[0:15]
	ds_read_b128 v[128:131], v207 offset:96
	ds_read_b128 v[132:135], v207 offset:4704
	ds_read_b128 v[136:139], v208 offset:18528
	ds_read_b128 v[140:143], v208 offset:23136
	ds_read_b128 v[144:147], v208 offset:27744
	ds_read_b128 v[148:151], v208 offset:32352
	s_waitcnt lgkmcnt(0)
	s_barrier
	v_mfma_f32_32x32x16_bf16 v[112:127], v[128:131], v[136:139], v[112:127]
	v_mfma_f32_32x32x16_bf16 v[96:111], v[128:131], v[140:143], v[96:111]
	v_mfma_f32_32x32x16_bf16 v[80:95], v[128:131], v[144:147], v[80:95]
	v_mfma_f32_32x32x16_bf16 v[64:79], v[128:131], v[148:151], v[64:79]
	v_mfma_f32_32x32x16_bf16 v[0:15], v[132:135], v[148:151], v[0:15]
	v_mfma_f32_32x32x16_bf16 v[16:31], v[132:135], v[144:147], v[16:31]
	v_mfma_f32_32x32x16_bf16 v[32:47], v[132:135], v[140:143], v[32:47]
	v_mfma_f32_32x32x16_bf16 v[48:63], v[132:135], v[136:139], v[48:63]
	s_cselect_b32 s91, 1, 0
	v_or_b32_e32 v239, s60, v179
	v_lshlrev_b32_e32 v239, 2, v239
	v_add_u32_e32 v239, v239, v192
	s_add_u32 s92, s68, 0x0
	s_addc_u32 s93, s69, 0
	global_load_dword v128, v239, s[92:93]
	s_add_u32 s92, s68, 0x1000
	s_addc_u32 s93, s69, 0
	global_load_dword v129, v239, s[92:93]
	s_add_u32 s92, s68, 0x2000
	s_addc_u32 s93, s69, 0
	global_load_dword v130, v239, s[92:93]
	s_add_u32 s92, s68, 0x3000
	s_addc_u32 s93, s69, 0
	global_load_dword v131, v239, s[92:93]
	s_add_u32 s92, s68, 0x8000
	s_addc_u32 s93, s69, 0
	global_load_dword v132, v239, s[92:93]
	s_add_u32 s92, s68, 0x9000
	s_addc_u32 s93, s69, 0
	global_load_dword v133, v239, s[92:93]
	s_add_u32 s92, s68, 0xa000
	s_addc_u32 s93, s69, 0
	global_load_dword v134, v239, s[92:93]
	s_add_u32 s92, s68, 0xb000
	s_addc_u32 s93, s69, 0
	global_load_dword v135, v239, s[92:93]
	s_add_u32 s92, s68, 0x10000
	s_addc_u32 s93, s69, 0
; DI int crow(int i, int h) { return (i & 3) + 8 * (i >> 2) + 4 * h; }
; template <int NT, class Epi>
; DI void gemm_tile(const u16* __restrict__ A, int lda, const u16* __restrict__ Bt, int ldb, int K, int m0, int n0, const Epi& epi, char* smem) {
;     ...
; #pragma unroll
;   for (int mt = 0; mt < 2; ++mt)
; #pragma unroll
;     for (int nt = 0; nt < NT; ++nt) epi(acc[mt][nt], m0 + wm * 64 + mt * 32, n0 + wn * 32 * NT + nt * 32, lane);
;   DI void operator()(const f32x16& acc, int row0, int col0, int lane) const {
;     const int r = lane & 31, h = lane >> 5, col = col0 + r;
; #pragma unroll
;     for (int i = 0; i < 16; ++i) { float* q = H + (size_t)(row0 + crow(i, h)) * DM + col; *q = *q + acc[i]; }
;   }
	global_load_dword v136, v239, s[92:93]
	s_add_u32 s92, s68, 0x11000
	s_addc_u32 s93, s69, 0
	global_load_dword v137, v239, s[92:93]
	s_add_u32 s92, s68, 0x12000
	s_addc_u32 s93, s69, 0
	global_load_dword v138, v239, s[92:93]
	s_add_u32 s92, s68, 0x13000
	s_addc_u32 s93, s69, 0
	global_load_dword v139, v239, s[92:93]
	s_add_u32 s92, s68, 0x18000
	s_addc_u32 s93, s69, 0
	global_load_dword v140, v239, s[92:93]
	s_add_u32 s92, s68, 0x19000
	s_addc_u32 s93, s69, 0
	global_load_dword v141, v239, s[92:93]
	s_add_u32 s92, s68, 0x1a000
	s_addc_u32 s93, s69, 0
	global_load_dword v142, v239, s[92:93]
	s_add_u32 s92, s68, 0x1b000
	s_addc_u32 s93, s69, 0
	global_load_dword v143, v239, s[92:93]
	s_add_u32 s92, s68, 0x80
	s_addc_u32 s93, s69, 0
	global_load_dword v240, v239, s[92:93]
	s_add_u32 s92, s68, 0x1080
	s_addc_u32 s93, s69, 0
	global_load_dword v241, v239, s[92:93]
	s_add_u32 s92, s68, 0x2080
	s_addc_u32 s93, s69, 0
	global_load_dword v242, v239, s[92:93]
	s_add_u32 s92, s68, 0x3080
	s_addc_u32 s93, s69, 0
	global_load_dword v243, v239, s[92:93]
	s_add_u32 s92, s68, 0x8080
	s_addc_u32 s93, s69, 0
	global_load_dword v244, v239, s[92:93]
	s_add_u32 s92, s68, 0x9080
	s_addc_u32 s93, s69, 0
	global_load_dword v245, v239, s[92:93]
	s_add_u32 s92, s68, 0xa080
	s_addc_u32 s93, s69, 0
	global_load_dword v246, v239, s[92:93]
	s_add_u32 s92, s68, 0xb080
	s_addc_u32 s93, s69, 0
	global_load_dword v247, v239, s[92:93]
	s_add_u32 s92, s68, 0x10080
	s_addc_u32 s93, s69, 0
	global_load_dword v248, v239, s[92:93]
	s_add_u32 s92, s68, 0x11080
	s_addc_u32 s93, s69, 0
	global_load_dword v249, v239, s[92:93]
	s_add_u32 s92, s68, 0x12080
	s_addc_u32 s93, s69, 0
	global_load_dword v250, v239, s[92:93]
	s_add_u32 s92, s68, 0x13080
	s_addc_u32 s93, s69, 0
	global_load_dword v251, v239, s[92:93]
	s_add_u32 s92, s68, 0x18080
	s_addc_u32 s93, s69, 0
	global_load_dword v252, v239, s[92:93]
	s_add_u32 s92, s68, 0x19080
	s_addc_u32 s93, s69, 0
	global_load_dword v253, v239, s[92:93]
	s_add_u32 s92, s68, 0x1a080
	s_addc_u32 s93, s69, 0
	global_load_dword v254, v239, s[92:93]
	s_add_u32 s92, s68, 0x1b080
	s_addc_u32 s93, s69, 0
	global_load_dword v255, v239, s[92:93]
	s_waitcnt vmcnt(16)
	v_add_f32_e32 v112, v112, v128
	v_add_f32_e32 v113, v113, v129
	v_add_f32_e32 v114, v114, v130
	v_add_f32_e32 v115, v115, v131
	v_add_f32_e32 v116, v116, v132
	v_add_f32_e32 v117, v117, v133
	v_add_f32_e32 v118, v118, v134
	v_add_f32_e32 v119, v119, v135
	v_add_f32_e32 v120, v120, v136
	v_add_f32_e32 v121, v121, v137
	v_add_f32_e32 v122, v122, v138
	v_add_f32_e32 v123, v123, v139
	v_add_f32_e32 v124, v124, v140
	v_add_f32_e32 v125, v125, v141
	v_add_f32_e32 v126, v126, v142
	v_add_f32_e32 v127, v127, v143
	s_add_u32 s92, s68, 0x0
	s_addc_u32 s93, s69, 0
	global_store_dword v239, v112, s[92:93]
	s_add_u32 s92, s68, 0x1000
	s_addc_u32 s93, s69, 0
	global_store_dword v239, v113, s[92:93]
	s_add_u32 s92, s68, 0x2000
	s_addc_u32 s93, s69, 0
	global_store_dword v239, v114, s[92:93]
	s_add_u32 s92, s68, 0x3000
	s_addc_u32 s93, s69, 0
	global_store_dword v239, v115, s[92:93]
	s_add_u32 s92, s68, 0x8000
	s_addc_u32 s93, s69, 0
	global_store_dword v239, v116, s[92:93]
	s_add_u32 s92, s68, 0x9000
	s_addc_u32 s93, s69, 0
	global_store_dword v239, v117, s[92:93]
	s_add_u32 s92, s68, 0xa000
	s_addc_u32 s93, s69, 0
	global_store_dword v239, v118, s[92:93]
	s_add_u32 s92, s68, 0xb000
	s_addc_u32 s93, s69, 0
	global_store_dword v239, v119, s[92:93]
	s_add_u32 s92, s68, 0x10000
	s_addc_u32 s93, s69, 0
	global_store_dword v239, v120, s[92:93]
	s_add_u32 s92, s68, 0x11000
	s_addc_u32 s93, s69, 0
	global_store_dword v239, v121, s[92:93]
	s_add_u32 s92, s68, 0x12000
	s_addc_u32 s93, s69, 0
	global_store_dword v239, v122, s[92:93]
	s_add_u32 s92, s68, 0x13000
	s_addc_u32 s93, s69, 0
	global_store_dword v239, v123, s[92:93]
	s_add_u32 s92, s68, 0x18000
	s_addc_u32 s93, s69, 0
	global_store_dword v239, v124, s[92:93]
	s_add_u32 s92, s68, 0x19000
	s_addc_u32 s93, s69, 0
	global_store_dword v239, v125, s[92:93]
	s_add_u32 s92, s68, 0x1a000
	s_addc_u32 s93, s69, 0
	global_store_dword v239, v126, s[92:93]
	s_add_u32 s92, s68, 0x1b000
	s_addc_u32 s93, s69, 0
	global_store_dword v239, v127, s[92:93]
	s_add_u32 s92, s68, 0x100
	s_addc_u32 s93, s69, 0
	global_load_dword v128, v239, s[92:93]
	s_add_u32 s92, s68, 0x1100
	s_addc_u32 s93, s69, 0
	global_load_dword v129, v239, s[92:93]
	s_add_u32 s92, s68, 0x2100
	s_addc_u32 s93, s69, 0
	global_load_dword v130, v239, s[92:93]
	s_add_u32 s92, s68, 0x3100
	s_addc_u32 s93, s69, 0
	global_load_dword v131, v239, s[92:93]
	s_add_u32 s92, s68, 0x8100
	s_addc_u32 s93, s69, 0
	global_load_dword v132, v239, s[92:93]
	s_add_u32 s92, s68, 0x9100
	s_addc_u32 s93, s69, 0
	global_load_dword v133, v239, s[92:93]
	s_add_u32 s92, s68, 0xa100
	s_addc_u32 s93, s69, 0
	global_load_dword v134, v239, s[92:93]
	s_add_u32 s92, s68, 0xb100
	s_addc_u32 s93, s69, 0
	global_load_dword v135, v239, s[92:93]
	s_add_u32 s92, s68, 0x10100
	s_addc_u32 s93, s69, 0
	global_load_dword v136, v239, s[92:93]
	s_add_u32 s92, s68, 0x11100
	s_addc_u32 s93, s69, 0
	global_load_dword v137, v239, s[92:93]
	s_add_u32 s92, s68, 0x12100
	s_addc_u32 s93, s69, 0
	global_load_dword v138, v239, s[92:93]
	s_add_u32 s92, s68, 0x13100
	s_addc_u32 s93, s69, 0
	global_load_dword v139, v239, s[92:93]
	s_add_u32 s92, s68, 0x18100
	s_addc_u32 s93, s69, 0
	global_load_dword v140, v239, s[92:93]
	s_add_u32 s92, s68, 0x19100
	s_addc_u32 s93, s69, 0
	global_load_dword v141, v239, s[92:93]
	s_add_u32 s92, s68, 0x1a100
	s_addc_u32 s93, s69, 0
	global_load_dword v142, v239, s[92:93]
	s_add_u32 s92, s68, 0x1b100
	s_addc_u32 s93, s69, 0
	global_load_dword v143, v239, s[92:93]
	s_waitcnt vmcnt(32)
; DI int crow(int i, int h) { return (i & 3) + 8 * (i >> 2) + 4 * h; }
; template <int NT, class Epi>
; DI void gemm_tile(const u16* __restrict__ A, int lda, const u16* __restrict__ Bt, int ldb, int K, int m0, int n0, const Epi& epi, char* smem) {
;     ...
; #pragma unroll
;   for (int mt = 0; mt < 2; ++mt)
; #pragma unroll
;     for (int nt = 0; nt < NT; ++nt) epi(acc[mt][nt], m0 + wm * 64 + mt * 32, n0 + wn * 32 * NT + nt * 32, lane);
;   DI void operator()(const f32x16& acc, int row0, int col0, int lane) const {
;     const int r = lane & 31, h = lane >> 5, col = col0 + r;
; #pragma unroll
;     for (int i = 0; i < 16; ++i) { float* q = H + (size_t)(row0 + crow(i, h)) * DM + col; *q = *q + acc[i]; }
;   }
	v_add_f32_e32 v96, v96, v240
	v_add_f32_e32 v97, v97, v241
	v_add_f32_e32 v98, v98, v242
	v_add_f32_e32 v99, v99, v243
	v_add_f32_e32 v100, v100, v244
	v_add_f32_e32 v101, v101, v245
	v_add_f32_e32 v102, v102, v246
	v_add_f32_e32 v103, v103, v247
	v_add_f32_e32 v104, v104, v248
	v_add_f32_e32 v105, v105, v249
	v_add_f32_e32 v106, v106, v250
	v_add_f32_e32 v107, v107, v251
	v_add_f32_e32 v108, v108, v252
	v_add_f32_e32 v109, v109, v253
	v_add_f32_e32 v110, v110, v254
	v_add_f32_e32 v111, v111, v255
	s_add_u32 s92, s68, 0x80
	s_addc_u32 s93, s69, 0
	global_store_dword v239, v96, s[92:93]
	s_add_u32 s92, s68, 0x1080
	s_addc_u32 s93, s69, 0
	global_store_dword v239, v97, s[92:93]
	s_add_u32 s92, s68, 0x2080
	s_addc_u32 s93, s69, 0
	global_store_dword v239, v98, s[92:93]
	s_add_u32 s92, s68, 0x3080
	s_addc_u32 s93, s69, 0
	global_store_dword v239, v99, s[92:93]
	s_add_u32 s92, s68, 0x8080
	s_addc_u32 s93, s69, 0
	global_store_dword v239, v100, s[92:93]
	s_add_u32 s92, s68, 0x9080
	s_addc_u32 s93, s69, 0
	global_store_dword v239, v101, s[92:93]
	s_add_u32 s92, s68, 0xa080
	s_addc_u32 s93, s69, 0
	global_store_dword v239, v102, s[92:93]
	s_add_u32 s92, s68, 0xb080
	s_addc_u32 s93, s69, 0
	global_store_dword v239, v103, s[92:93]
	s_add_u32 s92, s68, 0x10080
	s_addc_u32 s93, s69, 0
	global_store_dword v239, v104, s[92:93]
	s_add_u32 s92, s68, 0x11080
	s_addc_u32 s93, s69, 0
	global_store_dword v239, v105, s[92:93]
	s_add_u32 s92, s68, 0x12080
	s_addc_u32 s93, s69, 0
	global_store_dword v239, v106, s[92:93]
	s_add_u32 s92, s68, 0x13080
	s_addc_u32 s93, s69, 0
	global_store_dword v239, v107, s[92:93]
	s_add_u32 s92, s68, 0x18080
	s_addc_u32 s93, s69, 0
	global_store_dword v239, v108, s[92:93]
	s_add_u32 s92, s68, 0x19080
	s_addc_u32 s93, s69, 0
	global_store_dword v239, v109, s[92:93]
	s_add_u32 s92, s68, 0x1a080
	s_addc_u32 s93, s69, 0
	global_store_dword v239, v110, s[92:93]
	s_add_u32 s92, s68, 0x1b080
	s_addc_u32 s93, s69, 0
	global_store_dword v239, v111, s[92:93]
	s_add_u32 s92, s68, 0x180
	s_addc_u32 s93, s69, 0
	global_load_dword v240, v239, s[92:93]
	s_add_u32 s92, s68, 0x1180
	s_addc_u32 s93, s69, 0
	global_load_dword v241, v239, s[92:93]
	s_add_u32 s92, s68, 0x2180
	s_addc_u32 s93, s69, 0
	global_load_dword v242, v239, s[92:93]
	s_add_u32 s92, s68, 0x3180
	s_addc_u32 s93, s69, 0
	global_load_dword v243, v239, s[92:93]
	s_add_u32 s92, s68, 0x8180
	s_addc_u32 s93, s69, 0
	global_load_dword v244, v239, s[92:93]
	s_add_u32 s92, s68, 0x9180
	s_addc_u32 s93, s69, 0
	global_load_dword v245, v239, s[92:93]
	s_add_u32 s92, s68, 0xa180
	s_addc_u32 s93, s69, 0
	global_load_dword v246, v239, s[92:93]
	s_add_u32 s92, s68, 0xb180
	s_addc_u32 s93, s69, 0
	global_load_dword v247, v239, s[92:93]
	s_add_u32 s92, s68, 0x10180
	s_addc_u32 s93, s69, 0
	global_load_dword v248, v239, s[92:93]
	s_add_u32 s92, s68, 0x11180
	s_addc_u32 s93, s69, 0
	global_load_dword v249, v239, s[92:93]
	s_add_u32 s92, s68, 0x12180
	s_addc_u32 s93, s69, 0
	global_load_dword v250, v239, s[92:93]
	s_add_u32 s92, s68, 0x13180
	s_addc_u32 s93, s69, 0
	global_load_dword v251, v239, s[92:93]
	s_add_u32 s92, s68, 0x18180
	s_addc_u32 s93, s69, 0
	global_load_dword v252, v239, s[92:93]
	s_add_u32 s92, s68, 0x19180
	s_addc_u32 s93, s69, 0
	global_load_dword v253, v239, s[92:93]
	s_add_u32 s92, s68, 0x1a180
	s_addc_u32 s93, s69, 0
	global_load_dword v254, v239, s[92:93]
	s_add_u32 s92, s68, 0x1b180
	s_addc_u32 s93, s69, 0
	global_load_dword v255, v239, s[92:93]
	s_waitcnt vmcnt(32)
	v_add_f32_e32 v80, v80, v128
	v_add_f32_e32 v81, v81, v129
	v_add_f32_e32 v82, v82, v130
	v_add_f32_e32 v83, v83, v131
	v_add_f32_e32 v84, v84, v132
	v_add_f32_e32 v85, v85, v133
	v_add_f32_e32 v86, v86, v134
	v_add_f32_e32 v87, v87, v135
	v_add_f32_e32 v88, v88, v136
	v_add_f32_e32 v89, v89, v137
	v_add_f32_e32 v90, v90, v138
	v_add_f32_e32 v91, v91, v139
	v_add_f32_e32 v92, v92, v140
	v_add_f32_e32 v93, v93, v141
	v_add_f32_e32 v94, v94, v142
	v_add_f32_e32 v95, v95, v143
	s_add_u32 s92, s68, 0x100
	s_addc_u32 s93, s69, 0
	global_store_dword v239, v80, s[92:93]
	s_add_u32 s92, s68, 0x1100
	s_addc_u32 s93, s69, 0
	global_store_dword v239, v81, s[92:93]
	s_add_u32 s92, s68, 0x2100
	s_addc_u32 s93, s69, 0
	global_store_dword v239, v82, s[92:93]
	s_add_u32 s92, s68, 0x3100
	s_addc_u32 s93, s69, 0
	global_store_dword v239, v83, s[92:93]
	s_add_u32 s92, s68, 0x8100
	s_addc_u32 s93, s69, 0
	global_store_dword v239, v84, s[92:93]
	s_add_u32 s92, s68, 0x9100
	s_addc_u32 s93, s69, 0
	global_store_dword v239, v85, s[92:93]
	s_add_u32 s92, s68, 0xa100
	s_addc_u32 s93, s69, 0
	global_store_dword v239, v86, s[92:93]
	s_add_u32 s92, s68, 0xb100
	s_addc_u32 s93, s69, 0
	global_store_dword v239, v87, s[92:93]
	s_add_u32 s92, s68, 0x10100
	s_addc_u32 s93, s69, 0
	global_store_dword v239, v88, s[92:93]
	s_add_u32 s92, s68, 0x11100
	s_addc_u32 s93, s69, 0
	global_store_dword v239, v89, s[92:93]
	s_add_u32 s92, s68, 0x12100
	s_addc_u32 s93, s69, 0
	global_store_dword v239, v90, s[92:93]
	s_add_u32 s92, s68, 0x13100
	s_addc_u32 s93, s69, 0
	global_store_dword v239, v91, s[92:93]
	s_add_u32 s92, s68, 0x18100
	s_addc_u32 s93, s69, 0
	global_store_dword v239, v92, s[92:93]
	s_add_u32 s92, s68, 0x19100
	s_addc_u32 s93, s69, 0
	global_store_dword v239, v93, s[92:93]
	s_add_u32 s92, s68, 0x1a100
	s_addc_u32 s93, s69, 0
	global_store_dword v239, v94, s[92:93]
	s_add_u32 s92, s68, 0x1b100
	s_addc_u32 s93, s69, 0
	global_store_dword v239, v95, s[92:93]
	s_add_u32 s92, s68, 0x20000
	s_addc_u32 s93, s69, 0
	global_load_dword v128, v239, s[92:93]
	s_add_u32 s92, s68, 0x21000
	s_addc_u32 s93, s69, 0
	global_load_dword v129, v239, s[92:93]
	s_add_u32 s92, s68, 0x22000
	s_addc_u32 s93, s69, 0
	global_load_dword v130, v239, s[92:93]
	s_add_u32 s92, s68, 0x23000
	s_addc_u32 s93, s69, 0
	global_load_dword v131, v239, s[92:93]
	s_add_u32 s92, s68, 0x28000
	s_addc_u32 s93, s69, 0
	global_load_dword v132, v239, s[92:93]
	s_add_u32 s92, s68, 0x29000
	s_addc_u32 s93, s69, 0
	global_load_dword v133, v239, s[92:93]
	s_add_u32 s92, s68, 0x2a000
	s_addc_u32 s93, s69, 0
	global_load_dword v134, v239, s[92:93]
	s_add_u32 s92, s68, 0x2b000
	s_addc_u32 s93, s69, 0
	global_load_dword v135, v239, s[92:93]
	s_add_u32 s92, s68, 0x30000
	s_addc_u32 s93, s69, 0
	global_load_dword v136, v239, s[92:93]
	s_add_u32 s92, s68, 0x31000
	s_addc_u32 s93, s69, 0
	global_load_dword v137, v239, s[92:93]
	s_add_u32 s92, s68, 0x32000
	s_addc_u32 s93, s69, 0
	global_load_dword v138, v239, s[92:93]
	s_add_u32 s92, s68, 0x33000
	s_addc_u32 s93, s69, 0
	global_load_dword v139, v239, s[92:93]
	s_add_u32 s92, s68, 0x38000
	s_addc_u32 s93, s69, 0
	global_load_dword v140, v239, s[92:93]
	s_add_u32 s92, s68, 0x39000
	s_addc_u32 s93, s69, 0
	global_load_dword v141, v239, s[92:93]
	s_add_u32 s92, s68, 0x3a000
	s_addc_u32 s93, s69, 0
	global_load_dword v142, v239, s[92:93]
	s_add_u32 s92, s68, 0x3b000
	s_addc_u32 s93, s69, 0
	global_load_dword v143, v239, s[92:93]
	s_waitcnt vmcnt(32)
; DI int crow(int i, int h) { return (i & 3) + 8 * (i >> 2) + 4 * h; }
; template <int NT, class Epi>
; DI void gemm_tile(const u16* __restrict__ A, int lda, const u16* __restrict__ Bt, int ldb, int K, int m0, int n0, const Epi& epi, char* smem) {
;     ...
; #pragma unroll
;   for (int mt = 0; mt < 2; ++mt)
; #pragma unroll
;     for (int nt = 0; nt < NT; ++nt) epi(acc[mt][nt], m0 + wm * 64 + mt * 32, n0 + wn * 32 * NT + nt * 32, lane);
;   DI void operator()(const f32x16& acc, int row0, int col0, int lane) const {
;     const int r = lane & 31, h = lane >> 5, col = col0 + r;
; #pragma unroll
;     for (int i = 0; i < 16; ++i) { float* q = H + (size_t)(row0 + crow(i, h)) * DM + col; *q = *q + acc[i]; }
;   }
	v_add_f32_e32 v64, v64, v240
	v_add_f32_e32 v65, v65, v241
	v_add_f32_e32 v66, v66, v242
	v_add_f32_e32 v67, v67, v243
	v_add_f32_e32 v68, v68, v244
	v_add_f32_e32 v69, v69, v245
	v_add_f32_e32 v70, v70, v246
	v_add_f32_e32 v71, v71, v247
	v_add_f32_e32 v72, v72, v248
	v_add_f32_e32 v73, v73, v249
	v_add_f32_e32 v74, v74, v250
	v_add_f32_e32 v75, v75, v251
	v_add_f32_e32 v76, v76, v252
	v_add_f32_e32 v77, v77, v253
	v_add_f32_e32 v78, v78, v254
	v_add_f32_e32 v79, v79, v255
	s_add_u32 s92, s68, 0x180
	s_addc_u32 s93, s69, 0
	global_store_dword v239, v64, s[92:93]
	s_add_u32 s92, s68, 0x1180
	s_addc_u32 s93, s69, 0
	global_store_dword v239, v65, s[92:93]
	s_add_u32 s92, s68, 0x2180
	s_addc_u32 s93, s69, 0
	global_store_dword v239, v66, s[92:93]
	s_add_u32 s92, s68, 0x3180
	s_addc_u32 s93, s69, 0
	global_store_dword v239, v67, s[92:93]
	s_add_u32 s92, s68, 0x8180
	s_addc_u32 s93, s69, 0
	global_store_dword v239, v68, s[92:93]
	s_add_u32 s92, s68, 0x9180
	s_addc_u32 s93, s69, 0
	global_store_dword v239, v69, s[92:93]
	s_add_u32 s92, s68, 0xa180
	s_addc_u32 s93, s69, 0
	global_store_dword v239, v70, s[92:93]
	s_add_u32 s92, s68, 0xb180
	s_addc_u32 s93, s69, 0
	global_store_dword v239, v71, s[92:93]
	s_add_u32 s92, s68, 0x10180
	s_addc_u32 s93, s69, 0
	global_store_dword v239, v72, s[92:93]
	s_add_u32 s92, s68, 0x11180
	s_addc_u32 s93, s69, 0
	global_store_dword v239, v73, s[92:93]
	s_add_u32 s92, s68, 0x12180
	s_addc_u32 s93, s69, 0
	global_store_dword v239, v74, s[92:93]
	s_add_u32 s92, s68, 0x13180
	s_addc_u32 s93, s69, 0
	global_store_dword v239, v75, s[92:93]
	s_add_u32 s92, s68, 0x18180
	s_addc_u32 s93, s69, 0
	global_store_dword v239, v76, s[92:93]
	s_add_u32 s92, s68, 0x19180
	s_addc_u32 s93, s69, 0
	global_store_dword v239, v77, s[92:93]
	s_add_u32 s92, s68, 0x1a180
	s_addc_u32 s93, s69, 0
	global_store_dword v239, v78, s[92:93]
	s_add_u32 s92, s68, 0x1b180
	s_addc_u32 s93, s69, 0
	global_store_dword v239, v79, s[92:93]
	s_add_u32 s92, s68, 0x20080
	s_addc_u32 s93, s69, 0
	global_load_dword v240, v239, s[92:93]
	s_add_u32 s92, s68, 0x21080
	s_addc_u32 s93, s69, 0
	global_load_dword v241, v239, s[92:93]
	s_add_u32 s92, s68, 0x22080
	s_addc_u32 s93, s69, 0
	global_load_dword v242, v239, s[92:93]
	s_add_u32 s92, s68, 0x23080
	s_addc_u32 s93, s69, 0
	global_load_dword v243, v239, s[92:93]
	s_add_u32 s92, s68, 0x28080
	s_addc_u32 s93, s69, 0
	global_load_dword v244, v239, s[92:93]
	s_add_u32 s92, s68, 0x29080
	s_addc_u32 s93, s69, 0
	global_load_dword v245, v239, s[92:93]
	s_add_u32 s92, s68, 0x2a080
	s_addc_u32 s93, s69, 0
	global_load_dword v246, v239, s[92:93]
	s_add_u32 s92, s68, 0x2b080
	s_addc_u32 s93, s69, 0
	global_load_dword v247, v239, s[92:93]
	s_add_u32 s92, s68, 0x30080
	s_addc_u32 s93, s69, 0
	global_load_dword v248, v239, s[92:93]
	s_add_u32 s92, s68, 0x31080
	s_addc_u32 s93, s69, 0
	global_load_dword v249, v239, s[92:93]
	s_add_u32 s92, s68, 0x32080
	s_addc_u32 s93, s69, 0
	global_load_dword v250, v239, s[92:93]
	s_add_u32 s92, s68, 0x33080
	s_addc_u32 s93, s69, 0
	global_load_dword v251, v239, s[92:93]
	s_add_u32 s92, s68, 0x38080
	s_addc_u32 s93, s69, 0
	global_load_dword v252, v239, s[92:93]
	s_add_u32 s92, s68, 0x39080
	s_addc_u32 s93, s69, 0
	global_load_dword v253, v239, s[92:93]
	s_add_u32 s92, s68, 0x3a080
	s_addc_u32 s93, s69, 0
	global_load_dword v254, v239, s[92:93]
	s_add_u32 s92, s68, 0x3b080
	s_addc_u32 s93, s69, 0
	global_load_dword v255, v239, s[92:93]
	s_waitcnt vmcnt(32)
	v_add_f32_e32 v48, v48, v128
	v_add_f32_e32 v49, v49, v129
	v_add_f32_e32 v50, v50, v130
	v_add_f32_e32 v51, v51, v131
	v_add_f32_e32 v52, v52, v132
	v_add_f32_e32 v53, v53, v133
	v_add_f32_e32 v54, v54, v134
	v_add_f32_e32 v55, v55, v135
	v_add_f32_e32 v56, v56, v136
	v_add_f32_e32 v57, v57, v137
	v_add_f32_e32 v58, v58, v138
	v_add_f32_e32 v59, v59, v139
	v_add_f32_e32 v60, v60, v140
	v_add_f32_e32 v61, v61, v141
	v_add_f32_e32 v62, v62, v142
	v_add_f32_e32 v63, v63, v143
	s_add_u32 s92, s68, 0x20000
	s_addc_u32 s93, s69, 0
	global_store_dword v239, v48, s[92:93]
	s_add_u32 s92, s68, 0x21000
	s_addc_u32 s93, s69, 0
	global_store_dword v239, v49, s[92:93]
	s_add_u32 s92, s68, 0x22000
	s_addc_u32 s93, s69, 0
	global_store_dword v239, v50, s[92:93]
	s_add_u32 s92, s68, 0x23000
	s_addc_u32 s93, s69, 0
	global_store_dword v239, v51, s[92:93]
	s_add_u32 s92, s68, 0x28000
	s_addc_u32 s93, s69, 0
	global_store_dword v239, v52, s[92:93]
	s_add_u32 s92, s68, 0x29000
	s_addc_u32 s93, s69, 0
	global_store_dword v239, v53, s[92:93]
	s_add_u32 s92, s68, 0x2a000
	s_addc_u32 s93, s69, 0
	global_store_dword v239, v54, s[92:93]
	s_add_u32 s92, s68, 0x2b000
	s_addc_u32 s93, s69, 0
	global_store_dword v239, v55, s[92:93]
	s_add_u32 s92, s68, 0x30000
	s_addc_u32 s93, s69, 0
	global_store_dword v239, v56, s[92:93]
	s_add_u32 s92, s68, 0x31000
	s_addc_u32 s93, s69, 0
	global_store_dword v239, v57, s[92:93]
	s_add_u32 s92, s68, 0x32000
	s_addc_u32 s93, s69, 0
	global_store_dword v239, v58, s[92:93]
	s_add_u32 s92, s68, 0x33000
	s_addc_u32 s93, s69, 0
	global_store_dword v239, v59, s[92:93]
	s_add_u32 s92, s68, 0x38000
	s_addc_u32 s93, s69, 0
	global_store_dword v239, v60, s[92:93]
	s_add_u32 s92, s68, 0x39000
	s_addc_u32 s93, s69, 0
	global_store_dword v239, v61, s[92:93]
	s_add_u32 s92, s68, 0x3a000
	s_addc_u32 s93, s69, 0
	global_store_dword v239, v62, s[92:93]
	s_add_u32 s92, s68, 0x3b000
	s_addc_u32 s93, s69, 0
	global_store_dword v239, v63, s[92:93]
	s_add_u32 s92, s68, 0x20100
	s_addc_u32 s93, s69, 0
	global_load_dword v128, v239, s[92:93]
	s_add_u32 s92, s68, 0x21100
	s_addc_u32 s93, s69, 0
	global_load_dword v129, v239, s[92:93]
	s_add_u32 s92, s68, 0x22100
	s_addc_u32 s93, s69, 0
	global_load_dword v130, v239, s[92:93]
	s_add_u32 s92, s68, 0x23100
	s_addc_u32 s93, s69, 0
	global_load_dword v131, v239, s[92:93]
	s_add_u32 s92, s68, 0x28100
	s_addc_u32 s93, s69, 0
	global_load_dword v132, v239, s[92:93]
	s_add_u32 s92, s68, 0x29100
	s_addc_u32 s93, s69, 0
	global_load_dword v133, v239, s[92:93]
	s_add_u32 s92, s68, 0x2a100
	s_addc_u32 s93, s69, 0
	global_load_dword v134, v239, s[92:93]
	s_add_u32 s92, s68, 0x2b100
	s_addc_u32 s93, s69, 0
	global_load_dword v135, v239, s[92:93]
	s_add_u32 s92, s68, 0x30100
	s_addc_u32 s93, s69, 0
	global_load_dword v136, v239, s[92:93]
	s_add_u32 s92, s68, 0x31100
	s_addc_u32 s93, s69, 0
	global_load_dword v137, v239, s[92:93]
	s_add_u32 s92, s68, 0x32100
	s_addc_u32 s93, s69, 0
	global_load_dword v138, v239, s[92:93]
	s_add_u32 s92, s68, 0x33100
	s_addc_u32 s93, s69, 0
	global_load_dword v139, v239, s[92:93]
	s_add_u32 s92, s68, 0x38100
	s_addc_u32 s93, s69, 0
	global_load_dword v140, v239, s[92:93]
	s_add_u32 s92, s68, 0x39100
	s_addc_u32 s93, s69, 0
	global_load_dword v141, v239, s[92:93]
	s_add_u32 s92, s68, 0x3a100
	s_addc_u32 s93, s69, 0
	global_load_dword v142, v239, s[92:93]
	s_add_u32 s92, s68, 0x3b100
	s_addc_u32 s93, s69, 0
	global_load_dword v143, v239, s[92:93]
	s_waitcnt vmcnt(32)
; DI int crow(int i, int h) { return (i & 3) + 8 * (i >> 2) + 4 * h; }
; template <int NT, class Epi>
; DI void gemm_tile(const u16* __restrict__ A, int lda, const u16* __restrict__ Bt, int ldb, int K, int m0, int n0, const Epi& epi, char* smem) {
;     ...
; #pragma unroll
;   for (int mt = 0; mt < 2; ++mt)
; #pragma unroll
;     for (int nt = 0; nt < NT; ++nt) epi(acc[mt][nt], m0 + wm * 64 + mt * 32, n0 + wn * 32 * NT + nt * 32, lane);
;   DI void operator()(const f32x16& acc, int row0, int col0, int lane) const {
;     const int r = lane & 31, h = lane >> 5, col = col0 + r;
; #pragma unroll
;     for (int i = 0; i < 16; ++i) { float* q = H + (size_t)(row0 + crow(i, h)) * DM + col; *q = *q + acc[i]; }
;   }
	v_add_f32_e32 v32, v32, v240
	v_add_f32_e32 v33, v33, v241
	v_add_f32_e32 v34, v34, v242
	v_add_f32_e32 v35, v35, v243
	v_add_f32_e32 v36, v36, v244
	v_add_f32_e32 v37, v37, v245
	v_add_f32_e32 v38, v38, v246
	v_add_f32_e32 v39, v39, v247
	v_add_f32_e32 v40, v40, v248
	v_add_f32_e32 v41, v41, v249
	v_add_f32_e32 v42, v42, v250
	v_add_f32_e32 v43, v43, v251
	v_add_f32_e32 v44, v44, v252
	v_add_f32_e32 v45, v45, v253
	v_add_f32_e32 v46, v46, v254
	v_add_f32_e32 v47, v47, v255
	s_add_u32 s92, s68, 0x20080
	s_addc_u32 s93, s69, 0
	global_store_dword v239, v32, s[92:93]
	s_add_u32 s92, s68, 0x21080
	s_addc_u32 s93, s69, 0
	global_store_dword v239, v33, s[92:93]
	s_add_u32 s92, s68, 0x22080
	s_addc_u32 s93, s69, 0
	global_store_dword v239, v34, s[92:93]
	s_add_u32 s92, s68, 0x23080
	s_addc_u32 s93, s69, 0
	global_store_dword v239, v35, s[92:93]
	s_add_u32 s92, s68, 0x28080
	s_addc_u32 s93, s69, 0
	global_store_dword v239, v36, s[92:93]
	s_add_u32 s92, s68, 0x29080
	s_addc_u32 s93, s69, 0
	global_store_dword v239, v37, s[92:93]
	s_add_u32 s92, s68, 0x2a080
	s_addc_u32 s93, s69, 0
	global_store_dword v239, v38, s[92:93]
	s_add_u32 s92, s68, 0x2b080
	s_addc_u32 s93, s69, 0
	global_store_dword v239, v39, s[92:93]
	s_add_u32 s92, s68, 0x30080
	s_addc_u32 s93, s69, 0
	global_store_dword v239, v40, s[92:93]
	s_add_u32 s92, s68, 0x31080
	s_addc_u32 s93, s69, 0
	global_store_dword v239, v41, s[92:93]
	s_add_u32 s92, s68, 0x32080
	s_addc_u32 s93, s69, 0
	global_store_dword v239, v42, s[92:93]
	s_add_u32 s92, s68, 0x33080
	s_addc_u32 s93, s69, 0
	global_store_dword v239, v43, s[92:93]
	s_add_u32 s92, s68, 0x38080
	s_addc_u32 s93, s69, 0
	global_store_dword v239, v44, s[92:93]
	s_add_u32 s92, s68, 0x39080
	s_addc_u32 s93, s69, 0
	global_store_dword v239, v45, s[92:93]
	s_add_u32 s92, s68, 0x3a080
	s_addc_u32 s93, s69, 0
	global_store_dword v239, v46, s[92:93]
	s_add_u32 s92, s68, 0x3b080
	s_addc_u32 s93, s69, 0
	global_store_dword v239, v47, s[92:93]
	s_add_u32 s92, s68, 0x20180
	s_addc_u32 s93, s69, 0
	global_load_dword v240, v239, s[92:93]
	s_add_u32 s92, s68, 0x21180
	s_addc_u32 s93, s69, 0
	global_load_dword v241, v239, s[92:93]
	s_add_u32 s92, s68, 0x22180
	s_addc_u32 s93, s69, 0
	global_load_dword v242, v239, s[92:93]
	s_add_u32 s92, s68, 0x23180
	s_addc_u32 s93, s69, 0
	global_load_dword v243, v239, s[92:93]
	s_add_u32 s92, s68, 0x28180
	s_addc_u32 s93, s69, 0
	global_load_dword v244, v239, s[92:93]
	s_add_u32 s92, s68, 0x29180
	s_addc_u32 s93, s69, 0
	global_load_dword v245, v239, s[92:93]
	s_add_u32 s92, s68, 0x2a180
	s_addc_u32 s93, s69, 0
	global_load_dword v246, v239, s[92:93]
	s_add_u32 s92, s68, 0x2b180
	s_addc_u32 s93, s69, 0
	global_load_dword v247, v239, s[92:93]
	s_add_u32 s92, s68, 0x30180
	s_addc_u32 s93, s69, 0
	global_load_dword v248, v239, s[92:93]
	s_add_u32 s92, s68, 0x31180
	s_addc_u32 s93, s69, 0
	global_load_dword v249, v239, s[92:93]
	s_add_u32 s92, s68, 0x32180
	s_addc_u32 s93, s69, 0
	global_load_dword v250, v239, s[92:93]
	s_add_u32 s92, s68, 0x33180
	s_addc_u32 s93, s69, 0
	global_load_dword v251, v239, s[92:93]
	s_add_u32 s92, s68, 0x38180
	s_addc_u32 s93, s69, 0
	global_load_dword v252, v239, s[92:93]
	s_add_u32 s92, s68, 0x39180
	s_addc_u32 s93, s69, 0
	global_load_dword v253, v239, s[92:93]
	s_add_u32 s92, s68, 0x3a180
	s_addc_u32 s93, s69, 0
	global_load_dword v254, v239, s[92:93]
	s_add_u32 s92, s68, 0x3b180
	s_addc_u32 s93, s69, 0
	global_load_dword v255, v239, s[92:93]
	s_waitcnt vmcnt(32)
; DI int crow(int i, int h) { return (i & 3) + 8 * (i >> 2) + 4 * h; }
; template <int NT, class Epi>
; DI void gemm_tile(const u16* __restrict__ A, int lda, const u16* __restrict__ Bt, int ldb, int K, int m0, int n0, const Epi& epi, char* smem) {
;     ...
; #pragma unroll
;   for (int mt = 0; mt < 2; ++mt)
; #pragma unroll
;     for (int nt = 0; nt < NT; ++nt) epi(acc[mt][nt], m0 + wm * 64 + mt * 32, n0 + wn * 32 * NT + nt * 32, lane);
;   DI void operator()(const f32x16& acc, int row0, int col0, int lane) const {
;     const int r = lane & 31, h = lane >> 5, col = col0 + r;
; #pragma unroll
;     for (int i = 0; i < 16; ++i) { float* q = H + (size_t)(row0 + crow(i, h)) * DM + col; *q = *q + acc[i]; }
;   }
	v_add_f32_e32 v16, v16, v128
	v_add_f32_e32 v17, v17, v129
	v_add_f32_e32 v18, v18, v130
	v_add_f32_e32 v19, v19, v131
	v_add_f32_e32 v20, v20, v132
	v_add_f32_e32 v21, v21, v133
	v_add_f32_e32 v22, v22, v134
	v_add_f32_e32 v23, v23, v135
	v_add_f32_e32 v24, v24, v136
	v_add_f32_e32 v25, v25, v137
	v_add_f32_e32 v26, v26, v138
	v_add_f32_e32 v27, v27, v139
	v_add_f32_e32 v28, v28, v140
	v_add_f32_e32 v29, v29, v141
	v_add_f32_e32 v30, v30, v142
	v_add_f32_e32 v31, v31, v143
	s_add_u32 s92, s68, 0x20100
	s_addc_u32 s93, s69, 0
	global_store_dword v239, v16, s[92:93]
	s_add_u32 s92, s68, 0x21100
	s_addc_u32 s93, s69, 0
	global_store_dword v239, v17, s[92:93]
	s_add_u32 s92, s68, 0x22100
	s_addc_u32 s93, s69, 0
	global_store_dword v239, v18, s[92:93]
	s_add_u32 s92, s68, 0x23100
	s_addc_u32 s93, s69, 0
	global_store_dword v239, v19, s[92:93]
	s_add_u32 s92, s68, 0x28100
	s_addc_u32 s93, s69, 0
	global_store_dword v239, v20, s[92:93]
	s_add_u32 s92, s68, 0x29100
	s_addc_u32 s93, s69, 0
	global_store_dword v239, v21, s[92:93]
	s_add_u32 s92, s68, 0x2a100
	s_addc_u32 s93, s69, 0
	global_store_dword v239, v22, s[92:93]
	s_add_u32 s92, s68, 0x2b100
	s_addc_u32 s93, s69, 0
	global_store_dword v239, v23, s[92:93]
	s_add_u32 s92, s68, 0x30100
	s_addc_u32 s93, s69, 0
	global_store_dword v239, v24, s[92:93]
	s_add_u32 s92, s68, 0x31100
	s_addc_u32 s93, s69, 0
	global_store_dword v239, v25, s[92:93]
	s_add_u32 s92, s68, 0x32100
	s_addc_u32 s93, s69, 0
	global_store_dword v239, v26, s[92:93]
	s_add_u32 s92, s68, 0x33100
	s_addc_u32 s93, s69, 0
	global_store_dword v239, v27, s[92:93]
	s_add_u32 s92, s68, 0x38100
	s_addc_u32 s93, s69, 0
	global_store_dword v239, v28, s[92:93]
	s_add_u32 s92, s68, 0x39100
	s_addc_u32 s93, s69, 0
	global_store_dword v239, v29, s[92:93]
	s_add_u32 s92, s68, 0x3a100
	s_addc_u32 s93, s69, 0
	global_store_dword v239, v30, s[92:93]
	s_add_u32 s92, s68, 0x3b100
	s_addc_u32 s93, s69, 0
	global_store_dword v239, v31, s[92:93]
	s_waitcnt vmcnt(16)
	v_add_f32_e32 v0, v0, v240
	v_add_f32_e32 v1, v1, v241
	v_add_f32_e32 v2, v2, v242
	v_add_f32_e32 v3, v3, v243
	v_add_f32_e32 v4, v4, v244
	v_add_f32_e32 v5, v5, v245
	v_add_f32_e32 v6, v6, v246
	v_add_f32_e32 v7, v7, v247
	v_add_f32_e32 v8, v8, v248
	v_add_f32_e32 v9, v9, v249
	v_add_f32_e32 v10, v10, v250
	v_add_f32_e32 v11, v11, v251
	v_add_f32_e32 v12, v12, v252
	v_add_f32_e32 v13, v13, v253
	v_add_f32_e32 v14, v14, v254
	v_add_f32_e32 v15, v15, v255
	s_add_u32 s92, s68, 0x20180
	s_addc_u32 s93, s69, 0
	global_store_dword v239, v0, s[92:93]
	s_add_u32 s92, s68, 0x21180
	s_addc_u32 s93, s69, 0
	global_store_dword v239, v1, s[92:93]
	s_add_u32 s92, s68, 0x22180
	s_addc_u32 s93, s69, 0
	global_store_dword v239, v2, s[92:93]
	s_add_u32 s92, s68, 0x23180
	s_addc_u32 s93, s69, 0
	global_store_dword v239, v3, s[92:93]
	s_add_u32 s92, s68, 0x28180
	s_addc_u32 s93, s69, 0
	global_store_dword v239, v4, s[92:93]
	s_add_u32 s92, s68, 0x29180
	s_addc_u32 s93, s69, 0
	global_store_dword v239, v5, s[92:93]
	s_add_u32 s92, s68, 0x2a180
	s_addc_u32 s93, s69, 0
	global_store_dword v239, v6, s[92:93]
	s_add_u32 s92, s68, 0x2b180
	s_addc_u32 s93, s69, 0
	global_store_dword v239, v7, s[92:93]
	s_add_u32 s92, s68, 0x30180
	s_addc_u32 s93, s69, 0
	global_store_dword v239, v8, s[92:93]
	s_add_u32 s92, s68, 0x31180
	s_addc_u32 s93, s69, 0
	global_store_dword v239, v9, s[92:93]
	s_add_u32 s92, s68, 0x32180
	s_addc_u32 s93, s69, 0
	global_store_dword v239, v10, s[92:93]
	s_add_u32 s92, s68, 0x33180
	s_addc_u32 s93, s69, 0
	global_store_dword v239, v11, s[92:93]
	s_add_u32 s92, s68, 0x38180
	s_addc_u32 s93, s69, 0
	global_store_dword v239, v12, s[92:93]
	s_add_u32 s92, s68, 0x39180
	s_addc_u32 s93, s69, 0
	global_store_dword v239, v13, s[92:93]
	s_add_u32 s92, s68, 0x3a180
	s_addc_u32 s93, s69, 0
	global_store_dword v239, v14, s[92:93]
	s_add_u32 s92, s68, 0x3b180
	s_addc_u32 s93, s69, 0
	global_store_dword v239, v15, s[92:93]
	s_cmp_lg_u32 s91, 0
	s_cbranch_scc1 .LBB0_421

; DI f32x16 mfma32(bf16x8 a, bf16x8 b, f32x16 c) { return __builtin_amdgcn_mfma_f32_32x32x16_bf16(a, b, c, 0, 0, 0); }
; template <int NT, class Epi>
; DI void gemm_tile(const u16* __restrict__ A, int lda, const u16* __restrict__ Bt, int ldb, int K, int m0, int n0, const Epi& epi, char* smem) {
;     ...
;   for (int kt = 0; kt < nk; ++kt) {
; #pragma unroll
;     for (int i = 0; i < 4; ++i) *(u32x4*)(As + (lrow + 32 * i) * 72 + lch * 8) = ra[i];
; #pragma unroll
;     for (int i = 0; i < NB8; ++i) *(u32x4*)(Bs + (lrow + 32 * i) * 72 + lch * 8) = rb[i];
;     __syncthreads();
;     if (kt + 1 < nk) {
;       const int k0 = (kt + 1) * 64;
; #pragma unroll
;       for (int i = 0; i < 4; ++i) ra[i] = *(const u32x4*)(Ap + (size_t)(32 * i) * lda + k0);
; #pragma unroll
;       for (int i = 0; i < NB8; ++i) rb[i] = *(const u32x4*)(Bp + (size_t)(32 * i) * ldb + k0);
;     }
; #pragma unroll
;     for (int ks = 0; ks < 4; ++ks) {
;       bf16x8 a[2], b[NT];
; #pragma unroll
;       for (int mt = 0; mt < 2; ++mt) a[mt] = *(const bf16x8*)(As + (wm * 64 + mt * 32 + r) * 72 + ks * 16 + h * 8);
; #pragma unroll
;       for (int nt = 0; nt < NT; ++nt) b[nt] = *(const bf16x8*)(Bs + (wn * 32 * NT + nt * 32 + r) * 72 + ks * 16 + h * 8);
; #pragma unroll
;       for (int mt = 0; mt < 2; ++mt)
; #pragma unroll
;         for (int nt = 0; nt < NT; ++nt) acc[mt][nt] = mfma32(a[mt], b[nt], acc[mt][nt]);
;     }
;     __syncthreads();
;   }
.LBB0_455:
	s_waitcnt vmcnt(11)
	ds_write_b128 v206, v[128:131]
	s_waitcnt vmcnt(10)
	ds_write_b128 v206, v[132:135] offset:4608
	s_waitcnt vmcnt(9)
	ds_write_b128 v206, v[136:139] offset:9216
	s_waitcnt vmcnt(8)
	ds_write_b128 v206, v[140:143] offset:13824
	s_waitcnt vmcnt(7)
	ds_write_b128 v206, v[144:147] offset:18432
	s_waitcnt vmcnt(6)
	ds_write_b128 v206, v[148:151] offset:23040
	s_waitcnt vmcnt(5)
	ds_write_b128 v206, v[152:155] offset:27648
	s_waitcnt vmcnt(4)
	ds_write_b128 v206, v[156:159] offset:32256
	s_waitcnt vmcnt(3)
	ds_write_b128 v206, v[160:163] offset:36864
	s_waitcnt vmcnt(2)
	ds_write_b128 v206, v[164:167] offset:41472
	s_waitcnt vmcnt(1)
	ds_write_b128 v206, v[168:171] offset:46080
	s_waitcnt vmcnt(0)
	ds_write_b128 v206, v[172:175] offset:50688
	s_waitcnt lgkmcnt(0)
	s_barrier
	s_add_u32 s92, s16, s30
	s_addc_u32 s93, s17, 0
	v_lshl_add_u64 v[238:239], v[202:203], 0, s[92:93]
	global_load_dwordx4 v[128:131], v[238:239], off offset:128
	s_add_u32 s92, s16, s31
	s_addc_u32 s93, s17, 0
	v_lshl_add_u64 v[238:239], v[202:203], 0, s[92:93]
	global_load_dwordx4 v[132:135], v[238:239], off offset:128
	s_add_u32 s92, s16, s34
	s_addc_u32 s93, s17, 0
	v_lshl_add_u64 v[238:239], v[202:203], 0, s[92:93]
	global_load_dwordx4 v[136:139], v[238:239], off offset:128
	s_add_u32 s92, s16, s35
	s_addc_u32 s93, s17, 0
	v_lshl_add_u64 v[238:239], v[202:203], 0, s[92:93]
	global_load_dwordx4 v[140:143], v[238:239], off offset:128
	s_add_u32 s92, s16, s36
	s_addc_u32 s93, s17, 0
	v_lshl_add_u64 v[238:239], v[204:205], 0, s[92:93]
	global_load_dwordx4 v[144:147], v[238:239], off offset:128
	s_add_u32 s92, s16, s37
	s_addc_u32 s93, s17, 0
	v_lshl_add_u64 v[238:239], v[204:205], 0, s[92:93]
	global_load_dwordx4 v[148:151], v[238:239], off offset:128
	s_add_u32 s92, s16, s38
	s_addc_u32 s93, s17, 0
	v_lshl_add_u64 v[238:239], v[204:205], 0, s[92:93]
	global_load_dwordx4 v[152:155], v[238:239], off offset:128
	s_add_u32 s92, s16, s39
	s_addc_u32 s93, s17, 0
	v_lshl_add_u64 v[238:239], v[204:205], 0, s[92:93]
	global_load_dwordx4 v[156:159], v[238:239], off offset:128
	s_add_u32 s92, s16, s40
	s_addc_u32 s93, s17, 0
	v_lshl_add_u64 v[238:239], v[204:205], 0, s[92:93]
	global_load_dwordx4 v[160:163], v[238:239], off offset:128
	s_add_u32 s92, s16, s41
	s_addc_u32 s93, s17, 0
	v_lshl_add_u64 v[238:239], v[204:205], 0, s[92:93]
	global_load_dwordx4 v[164:167], v[238:239], off offset:128
	s_add_u32 s92, s16, s42
	s_addc_u32 s93, s17, 0
	v_lshl_add_u64 v[238:239], v[204:205], 0, s[92:93]
	global_load_dwordx4 v[168:171], v[238:239], off offset:128
	s_add_u32 s92, s16, s43
	s_addc_u32 s93, s17, 0
	v_lshl_add_u64 v[238:239], v[204:205], 0, s[92:93]
	global_load_dwordx4 v[172:175], v[238:239], off offset:128
	s_add_u32 s16, s16, 0x80
	s_addc_u32 s17, s17, 0
	s_cmpk_lg_i32 s16, 0x780
	ds_read_b128 v[210:213], v207
	ds_read_b128 v[252:255], v208 offset:18432
	ds_read_b128 v[248:251], v208 offset:23040
	ds_read_b128 v[244:247], v208 offset:27648
	ds_read_b128 v[240:243], v208 offset:32256
	ds_read_b128 v[222:225], v207 offset:4608
	s_waitcnt lgkmcnt(4)
	v_mfma_f32_32x32x16_bf16 v[112:127], v[210:213], v[252:255], v[112:127]
	s_waitcnt lgkmcnt(3)
	v_mfma_f32_32x32x16_bf16 v[96:111], v[210:213], v[248:251], v[96:111]
	s_waitcnt lgkmcnt(2)
	v_mfma_f32_32x32x16_bf16 v[80:95], v[210:213], v[244:247], v[80:95]
	s_waitcnt lgkmcnt(1)
	v_mfma_f32_32x32x16_bf16 v[64:79], v[210:213], v[240:243], v[64:79]
	ds_read_b128 v[210:213], v207 offset:32
	s_waitcnt lgkmcnt(1)
	v_mfma_f32_32x32x16_bf16 v[48:63], v[222:225], v[252:255], v[48:63]
	ds_read_b128 v[252:255], v208 offset:18464
	v_mfma_f32_32x32x16_bf16 v[32:47], v[222:225], v[248:251], v[32:47]
	ds_read_b128 v[248:251], v208 offset:23072
	v_mfma_f32_32x32x16_bf16 v[16:31], v[222:225], v[244:247], v[16:31]
	ds_read_b128 v[244:247], v208 offset:27680
	v_mfma_f32_32x32x16_bf16 v[0:15], v[222:225], v[240:243], v[0:15]
	ds_read_b128 v[240:243], v208 offset:32288
	ds_read_b128 v[222:225], v207 offset:4640
	s_waitcnt lgkmcnt(4)
	v_mfma_f32_32x32x16_bf16 v[112:127], v[210:213], v[252:255], v[112:127]
	s_waitcnt lgkmcnt(3)
	v_mfma_f32_32x32x16_bf16 v[96:111], v[210:213], v[248:251], v[96:111]
	s_waitcnt lgkmcnt(2)
	v_mfma_f32_32x32x16_bf16 v[80:95], v[210:213], v[244:247], v[80:95]
	s_waitcnt lgkmcnt(1)
	v_mfma_f32_32x32x16_bf16 v[64:79], v[210:213], v[240:243], v[64:79]
	ds_read_b128 v[210:213], v207 offset:64
	s_waitcnt lgkmcnt(1)
	v_mfma_f32_32x32x16_bf16 v[48:63], v[222:225], v[252:255], v[48:63]
	ds_read_b128 v[252:255], v208 offset:18496
	v_mfma_f32_32x32x16_bf16 v[32:47], v[222:225], v[248:251], v[32:47]
	ds_read_b128 v[248:251], v208 offset:23104
	v_mfma_f32_32x32x16_bf16 v[16:31], v[222:225], v[244:247], v[16:31]
	ds_read_b128 v[244:247], v208 offset:27712
	v_mfma_f32_32x32x16_bf16 v[0:15], v[222:225], v[240:243], v[0:15]
	ds_read_b128 v[240:243], v208 offset:32320
	ds_read_b128 v[222:225], v207 offset:4672
	s_waitcnt lgkmcnt(4)
	v_mfma_f32_32x32x16_bf16 v[112:127], v[210:213], v[252:255], v[112:127]
	s_waitcnt lgkmcnt(3)
	v_mfma_f32_32x32x16_bf16 v[96:111], v[210:213], v[248:251], v[96:111]
	s_waitcnt lgkmcnt(2)
	v_mfma_f32_32x32x16_bf16 v[80:95], v[210:213], v[244:247], v[80:95]
	s_waitcnt lgkmcnt(1)
	v_mfma_f32_32x32x16_bf16 v[64:79], v[210:213], v[240:243], v[64:79]
	ds_read_b128 v[210:213], v207 offset:96
	s_waitcnt lgkmcnt(1)
	v_mfma_f32_32x32x16_bf16 v[48:63], v[222:225], v[252:255], v[48:63]
	ds_read_b128 v[252:255], v208 offset:18528
	v_mfma_f32_32x32x16_bf16 v[32:47], v[222:225], v[248:251], v[32:47]
	ds_read_b128 v[248:251], v208 offset:23136
	v_mfma_f32_32x32x16_bf16 v[16:31], v[222:225], v[244:247], v[16:31]
	ds_read_b128 v[244:247], v208 offset:27744
	v_mfma_f32_32x32x16_bf16 v[0:15], v[222:225], v[240:243], v[0:15]
	ds_read_b128 v[240:243], v208 offset:32352
	ds_read_b128 v[222:225], v207 offset:4704
	s_waitcnt lgkmcnt(4)
	v_mfma_f32_32x32x16_bf16 v[112:127], v[210:213], v[252:255], v[112:127]
	s_waitcnt lgkmcnt(3)
	v_mfma_f32_32x32x16_bf16 v[96:111], v[210:213], v[248:251], v[96:111]
	s_waitcnt lgkmcnt(2)
	v_mfma_f32_32x32x16_bf16 v[80:95], v[210:213], v[244:247], v[80:95]
	s_waitcnt lgkmcnt(1)
	v_mfma_f32_32x32x16_bf16 v[64:79], v[210:213], v[240:243], v[64:79]
	s_waitcnt lgkmcnt(0)
	v_mfma_f32_32x32x16_bf16 v[48:63], v[222:225], v[252:255], v[48:63]
	v_mfma_f32_32x32x16_bf16 v[32:47], v[222:225], v[248:251], v[32:47]
	v_mfma_f32_32x32x16_bf16 v[16:31], v[222:225], v[244:247], v[16:31]
	s_barrier
; DI int crow(int i, int h) { return (i & 3) + 8 * (i >> 2) + 4 * h; }
; DI f32x16 mfma32(bf16x8 a, bf16x8 b, f32x16 c) { return __builtin_amdgcn_mfma_f32_32x32x16_bf16(a, b, c, 0, 0, 0); }
; template <int NT, class Epi>
; DI void gemm_tile(const u16* __restrict__ A, int lda, const u16* __restrict__ Bt, int ldb, int K, int m0, int n0, const Epi& epi, char* smem) {
;     ...
;   for (int kt = 0; kt < nk; ++kt) {
; #pragma unroll
;     for (int i = 0; i < 4; ++i) *(u32x4*)(As + (lrow + 32 * i) * 72 + lch * 8) = ra[i];
; #pragma unroll
;     for (int i = 0; i < NB8; ++i) *(u32x4*)(Bs + (lrow + 32 * i) * 72 + lch * 8) = rb[i];
;     __syncthreads();
;     if (kt + 1 < nk) {
;       const int k0 = (kt + 1) * 64;
; #pragma unroll
;       for (int i = 0; i < 4; ++i) ra[i] = *(const u32x4*)(Ap + (size_t)(32 * i) * lda + k0);
; #pragma unroll
;       for (int i = 0; i < NB8; ++i) rb[i] = *(const u32x4*)(Bp + (size_t)(32 * i) * ldb + k0);
;     }
; #pragma unroll
;     for (int ks = 0; ks < 4; ++ks) {
;       bf16x8 a[2], b[NT];
; #pragma unroll
;       for (int mt = 0; mt < 2; ++mt) a[mt] = *(const bf16x8*)(As + (wm * 64 + mt * 32 + r) * 72 + ks * 16 + h * 8);
; #pragma unroll
;       for (int nt = 0; nt < NT; ++nt) b[nt] = *(const bf16x8*)(Bs + (wn * 32 * NT + nt * 32 + r) * 72 + ks * 16 + h * 8);
; #pragma unroll
;       for (int mt = 0; mt < 2; ++mt)
; #pragma unroll
;         for (int nt = 0; nt < NT; ++nt) acc[mt][nt] = mfma32(a[mt], b[nt], acc[mt][nt]);
;     }
;     __syncthreads();
;   DI void operator()(const f32x16& acc, int row0, int col0, int lane) const {
;     const int r = lane & 31, h = lane >> 5, col = col0 + r;
;     if (col >= N) return;
; #pragma unroll
;     for (int i = 0; i < 16; ++i) C[(size_t)(row0 + crow(i, h)) * ldc + col] = f2bf(acc[i]);
;   }
	v_mfma_f32_32x32x16_bf16 v[0:15], v[222:225], v[240:243], v[0:15]
	s_cbranch_scc1 .LBB0_455
	s_waitcnt vmcnt(11)
	ds_write_b128 v206, v[128:131]
	s_waitcnt vmcnt(10)
	ds_write_b128 v206, v[132:135] offset:4608
	s_waitcnt vmcnt(9)
	ds_write_b128 v206, v[136:139] offset:9216
	s_waitcnt vmcnt(8)
	ds_write_b128 v206, v[140:143] offset:13824
	s_waitcnt vmcnt(7)
	ds_write_b128 v206, v[144:147] offset:18432
	s_waitcnt vmcnt(6)
	ds_write_b128 v206, v[148:151] offset:23040
	s_waitcnt vmcnt(5)
	ds_write_b128 v206, v[152:155] offset:27648
	s_waitcnt vmcnt(4)
	ds_write_b128 v206, v[156:159] offset:32256
	s_waitcnt vmcnt(3)
	ds_write_b128 v206, v[160:163] offset:36864
	s_waitcnt vmcnt(2)
	ds_write_b128 v206, v[164:167] offset:41472
	s_waitcnt vmcnt(1)
	ds_write_b128 v206, v[168:171] offset:46080
	s_waitcnt vmcnt(0)
	ds_write_b128 v206, v[172:175] offset:50688
	s_waitcnt lgkmcnt(0)
	s_barrier
	ds_read_b128 v[128:131], v207 offset:4608
	ds_read_b128 v[132:135], v208 offset:23040
	ds_read_b128 v[136:139], v208 offset:27648
	ds_read_b128 v[140:143], v208 offset:32256
	ds_read_b128 v[144:147], v207
	ds_read_b128 v[148:151], v207 offset:32
	ds_read_b128 v[152:155], v208 offset:18432
	ds_read_b128 v[156:159], v208 offset:18464
	s_waitcnt lgkmcnt(1)
	v_mfma_f32_32x32x16_bf16 v[112:127], v[144:147], v[152:155], v[112:127]
	s_add_i32 s44, s44, s78
	s_add_i32 s18, s18, s19
	s_cmpk_lt_u32 s44, 0x100
	v_mfma_f32_32x32x16_bf16 v[96:111], v[144:147], v[132:135], v[96:111]
	v_mfma_f32_32x32x16_bf16 v[80:95], v[144:147], v[136:139], v[80:95]
	v_mfma_f32_32x32x16_bf16 v[64:79], v[144:147], v[140:143], v[64:79]
	v_mfma_f32_32x32x16_bf16 v[48:63], v[128:131], v[152:155], v[48:63]
	v_mfma_f32_32x32x16_bf16 v[32:47], v[128:131], v[132:135], v[32:47]
	v_mfma_f32_32x32x16_bf16 v[16:31], v[128:131], v[136:139], v[16:31]
	v_mfma_f32_32x32x16_bf16 v[0:15], v[128:131], v[140:143], v[0:15]
	ds_read_b128 v[128:131], v207 offset:4640
	ds_read_b128 v[132:135], v208 offset:23072
	ds_read_b128 v[136:139], v208 offset:27680
	ds_read_b128 v[140:143], v208 offset:32288
	s_waitcnt lgkmcnt(4)
	v_mfma_f32_32x32x16_bf16 v[112:127], v[148:151], v[156:159], v[112:127]
	s_waitcnt lgkmcnt(2)
	v_mfma_f32_32x32x16_bf16 v[96:111], v[148:151], v[132:135], v[96:111]
	s_waitcnt lgkmcnt(1)
	v_mfma_f32_32x32x16_bf16 v[80:95], v[148:151], v[136:139], v[80:95]
	s_waitcnt lgkmcnt(0)
	v_mfma_f32_32x32x16_bf16 v[64:79], v[148:151], v[140:143], v[64:79]
	v_mfma_f32_32x32x16_bf16 v[48:63], v[128:131], v[156:159], v[48:63]
	v_mfma_f32_32x32x16_bf16 v[32:47], v[128:131], v[132:135], v[32:47]
	v_mfma_f32_32x32x16_bf16 v[16:31], v[128:131], v[136:139], v[16:31]
	v_mfma_f32_32x32x16_bf16 v[0:15], v[128:131], v[140:143], v[0:15]
	ds_read_b128 v[128:131], v207 offset:64
	ds_read_b128 v[132:135], v207 offset:4672
	ds_read_b128 v[136:139], v208 offset:18496
	ds_read_b128 v[140:143], v208 offset:23104
	ds_read_b128 v[144:147], v208 offset:27712
	ds_read_b128 v[148:151], v208 offset:32320
	s_waitcnt lgkmcnt(3)
	v_mfma_f32_32x32x16_bf16 v[112:127], v[128:131], v[136:139], v[112:127]
	s_waitcnt lgkmcnt(2)
	v_mfma_f32_32x32x16_bf16 v[96:111], v[128:131], v[140:143], v[96:111]
	s_waitcnt lgkmcnt(1)
	v_mfma_f32_32x32x16_bf16 v[80:95], v[128:131], v[144:147], v[80:95]
	s_waitcnt lgkmcnt(0)
	v_mfma_f32_32x32x16_bf16 v[64:79], v[128:131], v[148:151], v[64:79]
	v_mfma_f32_32x32x16_bf16 v[48:63], v[132:135], v[136:139], v[48:63]
	v_mfma_f32_32x32x16_bf16 v[32:47], v[132:135], v[140:143], v[32:47]
	v_mfma_f32_32x32x16_bf16 v[16:31], v[132:135], v[144:147], v[16:31]
	v_mfma_f32_32x32x16_bf16 v[0:15], v[132:135], v[148:151], v[0:15]
	ds_read_b128 v[128:131], v207 offset:96
	ds_read_b128 v[132:135], v207 offset:4704
	ds_read_b128 v[136:139], v208 offset:18528
	ds_read_b128 v[140:143], v208 offset:23136
	ds_read_b128 v[144:147], v208 offset:27744
	ds_read_b128 v[148:151], v208 offset:32352
	s_waitcnt lgkmcnt(0)
	s_barrier
	v_mfma_f32_32x32x16_bf16 v[112:127], v[128:131], v[136:139], v[112:127]
	v_mfma_f32_32x32x16_bf16 v[96:111], v[128:131], v[140:143], v[96:111]
	s_nop 10
	v_cvt_pk_bf16_f32 v112, v112, s0
	v_cvt_pk_bf16_f32 v114, v114, s0
	v_cvt_pk_bf16_f32 v116, v116, s0
	v_cvt_pk_bf16_f32 v118, v118, s0
	v_cvt_pk_bf16_f32 v120, v120, s0
	v_cvt_pk_bf16_f32 v122, v122, s0
	v_cvt_pk_bf16_f32 v124, v124, s0
	v_mfma_f32_32x32x16_bf16 v[80:95], v[128:131], v[144:147], v[80:95]
	v_cvt_pk_bf16_f32 v126, v126, s0
	v_cvt_pk_bf16_f32 v96, v96, s0
	v_cvt_pk_bf16_f32 v98, v98, s0
	v_mfma_f32_32x32x16_bf16 v[64:79], v[128:131], v[148:151], v[64:79]
	v_or_b32_e32 v128, s58, v179
	v_lshlrev_b32_e32 v192, 1, v128
	v_lshl_add_u64 v[128:129], s[52:53], 0, v[192:193]
	v_add_lshl_u32 v192, v181, s45, 11
	v_lshl_add_u64 v[130:131], v[128:129], 0, v[192:193]
	global_store_short v[130:131], v112, off
	v_cvt_pk_bf16_f32 v112, v113, s0
	v_mfma_f32_32x32x16_bf16 v[48:63], v[132:135], v[136:139], v[48:63]
	global_store_short v[130:131], v112, off offset:2048
	v_cvt_pk_bf16_f32 v136, v117, s0
	v_mov_b32_e32 v117, v193
	v_mov_b32_e32 v137, v193
	v_cvt_pk_bf16_f32 v138, v119, s0
	v_mov_b32_e32 v119, v193
	v_mov_b32_e32 v139, v193
	v_mfma_f32_32x32x16_bf16 v[32:47], v[132:135], v[140:143], v[32:47]
	v_cvt_pk_bf16_f32 v140, v121, s0
	v_mov_b32_e32 v121, v193
	v_mov_b32_e32 v141, v193
	v_cvt_pk_bf16_f32 v142, v123, s0
	v_mov_b32_e32 v123, v193
	v_mov_b32_e32 v143, v193
	global_store_short v[130:131], v96, off offset:64
	v_mfma_f32_32x32x16_bf16 v[16:31], v[132:135], v[144:147], v[16:31]
	v_cvt_pk_bf16_f32 v144, v125, s0
	v_mov_b32_e32 v125, v193
	v_mov_b32_e32 v145, v193
	v_cvt_pk_bf16_f32 v146, v127, s0
	v_mov_b32_e32 v127, v193
	v_cvt_pk_bf16_f32 v96, v97, s0
; DI int crow(int i, int h) { return (i & 3) + 8 * (i >> 2) + 4 * h; }
; template <int NT, class Epi>
; DI void gemm_tile(const u16* __restrict__ A, int lda, const u16* __restrict__ Bt, int ldb, int K, int m0, int n0, const Epi& epi, char* smem) {
;     ...
; #pragma unroll
;   for (int mt = 0; mt < 2; ++mt)
; #pragma unroll
;     for (int nt = 0; nt < NT; ++nt) epi(acc[mt][nt], m0 + wm * 64 + mt * 32, n0 + wn * 32 * NT + nt * 32, lane);
;   DI void operator()(const f32x16& acc, int row0, int col0, int lane) const {
;     const int r = lane & 31, h = lane >> 5, col = col0 + r;
;     if (col >= N) return;
; #pragma unroll
;     for (int i = 0; i < 16; ++i) C[(size_t)(row0 + crow(i, h)) * ldc + col] = f2bf(acc[i]);
;   }
	global_store_short v[130:131], v96, off offset:2112
	v_mfma_f32_32x32x16_bf16 v[0:15], v[132:135], v[148:151], v[0:15]
	v_or_b32_e32 v132, 0x1000, v192
	v_mov_b32_e32 v133, v193
	v_lshl_add_u64 v[112:113], v[128:129], 0, v[132:133]
	global_store_short v[112:113], v114, off
	v_cvt_pk_bf16_f32 v134, v115, s0
	v_or_b32_e32 v114, 0x1800, v192
	v_mov_b32_e32 v115, v193
	v_lshl_add_u64 v[112:113], v[128:129], 0, v[114:115]
	global_store_short v[112:113], v134, off
	v_or_b32_e32 v134, 0x4000, v192
	v_mov_b32_e32 v135, v193
	v_lshl_add_u64 v[112:113], v[128:129], 0, v[134:135]
	global_store_short v[112:113], v116, off
	v_or_b32_e32 v116, 0x4800, v192
	v_lshl_add_u64 v[112:113], v[128:129], 0, v[116:117]
	global_store_short v[112:113], v136, off
	v_or_b32_e32 v136, 0x5000, v192
	v_lshl_add_u64 v[112:113], v[128:129], 0, v[136:137]
	global_store_short v[112:113], v118, off
	v_or_b32_e32 v118, 0x5800, v192
	v_lshl_add_u64 v[112:113], v[128:129], 0, v[118:119]
	global_store_short v[112:113], v138, off
	v_or_b32_e32 v138, 0x8000, v192
	v_lshl_add_u64 v[112:113], v[128:129], 0, v[138:139]
	global_store_short v[112:113], v120, off
	v_or_b32_e32 v120, 0x8800, v192
	v_lshl_add_u64 v[112:113], v[128:129], 0, v[120:121]
	global_store_short v[112:113], v140, off
	v_or_b32_e32 v140, 0x9000, v192
	v_lshl_add_u64 v[112:113], v[128:129], 0, v[140:141]
	global_store_short v[112:113], v122, off
	v_or_b32_e32 v122, 0x9800, v192
	v_lshl_add_u64 v[112:113], v[128:129], 0, v[122:123]
	global_store_short v[112:113], v142, off
	v_or_b32_e32 v142, 0xc000, v192
	v_lshl_add_u64 v[112:113], v[128:129], 0, v[142:143]
	global_store_short v[112:113], v124, off
	v_or_b32_e32 v124, 0xc800, v192
	v_lshl_add_u64 v[112:113], v[128:129], 0, v[124:125]
	global_store_short v[112:113], v144, off
	v_or_b32_e32 v144, 0xd000, v192
	v_lshl_add_u64 v[112:113], v[128:129], 0, v[144:145]
	global_store_short v[112:113], v126, off
	v_or_b32_e32 v126, 0xd800, v192
	v_lshl_add_u64 v[112:113], v[128:129], 0, v[126:127]
	global_store_short v[112:113], v146, off
	v_lshl_add_u64 v[112:113], v[128:129], 0, 64
	v_lshl_add_u64 v[96:97], v[112:113], 0, v[132:133]
	global_store_short v[96:97], v98, off
	v_cvt_pk_bf16_f32 v98, v99, s0
	v_lshl_add_u64 v[96:97], v[112:113], 0, v[114:115]
	global_store_short v[96:97], v98, off
	v_cvt_pk_bf16_f32 v98, v100, s0
	v_lshl_add_u64 v[96:97], v[112:113], 0, v[134:135]
	global_store_short v[96:97], v98, off
	v_cvt_pk_bf16_f32 v98, v101, s0
	v_lshl_add_u64 v[96:97], v[112:113], 0, v[116:117]
	global_store_short v[96:97], v98, off
	v_cvt_pk_bf16_f32 v98, v102, s0
	v_lshl_add_u64 v[96:97], v[112:113], 0, v[136:137]
	global_store_short v[96:97], v98, off
	v_cvt_pk_bf16_f32 v98, v103, s0
	v_lshl_add_u64 v[96:97], v[112:113], 0, v[118:119]
	global_store_short v[96:97], v98, off
	v_cvt_pk_bf16_f32 v98, v104, s0
	v_lshl_add_u64 v[96:97], v[112:113], 0, v[138:139]
	global_store_short v[96:97], v98, off
	v_cvt_pk_bf16_f32 v98, v105, s0
	v_lshl_add_u64 v[96:97], v[112:113], 0, v[120:121]
	global_store_short v[96:97], v98, off
	v_cvt_pk_bf16_f32 v98, v106, s0
	v_lshl_add_u64 v[96:97], v[112:113], 0, v[140:141]
	global_store_short v[96:97], v98, off
	v_cvt_pk_bf16_f32 v98, v107, s0
	v_lshl_add_u64 v[96:97], v[112:113], 0, v[122:123]
	global_store_short v[96:97], v98, off
	v_cvt_pk_bf16_f32 v98, v108, s0
	v_lshl_add_u64 v[96:97], v[112:113], 0, v[142:143]
	global_store_short v[96:97], v98, off
	v_cvt_pk_bf16_f32 v98, v109, s0
	v_lshl_add_u64 v[96:97], v[112:113], 0, v[124:125]
	global_store_short v[96:97], v98, off
	v_cvt_pk_bf16_f32 v98, v110, s0
	v_lshl_add_u64 v[96:97], v[112:113], 0, v[144:145]
	global_store_short v[96:97], v98, off
	v_cvt_pk_bf16_f32 v98, v111, s0
	v_lshl_add_u64 v[96:97], v[112:113], 0, v[126:127]
	v_cvt_pk_bf16_f32 v80, v80, s0
	global_store_short v[96:97], v98, off
	v_lshl_add_u64 v[96:97], v[128:129], 0, s[12:13]
	global_store_short v[130:131], v80, off offset:128
	v_cvt_pk_bf16_f32 v80, v81, s0
	global_store_short v[130:131], v80, off offset:2176
	v_cvt_pk_bf16_f32 v82, v82, s0
	v_lshl_add_u64 v[80:81], v[96:97], 0, v[132:133]
	global_store_short v[80:81], v82, off
	v_cvt_pk_bf16_f32 v82, v83, s0
	v_lshl_add_u64 v[80:81], v[96:97], 0, v[114:115]
	global_store_short v[80:81], v82, off
	v_cvt_pk_bf16_f32 v82, v84, s0
	v_lshl_add_u64 v[80:81], v[96:97], 0, v[134:135]
	global_store_short v[80:81], v82, off
	v_cvt_pk_bf16_f32 v82, v85, s0
	v_lshl_add_u64 v[80:81], v[96:97], 0, v[116:117]
	global_store_short v[80:81], v82, off
	v_cvt_pk_bf16_f32 v82, v86, s0
	v_lshl_add_u64 v[80:81], v[96:97], 0, v[136:137]
	global_store_short v[80:81], v82, off
	v_cvt_pk_bf16_f32 v82, v87, s0
	v_lshl_add_u64 v[80:81], v[96:97], 0, v[118:119]
	global_store_short v[80:81], v82, off
	v_cvt_pk_bf16_f32 v82, v88, s0
	v_lshl_add_u64 v[80:81], v[96:97], 0, v[138:139]
	global_store_short v[80:81], v82, off
	v_cvt_pk_bf16_f32 v82, v89, s0
	v_lshl_add_u64 v[80:81], v[96:97], 0, v[120:121]
	global_store_short v[80:81], v82, off
	v_cvt_pk_bf16_f32 v82, v90, s0
	v_lshl_add_u64 v[80:81], v[96:97], 0, v[140:141]
	global_store_short v[80:81], v82, off
	v_cvt_pk_bf16_f32 v82, v91, s0
	v_lshl_add_u64 v[80:81], v[96:97], 0, v[122:123]
	global_store_short v[80:81], v82, off
	v_cvt_pk_bf16_f32 v82, v92, s0
	v_lshl_add_u64 v[80:81], v[96:97], 0, v[142:143]
	global_store_short v[80:81], v82, off
	v_cvt_pk_bf16_f32 v82, v93, s0
	v_lshl_add_u64 v[80:81], v[96:97], 0, v[124:125]
	global_store_short v[80:81], v82, off
	v_cvt_pk_bf16_f32 v82, v94, s0
	v_lshl_add_u64 v[80:81], v[96:97], 0, v[144:145]
	global_store_short v[80:81], v82, off
	v_cvt_pk_bf16_f32 v82, v95, s0
	v_lshl_add_u64 v[80:81], v[96:97], 0, v[126:127]
; DI int crow(int i, int h) { return (i & 3) + 8 * (i >> 2) + 4 * h; }
; template <int NT, class Epi>
; DI void gemm_tile(const u16* __restrict__ A, int lda, const u16* __restrict__ Bt, int ldb, int K, int m0, int n0, const Epi& epi, char* smem) {
;     ...
; #pragma unroll
;   for (int mt = 0; mt < 2; ++mt)
; #pragma unroll
;     for (int nt = 0; nt < NT; ++nt) epi(acc[mt][nt], m0 + wm * 64 + mt * 32, n0 + wn * 32 * NT + nt * 32, lane);
;   DI void operator()(const f32x16& acc, int row0, int col0, int lane) const {
;     const int r = lane & 31, h = lane >> 5, col = col0 + r;
;     if (col >= N) return;
; #pragma unroll
;     for (int i = 0; i < 16; ++i) C[(size_t)(row0 + crow(i, h)) * ldc + col] = f2bf(acc[i]);
;   }
	v_cvt_pk_bf16_f32 v64, v64, s0
	global_store_short v[80:81], v82, off
	v_lshl_add_u64 v[80:81], v[128:129], 0, s[14:15]
	global_store_short v[130:131], v64, off offset:192
	v_cvt_pk_bf16_f32 v64, v65, s0
	global_store_short v[130:131], v64, off offset:2240
	v_cvt_pk_bf16_f32 v66, v66, s0
	v_lshl_add_u64 v[64:65], v[80:81], 0, v[132:133]
	global_store_short v[64:65], v66, off
	v_cvt_pk_bf16_f32 v66, v67, s0
	v_lshl_add_u64 v[64:65], v[80:81], 0, v[114:115]
	global_store_short v[64:65], v66, off
	v_cvt_pk_bf16_f32 v66, v68, s0
	v_lshl_add_u64 v[64:65], v[80:81], 0, v[134:135]
	global_store_short v[64:65], v66, off
	v_cvt_pk_bf16_f32 v66, v69, s0
	v_lshl_add_u64 v[64:65], v[80:81], 0, v[116:117]
	global_store_short v[64:65], v66, off
	v_cvt_pk_bf16_f32 v66, v70, s0
	v_lshl_add_u64 v[64:65], v[80:81], 0, v[136:137]
	global_store_short v[64:65], v66, off
	v_cvt_pk_bf16_f32 v66, v71, s0
	v_lshl_add_u64 v[64:65], v[80:81], 0, v[118:119]
	global_store_short v[64:65], v66, off
	v_cvt_pk_bf16_f32 v66, v72, s0
	v_lshl_add_u64 v[64:65], v[80:81], 0, v[138:139]
	global_store_short v[64:65], v66, off
	v_cvt_pk_bf16_f32 v66, v73, s0
	v_lshl_add_u64 v[64:65], v[80:81], 0, v[120:121]
	global_store_short v[64:65], v66, off
	v_cvt_pk_bf16_f32 v66, v74, s0
	v_lshl_add_u64 v[64:65], v[80:81], 0, v[140:141]
	global_store_short v[64:65], v66, off
	v_cvt_pk_bf16_f32 v66, v75, s0
	v_lshl_add_u64 v[64:65], v[80:81], 0, v[122:123]
	global_store_short v[64:65], v66, off
	v_cvt_pk_bf16_f32 v66, v76, s0
	v_lshl_add_u64 v[64:65], v[80:81], 0, v[142:143]
	global_store_short v[64:65], v66, off
	v_cvt_pk_bf16_f32 v66, v77, s0
	v_lshl_add_u64 v[64:65], v[80:81], 0, v[124:125]
	global_store_short v[64:65], v66, off
	v_cvt_pk_bf16_f32 v66, v78, s0
	v_lshl_add_u64 v[64:65], v[80:81], 0, v[144:145]
	global_store_short v[64:65], v66, off
	v_cvt_pk_bf16_f32 v66, v79, s0
	v_lshl_add_u64 v[64:65], v[80:81], 0, v[126:127]
	global_store_short v[64:65], v66, off
	v_or_b32_e32 v64, 0x10000, v192
	v_mov_b32_e32 v65, v193
	v_cvt_pk_bf16_f32 v48, v48, s0
	v_lshl_add_u64 v[66:67], v[128:129], 0, v[64:65]
	global_store_short v[66:67], v48, off
	v_cvt_pk_bf16_f32 v68, v49, s0
	v_or_b32_e32 v48, 0x10800, v192
	v_mov_b32_e32 v49, v193
	v_lshl_add_u64 v[66:67], v[128:129], 0, v[48:49]
	global_store_short v[66:67], v68, off
	v_or_b32_e32 v66, 0x11000, v192
	v_mov_b32_e32 v67, v193
	v_cvt_pk_bf16_f32 v50, v50, s0
	v_lshl_add_u64 v[68:69], v[128:129], 0, v[66:67]
	global_store_short v[68:69], v50, off
	v_cvt_pk_bf16_f32 v70, v51, s0
	v_or_b32_e32 v50, 0x11800, v192
	v_mov_b32_e32 v51, v193
	v_lshl_add_u64 v[68:69], v[128:129], 0, v[50:51]
	global_store_short v[68:69], v70, off
	v_or_b32_e32 v68, 0x14000, v192
	v_mov_b32_e32 v69, v193
	v_cvt_pk_bf16_f32 v52, v52, s0
	v_lshl_add_u64 v[70:71], v[128:129], 0, v[68:69]
	global_store_short v[70:71], v52, off
	v_cvt_pk_bf16_f32 v72, v53, s0
	v_or_b32_e32 v52, 0x14800, v192
	v_mov_b32_e32 v53, v193
	v_lshl_add_u64 v[70:71], v[128:129], 0, v[52:53]
	global_store_short v[70:71], v72, off
	v_or_b32_e32 v70, 0x15000, v192
	v_mov_b32_e32 v71, v193
	v_cvt_pk_bf16_f32 v54, v54, s0
	v_lshl_add_u64 v[72:73], v[128:129], 0, v[70:71]
	global_store_short v[72:73], v54, off
	v_cvt_pk_bf16_f32 v74, v55, s0
	v_or_b32_e32 v54, 0x15800, v192
	v_mov_b32_e32 v55, v193
	v_lshl_add_u64 v[72:73], v[128:129], 0, v[54:55]
	global_store_short v[72:73], v74, off
	v_or_b32_e32 v72, 0x18000, v192
	v_mov_b32_e32 v73, v193
	v_cvt_pk_bf16_f32 v56, v56, s0
	v_lshl_add_u64 v[74:75], v[128:129], 0, v[72:73]
	global_store_short v[74:75], v56, off
	v_cvt_pk_bf16_f32 v76, v57, s0
	v_or_b32_e32 v56, 0x18800, v192
	v_mov_b32_e32 v57, v193
	v_lshl_add_u64 v[74:75], v[128:129], 0, v[56:57]
	global_store_short v[74:75], v76, off
	v_or_b32_e32 v74, 0x19000, v192
	v_mov_b32_e32 v75, v193
	v_cvt_pk_bf16_f32 v58, v58, s0
	v_lshl_add_u64 v[76:77], v[128:129], 0, v[74:75]
	global_store_short v[76:77], v58, off
	v_cvt_pk_bf16_f32 v78, v59, s0
	v_or_b32_e32 v58, 0x19800, v192
	v_mov_b32_e32 v59, v193
	v_lshl_add_u64 v[76:77], v[128:129], 0, v[58:59]
	global_store_short v[76:77], v78, off
	v_or_b32_e32 v76, 0x1c000, v192
	v_mov_b32_e32 v77, v193
	v_cvt_pk_bf16_f32 v60, v60, s0
	v_lshl_add_u64 v[78:79], v[128:129], 0, v[76:77]
	global_store_short v[78:79], v60, off
	v_cvt_pk_bf16_f32 v82, v61, s0
	v_or_b32_e32 v60, 0x1c800, v192
	v_mov_b32_e32 v61, v193
	v_lshl_add_u64 v[78:79], v[128:129], 0, v[60:61]
	global_store_short v[78:79], v82, off
	v_or_b32_e32 v78, 0x1d000, v192
	v_mov_b32_e32 v79, v193
	v_cvt_pk_bf16_f32 v62, v62, s0
	v_lshl_add_u64 v[82:83], v[128:129], 0, v[78:79]
	v_or_b32_e32 v192, 0x1d800, v192
	global_store_short v[82:83], v62, off
	v_cvt_pk_bf16_f32 v82, v63, s0
	v_lshl_add_u64 v[62:63], v[128:129], 0, v[192:193]
	global_store_short v[62:63], v82, off
	v_cvt_pk_bf16_f32 v32, v32, s0
	v_lshl_add_u64 v[62:63], v[112:113], 0, v[64:65]
	global_store_short v[62:63], v32, off
	v_cvt_pk_bf16_f32 v62, v33, s0
	v_lshl_add_u64 v[32:33], v[112:113], 0, v[48:49]
	global_store_short v[32:33], v62, off
	v_cvt_pk_bf16_f32 v34, v34, s0
	v_lshl_add_u64 v[32:33], v[112:113], 0, v[66:67]
	global_store_short v[32:33], v34, off
	v_cvt_pk_bf16_f32 v34, v35, s0
	v_lshl_add_u64 v[32:33], v[112:113], 0, v[50:51]
; DI int crow(int i, int h) { return (i & 3) + 8 * (i >> 2) + 4 * h; }
; template <int NT, class Epi>
; DI void gemm_tile(const u16* __restrict__ A, int lda, const u16* __restrict__ Bt, int ldb, int K, int m0, int n0, const Epi& epi, char* smem) {
;     ...
; #pragma unroll
;   for (int mt = 0; mt < 2; ++mt)
; #pragma unroll
;     for (int nt = 0; nt < NT; ++nt) epi(acc[mt][nt], m0 + wm * 64 + mt * 32, n0 + wn * 32 * NT + nt * 32, lane);
;   DI void operator()(const f32x16& acc, int row0, int col0, int lane) const {
;     const int r = lane & 31, h = lane >> 5, col = col0 + r;
;     if (col >= N) return;
; #pragma unroll
;     for (int i = 0; i < 16; ++i) C[(size_t)(row0 + crow(i, h)) * ldc + col] = f2bf(acc[i]);
;   }
	global_store_short v[32:33], v34, off
	v_cvt_pk_bf16_f32 v34, v36, s0
	v_lshl_add_u64 v[32:33], v[112:113], 0, v[68:69]
	global_store_short v[32:33], v34, off
	v_cvt_pk_bf16_f32 v34, v37, s0
	v_lshl_add_u64 v[32:33], v[112:113], 0, v[52:53]
	global_store_short v[32:33], v34, off
	v_cvt_pk_bf16_f32 v34, v38, s0
	v_lshl_add_u64 v[32:33], v[112:113], 0, v[70:71]
	global_store_short v[32:33], v34, off
	v_cvt_pk_bf16_f32 v34, v39, s0
	v_lshl_add_u64 v[32:33], v[112:113], 0, v[54:55]
	global_store_short v[32:33], v34, off
	v_cvt_pk_bf16_f32 v34, v40, s0
	v_lshl_add_u64 v[32:33], v[112:113], 0, v[72:73]
	global_store_short v[32:33], v34, off
	v_cvt_pk_bf16_f32 v34, v41, s0
	v_lshl_add_u64 v[32:33], v[112:113], 0, v[56:57]
	global_store_short v[32:33], v34, off
	v_cvt_pk_bf16_f32 v34, v42, s0
	v_lshl_add_u64 v[32:33], v[112:113], 0, v[74:75]
	global_store_short v[32:33], v34, off
	v_cvt_pk_bf16_f32 v34, v43, s0
	v_lshl_add_u64 v[32:33], v[112:113], 0, v[58:59]
	global_store_short v[32:33], v34, off
	v_cvt_pk_bf16_f32 v34, v44, s0
	v_lshl_add_u64 v[32:33], v[112:113], 0, v[76:77]
	global_store_short v[32:33], v34, off
	v_cvt_pk_bf16_f32 v34, v45, s0
	v_lshl_add_u64 v[32:33], v[112:113], 0, v[60:61]
	global_store_short v[32:33], v34, off
	v_cvt_pk_bf16_f32 v34, v46, s0
	v_lshl_add_u64 v[32:33], v[112:113], 0, v[78:79]
	global_store_short v[32:33], v34, off
	v_cvt_pk_bf16_f32 v34, v47, s0
	v_lshl_add_u64 v[32:33], v[112:113], 0, v[192:193]
	global_store_short v[32:33], v34, off
	v_cvt_pk_bf16_f32 v16, v16, s0
	v_lshl_add_u64 v[32:33], v[96:97], 0, v[64:65]
	global_store_short v[32:33], v16, off
	v_cvt_pk_bf16_f32 v32, v17, s0
	v_lshl_add_u64 v[16:17], v[96:97], 0, v[48:49]
	global_store_short v[16:17], v32, off
	v_cvt_pk_bf16_f32 v18, v18, s0
	v_lshl_add_u64 v[16:17], v[96:97], 0, v[66:67]
	global_store_short v[16:17], v18, off
	v_cvt_pk_bf16_f32 v18, v19, s0
	v_lshl_add_u64 v[16:17], v[96:97], 0, v[50:51]
	global_store_short v[16:17], v18, off
	v_cvt_pk_bf16_f32 v18, v20, s0
	v_lshl_add_u64 v[16:17], v[96:97], 0, v[68:69]
	global_store_short v[16:17], v18, off
	v_cvt_pk_bf16_f32 v18, v21, s0
	v_lshl_add_u64 v[16:17], v[96:97], 0, v[52:53]
	global_store_short v[16:17], v18, off
	v_cvt_pk_bf16_f32 v18, v22, s0
	v_lshl_add_u64 v[16:17], v[96:97], 0, v[70:71]
	global_store_short v[16:17], v18, off
	v_cvt_pk_bf16_f32 v18, v23, s0
	v_lshl_add_u64 v[16:17], v[96:97], 0, v[54:55]
	global_store_short v[16:17], v18, off
	v_cvt_pk_bf16_f32 v18, v24, s0
	v_lshl_add_u64 v[16:17], v[96:97], 0, v[72:73]
	global_store_short v[16:17], v18, off
	v_cvt_pk_bf16_f32 v18, v25, s0
	v_lshl_add_u64 v[16:17], v[96:97], 0, v[56:57]
	global_store_short v[16:17], v18, off
	v_cvt_pk_bf16_f32 v18, v26, s0
	v_lshl_add_u64 v[16:17], v[96:97], 0, v[74:75]
	global_store_short v[16:17], v18, off
	v_cvt_pk_bf16_f32 v18, v27, s0
	v_lshl_add_u64 v[16:17], v[96:97], 0, v[58:59]
	global_store_short v[16:17], v18, off
	v_cvt_pk_bf16_f32 v18, v28, s0
	v_lshl_add_u64 v[16:17], v[96:97], 0, v[76:77]
	global_store_short v[16:17], v18, off
	v_cvt_pk_bf16_f32 v18, v29, s0
	v_lshl_add_u64 v[16:17], v[96:97], 0, v[60:61]
	global_store_short v[16:17], v18, off
	v_cvt_pk_bf16_f32 v18, v30, s0
	v_lshl_add_u64 v[16:17], v[96:97], 0, v[78:79]
	global_store_short v[16:17], v18, off
	v_cvt_pk_bf16_f32 v18, v31, s0
	v_lshl_add_u64 v[16:17], v[96:97], 0, v[192:193]
	global_store_short v[16:17], v18, off
	v_cvt_pk_bf16_f32 v0, v0, s0
	v_lshl_add_u64 v[16:17], v[80:81], 0, v[64:65]
	global_store_short v[16:17], v0, off
	v_cvt_pk_bf16_f32 v16, v1, s0
	v_lshl_add_u64 v[0:1], v[80:81], 0, v[48:49]
	global_store_short v[0:1], v16, off
	v_cvt_pk_bf16_f32 v2, v2, s0
	v_lshl_add_u64 v[0:1], v[80:81], 0, v[66:67]
	global_store_short v[0:1], v2, off
	v_cvt_pk_bf16_f32 v2, v3, s0
	v_lshl_add_u64 v[0:1], v[80:81], 0, v[50:51]
	global_store_short v[0:1], v2, off
	v_cvt_pk_bf16_f32 v2, v4, s0
	v_lshl_add_u64 v[0:1], v[80:81], 0, v[68:69]
	global_store_short v[0:1], v2, off
	v_cvt_pk_bf16_f32 v2, v5, s0
	v_lshl_add_u64 v[0:1], v[80:81], 0, v[52:53]
	global_store_short v[0:1], v2, off
	v_cvt_pk_bf16_f32 v2, v6, s0
	v_lshl_add_u64 v[0:1], v[80:81], 0, v[70:71]
	global_store_short v[0:1], v2, off
	v_cvt_pk_bf16_f32 v2, v7, s0
	v_lshl_add_u64 v[0:1], v[80:81], 0, v[54:55]
	global_store_short v[0:1], v2, off
	v_cvt_pk_bf16_f32 v2, v8, s0
	v_lshl_add_u64 v[0:1], v[80:81], 0, v[72:73]
	global_store_short v[0:1], v2, off
	v_cvt_pk_bf16_f32 v2, v9, s0
	v_lshl_add_u64 v[0:1], v[80:81], 0, v[56:57]
	global_store_short v[0:1], v2, off
	v_cvt_pk_bf16_f32 v2, v10, s0
	v_lshl_add_u64 v[0:1], v[80:81], 0, v[74:75]
	global_store_short v[0:1], v2, off
	v_cvt_pk_bf16_f32 v2, v11, s0
	v_lshl_add_u64 v[0:1], v[80:81], 0, v[58:59]
	global_store_short v[0:1], v2, off
	v_cvt_pk_bf16_f32 v2, v12, s0
	v_lshl_add_u64 v[0:1], v[80:81], 0, v[76:77]
	global_store_short v[0:1], v2, off
	v_cvt_pk_bf16_f32 v2, v13, s0
	v_lshl_add_u64 v[0:1], v[80:81], 0, v[60:61]
	global_store_short v[0:1], v2, off
	v_cvt_pk_bf16_f32 v2, v14, s0
	v_lshl_add_u64 v[0:1], v[80:81], 0, v[78:79]
	global_store_short v[0:1], v2, off
	v_cvt_pk_bf16_f32 v2, v15, s0
	v_lshl_add_u64 v[0:1], v[80:81], 0, v[192:193]
	global_store_short v[0:1], v2, off
	s_cbranch_scc1 .LBB0_454

; DI f32x16 mfma32(bf16x8 a, bf16x8 b, f32x16 c) { return __builtin_amdgcn_mfma_f32_32x32x16_bf16(a, b, c, 0, 0, 0); }
; template <int NT, class Epi>
; DI void gemm_tile(const u16* __restrict__ A, int lda, const u16* __restrict__ Bt, int ldb, int K, int m0, int n0, const Epi& epi, char* smem) {
;     ...
;   for (int kt = 0; kt < nk; ++kt) {
; #pragma unroll
;     for (int i = 0; i < 4; ++i) *(u32x4*)(As + (lrow + 32 * i) * 72 + lch * 8) = ra[i];
; #pragma unroll
;     for (int i = 0; i < NB8; ++i) *(u32x4*)(Bs + (lrow + 32 * i) * 72 + lch * 8) = rb[i];
;     __syncthreads();
;     if (kt + 1 < nk) {
;       const int k0 = (kt + 1) * 64;
; #pragma unroll
;       for (int i = 0; i < 4; ++i) ra[i] = *(const u32x4*)(Ap + (size_t)(32 * i) * lda + k0);
; #pragma unroll
;       for (int i = 0; i < NB8; ++i) rb[i] = *(const u32x4*)(Bp + (size_t)(32 * i) * ldb + k0);
;     }
; #pragma unroll
;     for (int ks = 0; ks < 4; ++ks) {
;       bf16x8 a[2], b[NT];
; #pragma unroll
;       for (int mt = 0; mt < 2; ++mt) a[mt] = *(const bf16x8*)(As + (wm * 64 + mt * 32 + r) * 72 + ks * 16 + h * 8);
; #pragma unroll
;       for (int nt = 0; nt < NT; ++nt) b[nt] = *(const bf16x8*)(Bs + (wn * 32 * NT + nt * 32 + r) * 72 + ks * 16 + h * 8);
; #pragma unroll
;       for (int mt = 0; mt < 2; ++mt)
; #pragma unroll
;         for (int nt = 0; nt < NT; ++nt) acc[mt][nt] = mfma32(a[mt], b[nt], acc[mt][nt]);
;     }
;     __syncthreads();
;   }
.LBB0_520:
	s_waitcnt vmcnt(11)
	ds_write_b128 v185, v[128:131]
	s_waitcnt vmcnt(10)
	ds_write_b128 v185, v[132:135] offset:4608
	s_waitcnt vmcnt(9)
	ds_write_b128 v185, v[136:139] offset:9216
	s_waitcnt vmcnt(8)
	ds_write_b128 v185, v[140:143] offset:13824
	s_waitcnt vmcnt(7)
	ds_write_b128 v185, v[144:147] offset:18432
	s_waitcnt vmcnt(6)
	ds_write_b128 v185, v[148:151] offset:23040
	s_waitcnt vmcnt(5)
	ds_write_b128 v185, v[152:155] offset:27648
	s_waitcnt vmcnt(4)
	ds_write_b128 v185, v[156:159] offset:32256
	s_waitcnt vmcnt(3)
	ds_write_b128 v185, v[160:163] offset:36864
	s_waitcnt vmcnt(2)
	ds_write_b128 v185, v[164:167] offset:41472
	s_waitcnt vmcnt(1)
	ds_write_b128 v185, v[168:171] offset:46080
	s_waitcnt vmcnt(0)
	ds_write_b128 v185, v[172:175] offset:50688
	s_waitcnt lgkmcnt(0)
	s_barrier
	s_add_u32 s92, s12, s26
	s_addc_u32 s93, s13, 0
	v_lshl_add_u64 v[192:193], v[208:209], 0, s[92:93]
	global_load_dwordx4 v[128:131], v[192:193], off offset:128
	s_add_u32 s92, s12, s27
	s_addc_u32 s93, s13, 0
	v_lshl_add_u64 v[192:193], v[208:209], 0, s[92:93]
	global_load_dwordx4 v[132:135], v[192:193], off offset:128
	s_add_u32 s92, s12, s28
	s_addc_u32 s93, s13, 0
	v_lshl_add_u64 v[192:193], v[208:209], 0, s[92:93]
	global_load_dwordx4 v[136:139], v[192:193], off offset:128
	s_add_u32 s92, s12, s29
	s_addc_u32 s93, s13, 0
	v_lshl_add_u64 v[192:193], v[208:209], 0, s[92:93]
	global_load_dwordx4 v[140:143], v[192:193], off offset:128
	s_add_u32 s92, s12, s30
	s_addc_u32 s93, s13, 0
	v_lshl_add_u64 v[192:193], v[210:211], 0, s[92:93]
	global_load_dwordx4 v[144:147], v[192:193], off offset:128
	s_add_u32 s92, s12, s31
	s_addc_u32 s93, s13, 0
	v_lshl_add_u64 v[192:193], v[210:211], 0, s[92:93]
	global_load_dwordx4 v[148:151], v[192:193], off offset:128
	s_add_u32 s92, s12, s34
	s_addc_u32 s93, s13, 0
	v_lshl_add_u64 v[192:193], v[210:211], 0, s[92:93]
	global_load_dwordx4 v[152:155], v[192:193], off offset:128
	s_add_u32 s92, s12, s35
	s_addc_u32 s93, s13, 0
	v_lshl_add_u64 v[192:193], v[210:211], 0, s[92:93]
	global_load_dwordx4 v[156:159], v[192:193], off offset:128
	s_add_u32 s92, s12, s36
	s_addc_u32 s93, s13, 0
	v_lshl_add_u64 v[192:193], v[210:211], 0, s[92:93]
	global_load_dwordx4 v[160:163], v[192:193], off offset:128
	s_add_u32 s92, s12, s37
	s_addc_u32 s93, s13, 0
	v_lshl_add_u64 v[192:193], v[210:211], 0, s[92:93]
	global_load_dwordx4 v[164:167], v[192:193], off offset:128
	s_add_u32 s92, s12, s38
	s_addc_u32 s93, s13, 0
	v_lshl_add_u64 v[192:193], v[210:211], 0, s[92:93]
	global_load_dwordx4 v[168:171], v[192:193], off offset:128
	s_add_u32 s92, s12, s39
	s_addc_u32 s93, s13, 0
	v_lshl_add_u64 v[192:193], v[210:211], 0, s[92:93]
	global_load_dwordx4 v[172:175], v[192:193], off offset:128
	s_add_u32 s12, s12, 0x80
	s_addc_u32 s13, s13, 0
	s_cmpk_lg_i32 s12, 0x780
	ds_read_b128 v[230:233], v197
	ds_read_b128 v[252:255], v199 offset:18432
	ds_read_b128 v[248:251], v199 offset:23040
	ds_read_b128 v[244:247], v199 offset:27648
	ds_read_b128 v[240:243], v199 offset:32256
	ds_read_b128 v[234:237], v197 offset:4608
	s_waitcnt lgkmcnt(4)
	v_mfma_f32_32x32x16_bf16 v[112:127], v[230:233], v[252:255], v[112:127]
	s_waitcnt lgkmcnt(3)
	v_mfma_f32_32x32x16_bf16 v[96:111], v[230:233], v[248:251], v[96:111]
	s_waitcnt lgkmcnt(2)
	v_mfma_f32_32x32x16_bf16 v[80:95], v[230:233], v[244:247], v[80:95]
	s_waitcnt lgkmcnt(1)
	v_mfma_f32_32x32x16_bf16 v[64:79], v[230:233], v[240:243], v[64:79]
	ds_read_b128 v[230:233], v197 offset:32
	s_waitcnt lgkmcnt(1)
	v_mfma_f32_32x32x16_bf16 v[48:63], v[234:237], v[252:255], v[48:63]
	ds_read_b128 v[252:255], v199 offset:18464
	v_mfma_f32_32x32x16_bf16 v[32:47], v[234:237], v[248:251], v[32:47]
	ds_read_b128 v[248:251], v199 offset:23072
	v_mfma_f32_32x32x16_bf16 v[16:31], v[234:237], v[244:247], v[16:31]
	ds_read_b128 v[244:247], v199 offset:27680
	v_mfma_f32_32x32x16_bf16 v[0:15], v[234:237], v[240:243], v[0:15]
	ds_read_b128 v[240:243], v199 offset:32288
	ds_read_b128 v[234:237], v197 offset:4640
	s_waitcnt lgkmcnt(4)
	v_mfma_f32_32x32x16_bf16 v[112:127], v[230:233], v[252:255], v[112:127]
	s_waitcnt lgkmcnt(3)
	v_mfma_f32_32x32x16_bf16 v[96:111], v[230:233], v[248:251], v[96:111]
	s_waitcnt lgkmcnt(2)
	v_mfma_f32_32x32x16_bf16 v[80:95], v[230:233], v[244:247], v[80:95]
	s_waitcnt lgkmcnt(1)
	v_mfma_f32_32x32x16_bf16 v[64:79], v[230:233], v[240:243], v[64:79]
	ds_read_b128 v[230:233], v197 offset:64
	s_waitcnt lgkmcnt(1)
	v_mfma_f32_32x32x16_bf16 v[48:63], v[234:237], v[252:255], v[48:63]
	ds_read_b128 v[252:255], v199 offset:18496
	v_mfma_f32_32x32x16_bf16 v[32:47], v[234:237], v[248:251], v[32:47]
	ds_read_b128 v[248:251], v199 offset:23104
	v_mfma_f32_32x32x16_bf16 v[16:31], v[234:237], v[244:247], v[16:31]
	ds_read_b128 v[244:247], v199 offset:27712
	v_mfma_f32_32x32x16_bf16 v[0:15], v[234:237], v[240:243], v[0:15]
	ds_read_b128 v[240:243], v199 offset:32320
	ds_read_b128 v[234:237], v197 offset:4672
	s_waitcnt lgkmcnt(4)
	v_mfma_f32_32x32x16_bf16 v[112:127], v[230:233], v[252:255], v[112:127]
	s_waitcnt lgkmcnt(3)
	v_mfma_f32_32x32x16_bf16 v[96:111], v[230:233], v[248:251], v[96:111]
	s_waitcnt lgkmcnt(2)
	v_mfma_f32_32x32x16_bf16 v[80:95], v[230:233], v[244:247], v[80:95]
	s_waitcnt lgkmcnt(1)
	v_mfma_f32_32x32x16_bf16 v[64:79], v[230:233], v[240:243], v[64:79]
	ds_read_b128 v[230:233], v197 offset:96
	s_waitcnt lgkmcnt(1)
	v_mfma_f32_32x32x16_bf16 v[48:63], v[234:237], v[252:255], v[48:63]
	ds_read_b128 v[252:255], v199 offset:18528
	v_mfma_f32_32x32x16_bf16 v[32:47], v[234:237], v[248:251], v[32:47]
	ds_read_b128 v[248:251], v199 offset:23136
	v_mfma_f32_32x32x16_bf16 v[16:31], v[234:237], v[244:247], v[16:31]
	ds_read_b128 v[244:247], v199 offset:27744
	v_mfma_f32_32x32x16_bf16 v[0:15], v[234:237], v[240:243], v[0:15]
	ds_read_b128 v[240:243], v199 offset:32352
	ds_read_b128 v[234:237], v197 offset:4704
	s_waitcnt lgkmcnt(4)
	v_mfma_f32_32x32x16_bf16 v[112:127], v[230:233], v[252:255], v[112:127]
	s_waitcnt lgkmcnt(3)
	v_mfma_f32_32x32x16_bf16 v[96:111], v[230:233], v[248:251], v[96:111]
	s_waitcnt lgkmcnt(2)
	v_mfma_f32_32x32x16_bf16 v[80:95], v[230:233], v[244:247], v[80:95]
	s_waitcnt lgkmcnt(1)
	v_mfma_f32_32x32x16_bf16 v[64:79], v[230:233], v[240:243], v[64:79]
	s_waitcnt lgkmcnt(0)
	v_mfma_f32_32x32x16_bf16 v[48:63], v[234:237], v[252:255], v[48:63]
	v_mfma_f32_32x32x16_bf16 v[32:47], v[234:237], v[248:251], v[32:47]
	v_mfma_f32_32x32x16_bf16 v[16:31], v[234:237], v[244:247], v[16:31]
	s_barrier
; DI f32x16 mfma32(bf16x8 a, bf16x8 b, f32x16 c) { return __builtin_amdgcn_mfma_f32_32x32x16_bf16(a, b, c, 0, 0, 0); }
; template <int NT, class Epi>
; DI void gemm_tile(const u16* __restrict__ A, int lda, const u16* __restrict__ Bt, int ldb, int K, int m0, int n0, const Epi& epi, char* smem) {
;     ...
;   for (int kt = 0; kt < nk; ++kt) {
; #pragma unroll
;     for (int i = 0; i < 4; ++i) *(u32x4*)(As + (lrow + 32 * i) * 72 + lch * 8) = ra[i];
; #pragma unroll
;     for (int i = 0; i < NB8; ++i) *(u32x4*)(Bs + (lrow + 32 * i) * 72 + lch * 8) = rb[i];
;     __syncthreads();
;     if (kt + 1 < nk) {
;       const int k0 = (kt + 1) * 64;
; #pragma unroll
;       for (int i = 0; i < 4; ++i) ra[i] = *(const u32x4*)(Ap + (size_t)(32 * i) * lda + k0);
; #pragma unroll
;       for (int i = 0; i < NB8; ++i) rb[i] = *(const u32x4*)(Bp + (size_t)(32 * i) * ldb + k0);
;     }
; #pragma unroll
;     for (int ks = 0; ks < 4; ++ks) {
;       bf16x8 a[2], b[NT];
; #pragma unroll
;       for (int mt = 0; mt < 2; ++mt) a[mt] = *(const bf16x8*)(As + (wm * 64 + mt * 32 + r) * 72 + ks * 16 + h * 8);
; #pragma unroll
;       for (int nt = 0; nt < NT; ++nt) b[nt] = *(const bf16x8*)(Bs + (wn * 32 * NT + nt * 32 + r) * 72 + ks * 16 + h * 8);
; #pragma unroll
;       for (int mt = 0; mt < 2; ++mt)
; #pragma unroll
;         for (int nt = 0; nt < NT; ++nt) acc[mt][nt] = mfma32(a[mt], b[nt], acc[mt][nt]);
;     }
;     __syncthreads();
	v_mfma_f32_32x32x16_bf16 v[0:15], v[234:237], v[240:243], v[0:15]
	s_cbranch_scc1 .LBB0_520
	s_waitcnt vmcnt(11)
	ds_write_b128 v185, v[128:131]
	s_waitcnt vmcnt(10)
	ds_write_b128 v185, v[132:135] offset:4608
	s_waitcnt vmcnt(9)
	ds_write_b128 v185, v[136:139] offset:9216
	s_waitcnt vmcnt(8)
	ds_write_b128 v185, v[140:143] offset:13824
	s_waitcnt vmcnt(7)
	ds_write_b128 v185, v[144:147] offset:18432
	s_waitcnt vmcnt(6)
	ds_write_b128 v185, v[148:151] offset:23040
	s_waitcnt vmcnt(5)
	ds_write_b128 v185, v[152:155] offset:27648
	s_waitcnt vmcnt(4)
	ds_write_b128 v185, v[156:159] offset:32256
	s_waitcnt vmcnt(3)
	ds_write_b128 v185, v[160:163] offset:36864
	s_waitcnt vmcnt(2)
	ds_write_b128 v185, v[164:167] offset:41472
	s_waitcnt vmcnt(1)
	ds_write_b128 v185, v[168:171] offset:46080
	s_waitcnt vmcnt(0)
	ds_write_b128 v185, v[172:175] offset:50688
	s_waitcnt lgkmcnt(0)
	s_barrier
	ds_read_b128 v[128:131], v197
	ds_read_b128 v[132:135], v199 offset:18432
	ds_read_b128 v[136:139], v197 offset:32
	ds_read_b128 v[140:143], v199 offset:18464
	ds_read_b128 v[144:147], v199 offset:23040
	ds_read_b128 v[148:151], v199 offset:23072
	ds_read_b128 v[152:155], v199 offset:27648
	ds_read_b128 v[156:159], v199 offset:27680
	ds_read_b128 v[160:163], v199 offset:32256
	ds_read_b128 v[164:167], v199 offset:32288
	s_waitcnt lgkmcnt(8)
	v_mfma_f32_32x32x16_bf16 v[112:127], v[128:131], v[132:135], v[112:127]
	s_waitcnt lgkmcnt(5)
	v_mfma_f32_32x32x16_bf16 v[96:111], v[128:131], v[144:147], v[96:111]
	s_waitcnt lgkmcnt(3)
	v_mfma_f32_32x32x16_bf16 v[80:95], v[128:131], v[152:155], v[80:95]
	s_waitcnt lgkmcnt(1)
	v_mfma_f32_32x32x16_bf16 v[64:79], v[128:131], v[160:163], v[64:79]
	ds_read_b128 v[128:131], v197 offset:4608
	ds_read_b128 v[168:171], v197 offset:4640
	s_waitcnt lgkmcnt(1)
	v_mfma_f32_32x32x16_bf16 v[48:63], v[128:131], v[132:135], v[48:63]
	v_mfma_f32_32x32x16_bf16 v[32:47], v[128:131], v[144:147], v[32:47]
	v_mfma_f32_32x32x16_bf16 v[16:31], v[128:131], v[152:155], v[16:31]
	v_mfma_f32_32x32x16_bf16 v[0:15], v[128:131], v[160:163], v[0:15]
	v_mfma_f32_32x32x16_bf16 v[112:127], v[136:139], v[140:143], v[112:127]
	v_mfma_f32_32x32x16_bf16 v[96:111], v[136:139], v[148:151], v[96:111]
	v_mfma_f32_32x32x16_bf16 v[80:95], v[136:139], v[156:159], v[80:95]
	v_mfma_f32_32x32x16_bf16 v[64:79], v[136:139], v[164:167], v[64:79]
	s_waitcnt lgkmcnt(0)
	v_mfma_f32_32x32x16_bf16 v[48:63], v[168:171], v[140:143], v[48:63]
	ds_read_b128 v[128:131], v197 offset:64
	ds_read_b128 v[132:135], v199 offset:18496
	ds_read_b128 v[138:141], v197 offset:96
	ds_read_b128 v[142:145], v199 offset:18528
	v_mfma_f32_32x32x16_bf16 v[32:47], v[168:171], v[148:151], v[32:47]
	ds_read_b128 v[146:149], v199 offset:23104
	ds_read_b128 v[160:163], v199 offset:23136
	v_mfma_f32_32x32x16_bf16 v[16:31], v[168:171], v[156:159], v[16:31]
	v_mfma_f32_32x32x16_bf16 v[0:15], v[168:171], v[164:167], v[0:15]
	ds_read_b128 v[150:153], v199 offset:27712
	ds_read_b128 v[164:167], v199 offset:27744
	ds_read_b128 v[154:157], v199 offset:32320
	ds_read_b128 v[170:173], v199 offset:32352
	v_add_u32_e32 v168, s14, v181
	v_or_b32_e32 v169, s15, v179
	v_or_b32_e32 v136, 8, v168
	v_mul_hi_u32_u24_e32 v137, 0xc10, v136
	v_mul_u32_u24_e32 v136, 0xc10, v136
	s_waitcnt lgkmcnt(8)
	v_mfma_f32_32x32x16_bf16 v[112:127], v[128:131], v[132:135], v[112:127]
	v_cmp_gt_u32_e64 s[12:13], s40, v169
	v_lshlrev_b32_e32 v200, 1, v169
	s_waitcnt lgkmcnt(5)
	v_mfma_f32_32x32x16_bf16 v[96:111], v[128:131], v[146:149], v[96:111]
	s_waitcnt lgkmcnt(3)
	v_mfma_f32_32x32x16_bf16 v[80:95], v[128:131], v[150:153], v[80:95]
	s_waitcnt lgkmcnt(1)
	v_mfma_f32_32x32x16_bf16 v[64:79], v[128:131], v[154:157], v[64:79]
	ds_read_b128 v[128:131], v197 offset:4672
	ds_read_b128 v[208:211], v197 offset:4704
	s_waitcnt lgkmcnt(0)
	s_barrier
; DI int crow(int i, int h) { return (i & 3) + 8 * (i >> 2) + 4 * h; }
; DI f32x16 mfma32(bf16x8 a, bf16x8 b, f32x16 c) { return __builtin_amdgcn_mfma_f32_32x32x16_bf16(a, b, c, 0, 0, 0); }
; template <int NT, class Epi>
; DI void gemm_tile(const u16* __restrict__ A, int lda, const u16* __restrict__ Bt, int ldb, int K, int m0, int n0, const Epi& epi, char* smem) {
;     ...
; #pragma unroll
;     for (int ks = 0; ks < 4; ++ks) {
;       bf16x8 a[2], b[NT];
; #pragma unroll
;       for (int mt = 0; mt < 2; ++mt) a[mt] = *(const bf16x8*)(As + (wm * 64 + mt * 32 + r) * 72 + ks * 16 + h * 8);
; #pragma unroll
;       for (int nt = 0; nt < NT; ++nt) b[nt] = *(const bf16x8*)(Bs + (wn * 32 * NT + nt * 32 + r) * 72 + ks * 16 + h * 8);
; #pragma unroll
;       for (int mt = 0; mt < 2; ++mt)
; #pragma unroll
;         for (int nt = 0; nt < NT; ++nt) acc[mt][nt] = mfma32(a[mt], b[nt], acc[mt][nt]);
;     }
;   DI void operator()(const f32x16& acc, int row0, int col0, int lane) const {
;     const int r = lane & 31, h = lane >> 5, col = col0 + r;
;     if (col >= N) return;
; #pragma unroll
;     for (int i = 0; i < 16; ++i) C[(size_t)(row0 + crow(i, h)) * ldc + col] = f2bf(acc[i]);
;   }
	v_mfma_f32_32x32x16_bf16 v[48:63], v[128:131], v[132:135], v[48:63]
	v_or_b32_e32 v132, 2, v168
	v_or_b32_e32 v134, 3, v168
	v_mul_hi_u32_u24_e32 v133, 0xc10, v132
	v_mul_u32_u24_e32 v132, 0xc10, v132
	v_mul_hi_u32_u24_e32 v135, 0xc10, v134
	v_mul_u32_u24_e32 v134, 0xc10, v134
	v_mfma_f32_32x32x16_bf16 v[32:47], v[128:131], v[146:149], v[32:47]
	v_or_b32_e32 v146, 9, v168
	v_or_b32_e32 v148, 10, v168
	v_mul_hi_u32_u24_e32 v147, 0xc10, v146
	v_mul_u32_u24_e32 v146, 0xc10, v146
	v_mul_hi_u32_u24_e32 v149, 0xc10, v148
	v_mul_u32_u24_e32 v148, 0xc10, v148
	v_mfma_f32_32x32x16_bf16 v[16:31], v[128:131], v[150:153], v[16:31]
	v_mfma_f32_32x32x16_bf16 v[0:15], v[128:131], v[154:157], v[0:15]
	v_or_b32_e32 v130, 1, v168
	v_mul_hi_u32_u24_e32 v129, 0xc10, v168
	v_mul_u32_u24_e32 v128, 0xc10, v168
	v_mul_hi_u32_u24_e32 v131, 0xc10, v130
	v_mul_u32_u24_e32 v130, 0xc10, v130
	v_mfma_f32_32x32x16_bf16 v[112:127], v[138:141], v[142:145], v[112:127]
	v_mfma_f32_32x32x16_bf16 v[96:111], v[138:141], v[160:163], v[96:111]
	v_mfma_f32_32x32x16_bf16 v[80:95], v[138:141], v[164:167], v[80:95]
	v_mfma_f32_32x32x16_bf16 v[64:79], v[138:141], v[170:173], v[64:79]
	v_or_b32_e32 v138, 11, v168
	v_mul_hi_u32_u24_e32 v151, 0xc10, v138
	v_mul_u32_u24_e32 v150, 0xc10, v138
	v_or_b32_e32 v138, 16, v168
	v_mul_hi_u32_u24_e32 v153, 0xc10, v138
	v_mul_u32_u24_e32 v152, 0xc10, v138
	v_or_b32_e32 v138, 17, v168
	v_mfma_f32_32x32x16_bf16 v[48:63], v[208:211], v[142:145], v[48:63]
	v_mul_hi_u32_u24_e32 v155, 0xc10, v138
	v_mul_u32_u24_e32 v154, 0xc10, v138
	v_or_b32_e32 v138, 18, v168
	v_mul_hi_u32_u24_e32 v157, 0xc10, v138
	v_mul_u32_u24_e32 v156, 0xc10, v138
	v_or_b32_e32 v138, 19, v168
	v_mul_hi_u32_u24_e32 v159, 0xc10, v138
	v_mfma_f32_32x32x16_bf16 v[32:47], v[208:211], v[160:163], v[32:47]
	v_mul_u32_u24_e32 v158, 0xc10, v138
	v_or_b32_e32 v138, 24, v168
	v_mul_hi_u32_u24_e32 v161, 0xc10, v138
	v_mul_u32_u24_e32 v160, 0xc10, v138
	v_or_b32_e32 v138, 25, v168
	v_mul_hi_u32_u24_e32 v163, 0xc10, v138
	v_mul_u32_u24_e32 v162, 0xc10, v138
	v_mfma_f32_32x32x16_bf16 v[16:31], v[208:211], v[164:167], v[16:31]
	v_or_b32_e32 v138, 26, v168
	v_mul_hi_u32_u24_e32 v165, 0xc10, v138
	v_mul_u32_u24_e32 v164, 0xc10, v138
	v_or_b32_e32 v138, 27, v168
	v_mul_hi_u32_u24_e32 v167, 0xc10, v138
	v_mul_u32_u24_e32 v166, 0xc10, v138
	v_mfma_f32_32x32x16_bf16 v[0:15], v[208:211], v[170:173], v[0:15]
	s_and_saveexec_b64 s[14:15], s[12:13]
	s_cbranch_execz .LBB0_523
	v_lshl_add_u64 v[138:139], s[52:53], 0, v[200:201]
	v_cvt_pk_bf16_f32 v112, v112, s0
	v_lshl_add_u64 v[140:141], v[128:129], 1, v[138:139]
	global_store_short v[140:141], v112, off
	v_cvt_pk_bf16_f32 v140, v113, s0
	v_lshl_add_u64 v[112:113], v[130:131], 1, v[138:139]
	global_store_short v[112:113], v140, off
	v_cvt_pk_bf16_f32 v114, v114, s0
	v_lshl_add_u64 v[112:113], v[132:133], 1, v[138:139]
	global_store_short v[112:113], v114, off
	v_cvt_pk_bf16_f32 v114, v115, s0
	v_lshl_add_u64 v[112:113], v[134:135], 1, v[138:139]
	global_store_short v[112:113], v114, off
	v_cvt_pk_bf16_f32 v114, v116, s0
	v_lshl_add_u64 v[112:113], v[136:137], 1, v[138:139]
	global_store_short v[112:113], v114, off
	v_cvt_pk_bf16_f32 v114, v117, s0
	v_lshl_add_u64 v[112:113], v[146:147], 1, v[138:139]
	global_store_short v[112:113], v114, off
	v_cvt_pk_bf16_f32 v114, v118, s0
	v_lshl_add_u64 v[112:113], v[148:149], 1, v[138:139]
	global_store_short v[112:113], v114, off
	v_cvt_pk_bf16_f32 v114, v119, s0
	v_lshl_add_u64 v[112:113], v[150:151], 1, v[138:139]
	global_store_short v[112:113], v114, off
	v_cvt_pk_bf16_f32 v114, v120, s0
	v_lshl_add_u64 v[112:113], v[152:153], 1, v[138:139]
	global_store_short v[112:113], v114, off
	v_cvt_pk_bf16_f32 v114, v121, s0
	v_lshl_add_u64 v[112:113], v[154:155], 1, v[138:139]
	global_store_short v[112:113], v114, off
	v_cvt_pk_bf16_f32 v114, v122, s0
	v_lshl_add_u64 v[112:113], v[156:157], 1, v[138:139]
	global_store_short v[112:113], v114, off
	v_cvt_pk_bf16_f32 v114, v123, s0
	v_lshl_add_u64 v[112:113], v[158:159], 1, v[138:139]
	global_store_short v[112:113], v114, off
	v_cvt_pk_bf16_f32 v114, v124, s0
	v_lshl_add_u64 v[112:113], v[160:161], 1, v[138:139]
	global_store_short v[112:113], v114, off
	v_cvt_pk_bf16_f32 v114, v125, s0
	v_lshl_add_u64 v[112:113], v[162:163], 1, v[138:139]
	global_store_short v[112:113], v114, off
	v_cvt_pk_bf16_f32 v114, v126, s0
	v_lshl_add_u64 v[112:113], v[164:165], 1, v[138:139]
	global_store_short v[112:113], v114, off
	v_cvt_pk_bf16_f32 v114, v127, s0
	v_lshl_add_u64 v[112:113], v[166:167], 1, v[138:139]
	global_store_short v[112:113], v114, off

; DI f32x16 mfma32(bf16x8 a, bf16x8 b, f32x16 c) { return __builtin_amdgcn_mfma_f32_32x32x16_bf16(a, b, c, 0, 0, 0); }
; template <int NT, class Epi>
; DI void gemm_tile(const u16* __restrict__ A, int lda, const u16* __restrict__ Bt, int ldb, int K, int m0, int n0, const Epi& epi, char* smem) {
;     ...
;   for (int kt = 0; kt < nk; ++kt) {
; #pragma unroll
;     for (int i = 0; i < 4; ++i) *(u32x4*)(As + (lrow + 32 * i) * 72 + lch * 8) = ra[i];
; #pragma unroll
;     for (int i = 0; i < NB8; ++i) *(u32x4*)(Bs + (lrow + 32 * i) * 72 + lch * 8) = rb[i];
;     __syncthreads();
;     if (kt + 1 < nk) {
;       const int k0 = (kt + 1) * 64;
; #pragma unroll
;       for (int i = 0; i < 4; ++i) ra[i] = *(const u32x4*)(Ap + (size_t)(32 * i) * lda + k0);
; #pragma unroll
;       for (int i = 0; i < NB8; ++i) rb[i] = *(const u32x4*)(Bp + (size_t)(32 * i) * ldb + k0);
;     }
; #pragma unroll
;     for (int ks = 0; ks < 4; ++ks) {
;       bf16x8 a[2], b[NT];
; #pragma unroll
;       for (int mt = 0; mt < 2; ++mt) a[mt] = *(const bf16x8*)(As + (wm * 64 + mt * 32 + r) * 72 + ks * 16 + h * 8);
; #pragma unroll
;       for (int nt = 0; nt < NT; ++nt) b[nt] = *(const bf16x8*)(Bs + (wn * 32 * NT + nt * 32 + r) * 72 + ks * 16 + h * 8);
; #pragma unroll
;       for (int mt = 0; mt < 2; ++mt)
; #pragma unroll
;         for (int nt = 0; nt < NT; ++nt) acc[mt][nt] = mfma32(a[mt], b[nt], acc[mt][nt]);
;     }
;     __syncthreads();
;   }
.LBB0_643:
	s_waitcnt vmcnt(11)
	ds_write_b128 v197, v[128:131]
	s_waitcnt vmcnt(10)
	ds_write_b128 v197, v[132:135] offset:4608
	s_waitcnt vmcnt(9)
	ds_write_b128 v197, v[136:139] offset:9216
	s_waitcnt vmcnt(8)
	ds_write_b128 v197, v[140:143] offset:13824
	s_waitcnt vmcnt(7)
	ds_write_b128 v197, v[144:147] offset:18432
	s_waitcnt vmcnt(6)
	ds_write_b128 v197, v[148:151] offset:23040
	s_waitcnt vmcnt(5)
	ds_write_b128 v197, v[152:155] offset:27648
	s_waitcnt vmcnt(4)
	ds_write_b128 v197, v[156:159] offset:32256
	s_waitcnt vmcnt(3)
	ds_write_b128 v197, v[160:163] offset:36864
	s_waitcnt vmcnt(2)
	ds_write_b128 v197, v[164:167] offset:41472
	s_waitcnt vmcnt(1)
	ds_write_b128 v197, v[168:171] offset:46080
	s_waitcnt vmcnt(0)
	ds_write_b128 v197, v[172:175] offset:50688
	s_waitcnt lgkmcnt(0)
	s_barrier
	s_add_u32 s92, s20, s28
	s_addc_u32 s93, s21, 0
	v_lshl_add_u64 v[238:239], v[202:203], 0, s[92:93]
	global_load_dwordx4 v[128:131], v[238:239], off offset:128
	s_add_u32 s92, s20, s29
	s_addc_u32 s93, s21, 0
	v_lshl_add_u64 v[238:239], v[202:203], 0, s[92:93]
	global_load_dwordx4 v[132:135], v[238:239], off offset:128
	s_add_u32 s92, s20, s30
	s_addc_u32 s93, s21, 0
	v_lshl_add_u64 v[238:239], v[202:203], 0, s[92:93]
	global_load_dwordx4 v[136:139], v[238:239], off offset:128
	s_add_u32 s92, s20, s31
	s_addc_u32 s93, s21, 0
	v_lshl_add_u64 v[238:239], v[202:203], 0, s[92:93]
	global_load_dwordx4 v[140:143], v[238:239], off offset:128
	s_add_u32 s92, s20, s34
	s_addc_u32 s93, s21, 0
	v_lshl_add_u64 v[238:239], v[204:205], 0, s[92:93]
	global_load_dwordx4 v[144:147], v[238:239], off offset:128
	s_add_u32 s92, s20, s35
	s_addc_u32 s93, s21, 0
	v_lshl_add_u64 v[238:239], v[204:205], 0, s[92:93]
	global_load_dwordx4 v[148:151], v[238:239], off offset:128
	s_add_u32 s92, s20, s36
	s_addc_u32 s93, s21, 0
	v_lshl_add_u64 v[238:239], v[204:205], 0, s[92:93]
	global_load_dwordx4 v[152:155], v[238:239], off offset:128
	s_add_u32 s92, s20, s37
	s_addc_u32 s93, s21, 0
	v_lshl_add_u64 v[238:239], v[204:205], 0, s[92:93]
	global_load_dwordx4 v[156:159], v[238:239], off offset:128
	s_add_u32 s92, s20, s38
	s_addc_u32 s93, s21, 0
	v_lshl_add_u64 v[238:239], v[204:205], 0, s[92:93]
	global_load_dwordx4 v[160:163], v[238:239], off offset:128
	s_add_u32 s92, s20, s39
	s_addc_u32 s93, s21, 0
	v_lshl_add_u64 v[238:239], v[204:205], 0, s[92:93]
	global_load_dwordx4 v[164:167], v[238:239], off offset:128
	s_add_u32 s92, s20, s40
	s_addc_u32 s93, s21, 0
	v_lshl_add_u64 v[238:239], v[204:205], 0, s[92:93]
	global_load_dwordx4 v[168:171], v[238:239], off offset:128
	s_add_u32 s92, s20, s41
	s_addc_u32 s93, s21, 0
	v_lshl_add_u64 v[238:239], v[204:205], 0, s[92:93]
	global_load_dwordx4 v[172:175], v[238:239], off offset:128
	s_add_u32 s20, s20, 0x80
	s_addc_u32 s21, s21, 0
	s_cmpk_lg_i32 s20, 0x780
	ds_read_b128 v[208:211], v199
	ds_read_b128 v[252:255], v206 offset:18432
	ds_read_b128 v[248:251], v206 offset:23040
	ds_read_b128 v[244:247], v206 offset:27648
	ds_read_b128 v[240:243], v206 offset:32256
	ds_read_b128 v[230:233], v199 offset:4608
	s_waitcnt lgkmcnt(4)
	v_mfma_f32_32x32x16_bf16 v[112:127], v[208:211], v[252:255], v[112:127]
	s_waitcnt lgkmcnt(3)
	v_mfma_f32_32x32x16_bf16 v[96:111], v[208:211], v[248:251], v[96:111]
	s_waitcnt lgkmcnt(2)
	v_mfma_f32_32x32x16_bf16 v[80:95], v[208:211], v[244:247], v[80:95]
	s_waitcnt lgkmcnt(1)
	v_mfma_f32_32x32x16_bf16 v[64:79], v[208:211], v[240:243], v[64:79]
	ds_read_b128 v[208:211], v199 offset:32
	s_waitcnt lgkmcnt(1)
	v_mfma_f32_32x32x16_bf16 v[48:63], v[230:233], v[252:255], v[48:63]
	ds_read_b128 v[252:255], v206 offset:18464
	v_mfma_f32_32x32x16_bf16 v[32:47], v[230:233], v[248:251], v[32:47]
	ds_read_b128 v[248:251], v206 offset:23072
	v_mfma_f32_32x32x16_bf16 v[16:31], v[230:233], v[244:247], v[16:31]
	ds_read_b128 v[244:247], v206 offset:27680
	v_mfma_f32_32x32x16_bf16 v[0:15], v[230:233], v[240:243], v[0:15]
	ds_read_b128 v[240:243], v206 offset:32288
	ds_read_b128 v[230:233], v199 offset:4640
	s_waitcnt lgkmcnt(4)
	v_mfma_f32_32x32x16_bf16 v[112:127], v[208:211], v[252:255], v[112:127]
	s_waitcnt lgkmcnt(3)
	v_mfma_f32_32x32x16_bf16 v[96:111], v[208:211], v[248:251], v[96:111]
	s_waitcnt lgkmcnt(2)
	v_mfma_f32_32x32x16_bf16 v[80:95], v[208:211], v[244:247], v[80:95]
	s_waitcnt lgkmcnt(1)
	v_mfma_f32_32x32x16_bf16 v[64:79], v[208:211], v[240:243], v[64:79]
	ds_read_b128 v[208:211], v199 offset:64
	s_waitcnt lgkmcnt(1)
	v_mfma_f32_32x32x16_bf16 v[48:63], v[230:233], v[252:255], v[48:63]
	ds_read_b128 v[252:255], v206 offset:18496
	v_mfma_f32_32x32x16_bf16 v[32:47], v[230:233], v[248:251], v[32:47]
	ds_read_b128 v[248:251], v206 offset:23104
	v_mfma_f32_32x32x16_bf16 v[16:31], v[230:233], v[244:247], v[16:31]
	ds_read_b128 v[244:247], v206 offset:27712
	v_mfma_f32_32x32x16_bf16 v[0:15], v[230:233], v[240:243], v[0:15]
	ds_read_b128 v[240:243], v206 offset:32320
	ds_read_b128 v[230:233], v199 offset:4672
	s_waitcnt lgkmcnt(4)
	v_mfma_f32_32x32x16_bf16 v[112:127], v[208:211], v[252:255], v[112:127]
	s_waitcnt lgkmcnt(3)
	v_mfma_f32_32x32x16_bf16 v[96:111], v[208:211], v[248:251], v[96:111]
	s_waitcnt lgkmcnt(2)
	v_mfma_f32_32x32x16_bf16 v[80:95], v[208:211], v[244:247], v[80:95]
	s_waitcnt lgkmcnt(1)
	v_mfma_f32_32x32x16_bf16 v[64:79], v[208:211], v[240:243], v[64:79]
	ds_read_b128 v[208:211], v199 offset:96
	s_waitcnt lgkmcnt(1)
	v_mfma_f32_32x32x16_bf16 v[48:63], v[230:233], v[252:255], v[48:63]
	ds_read_b128 v[252:255], v206 offset:18528
	v_mfma_f32_32x32x16_bf16 v[32:47], v[230:233], v[248:251], v[32:47]
	ds_read_b128 v[248:251], v206 offset:23136
	v_mfma_f32_32x32x16_bf16 v[16:31], v[230:233], v[244:247], v[16:31]
	ds_read_b128 v[244:247], v206 offset:27744
	v_mfma_f32_32x32x16_bf16 v[0:15], v[230:233], v[240:243], v[0:15]
	ds_read_b128 v[240:243], v206 offset:32352
	ds_read_b128 v[230:233], v199 offset:4704
	s_waitcnt lgkmcnt(4)
	v_mfma_f32_32x32x16_bf16 v[112:127], v[208:211], v[252:255], v[112:127]
	s_waitcnt lgkmcnt(3)
	v_mfma_f32_32x32x16_bf16 v[96:111], v[208:211], v[248:251], v[96:111]
	s_waitcnt lgkmcnt(2)
	v_mfma_f32_32x32x16_bf16 v[80:95], v[208:211], v[244:247], v[80:95]
	s_waitcnt lgkmcnt(1)
	v_mfma_f32_32x32x16_bf16 v[64:79], v[208:211], v[240:243], v[64:79]
	s_waitcnt lgkmcnt(0)
	v_mfma_f32_32x32x16_bf16 v[48:63], v[230:233], v[252:255], v[48:63]
	v_mfma_f32_32x32x16_bf16 v[32:47], v[230:233], v[248:251], v[32:47]
	v_mfma_f32_32x32x16_bf16 v[16:31], v[230:233], v[244:247], v[16:31]
	s_barrier
; DI int crow(int i, int h) { return (i & 3) + 8 * (i >> 2) + 4 * h; }
; DI f32x16 mfma32(bf16x8 a, bf16x8 b, f32x16 c) { return __builtin_amdgcn_mfma_f32_32x32x16_bf16(a, b, c, 0, 0, 0); }
; template <int NT, class Epi>
; DI void gemm_tile(const u16* __restrict__ A, int lda, const u16* __restrict__ Bt, int ldb, int K, int m0, int n0, const Epi& epi, char* smem) {
;     ...
;   for (int kt = 0; kt < nk; ++kt) {
; #pragma unroll
;     for (int i = 0; i < 4; ++i) *(u32x4*)(As + (lrow + 32 * i) * 72 + lch * 8) = ra[i];
; #pragma unroll
;     for (int i = 0; i < NB8; ++i) *(u32x4*)(Bs + (lrow + 32 * i) * 72 + lch * 8) = rb[i];
;     __syncthreads();
;     if (kt + 1 < nk) {
;       const int k0 = (kt + 1) * 64;
; #pragma unroll
;       for (int i = 0; i < 4; ++i) ra[i] = *(const u32x4*)(Ap + (size_t)(32 * i) * lda + k0);
; #pragma unroll
;       for (int i = 0; i < NB8; ++i) rb[i] = *(const u32x4*)(Bp + (size_t)(32 * i) * ldb + k0);
;     }
; #pragma unroll
;     for (int ks = 0; ks < 4; ++ks) {
;       bf16x8 a[2], b[NT];
; #pragma unroll
;       for (int mt = 0; mt < 2; ++mt) a[mt] = *(const bf16x8*)(As + (wm * 64 + mt * 32 + r) * 72 + ks * 16 + h * 8);
; #pragma unroll
;       for (int nt = 0; nt < NT; ++nt) b[nt] = *(const bf16x8*)(Bs + (wn * 32 * NT + nt * 32 + r) * 72 + ks * 16 + h * 8);
; #pragma unroll
;       for (int mt = 0; mt < 2; ++mt)
; #pragma unroll
;         for (int nt = 0; nt < NT; ++nt) acc[mt][nt] = mfma32(a[mt], b[nt], acc[mt][nt]);
;     }
;     __syncthreads();
;   DI void operator()(const f32x16& acc, int row0, int col0, int lane) const {
;     const int r = lane & 31, h = lane >> 5, col = col0 + r;
; #pragma unroll
;     for (int i = 0; i < 16; ++i) { float* q = H + (size_t)(row0 + crow(i, h)) * DM + col; *q = *q + acc[i]; }
;   }
	v_mfma_f32_32x32x16_bf16 v[0:15], v[230:233], v[240:243], v[0:15]
	s_cbranch_scc1 .LBB0_643
	s_waitcnt vmcnt(11)
	ds_write_b128 v197, v[128:131]
	s_waitcnt vmcnt(10)
	ds_write_b128 v197, v[132:135] offset:4608
	s_waitcnt vmcnt(9)
	ds_write_b128 v197, v[136:139] offset:9216
	s_waitcnt vmcnt(8)
	ds_write_b128 v197, v[140:143] offset:13824
	s_waitcnt vmcnt(7)
	ds_write_b128 v197, v[144:147] offset:18432
	s_waitcnt vmcnt(6)
	ds_write_b128 v197, v[148:151] offset:23040
	s_waitcnt vmcnt(5)
	ds_write_b128 v197, v[152:155] offset:27648
	s_waitcnt vmcnt(4)
	ds_write_b128 v197, v[156:159] offset:32256
	s_waitcnt vmcnt(3)
	ds_write_b128 v197, v[160:163] offset:36864
	s_waitcnt vmcnt(2)
	ds_write_b128 v197, v[164:167] offset:41472
	s_waitcnt vmcnt(1)
	ds_write_b128 v197, v[168:171] offset:46080
	s_waitcnt vmcnt(0)
	ds_write_b128 v197, v[172:175] offset:50688
	s_waitcnt lgkmcnt(0)
	s_barrier
	ds_read_b128 v[128:131], v199 offset:4608
	ds_read_b128 v[132:135], v206 offset:23040
	ds_read_b128 v[136:139], v206 offset:27648
	ds_read_b128 v[140:143], v206 offset:32256
	ds_read_b128 v[144:147], v199
	ds_read_b128 v[148:151], v199 offset:32
	ds_read_b128 v[152:155], v206 offset:18432
	ds_read_b128 v[156:159], v206 offset:18464
	s_waitcnt lgkmcnt(1)
	v_mfma_f32_32x32x16_bf16 v[112:127], v[144:147], v[152:155], v[112:127]
	v_add_lshl_u32 v188, v181, s43, 12
	s_add_i32 s42, s42, s78
	s_add_i32 s22, s22, s23
	s_cmpk_lt_u32 s42, 0x100
	v_mfma_f32_32x32x16_bf16 v[96:111], v[144:147], v[132:135], v[96:111]
	v_mfma_f32_32x32x16_bf16 v[80:95], v[144:147], v[136:139], v[80:95]
	v_mfma_f32_32x32x16_bf16 v[64:79], v[144:147], v[140:143], v[64:79]
	v_mfma_f32_32x32x16_bf16 v[48:63], v[128:131], v[152:155], v[48:63]
	v_or_b32_e32 v154, 0x3000, v188
	v_mov_b32_e32 v155, v189
	v_or_b32_e32 v152, 0x8000, v188
	v_mov_b32_e32 v153, v189
	v_mfma_f32_32x32x16_bf16 v[32:47], v[128:131], v[132:135], v[32:47]
	v_mfma_f32_32x32x16_bf16 v[16:31], v[128:131], v[136:139], v[16:31]
	v_mfma_f32_32x32x16_bf16 v[0:15], v[128:131], v[140:143], v[0:15]
	ds_read_b128 v[128:131], v199 offset:4640
	ds_read_b128 v[132:135], v206 offset:23072
	ds_read_b128 v[136:139], v206 offset:27680
	ds_read_b128 v[140:143], v206 offset:32288
	s_waitcnt lgkmcnt(4)
	v_mfma_f32_32x32x16_bf16 v[112:127], v[148:151], v[156:159], v[112:127]
	s_waitcnt lgkmcnt(2)
	v_mfma_f32_32x32x16_bf16 v[96:111], v[148:151], v[132:135], v[96:111]
	s_waitcnt lgkmcnt(1)
	v_mfma_f32_32x32x16_bf16 v[80:95], v[148:151], v[136:139], v[80:95]
	s_waitcnt lgkmcnt(0)
	v_mfma_f32_32x32x16_bf16 v[64:79], v[148:151], v[140:143], v[64:79]
	v_mfma_f32_32x32x16_bf16 v[48:63], v[128:131], v[156:159], v[48:63]
	v_or_b32_e32 v158, 0x1000, v188
	v_mov_b32_e32 v159, v189
	v_or_b32_e32 v156, 0x2000, v188
	v_mov_b32_e32 v157, v189
	v_mfma_f32_32x32x16_bf16 v[32:47], v[128:131], v[132:135], v[32:47]
	v_mfma_f32_32x32x16_bf16 v[16:31], v[128:131], v[136:139], v[16:31]
	v_mfma_f32_32x32x16_bf16 v[0:15], v[128:131], v[140:143], v[0:15]
	ds_read_b128 v[128:131], v199 offset:64
	ds_read_b128 v[132:135], v199 offset:4672
	ds_read_b128 v[136:139], v206 offset:18496
	ds_read_b128 v[140:143], v206 offset:23104
	ds_read_b128 v[144:147], v206 offset:27712
	ds_read_b128 v[148:151], v206 offset:32320
	s_waitcnt lgkmcnt(3)
	v_mfma_f32_32x32x16_bf16 v[112:127], v[128:131], v[136:139], v[112:127]
	s_waitcnt lgkmcnt(2)
	v_mfma_f32_32x32x16_bf16 v[96:111], v[128:131], v[140:143], v[96:111]
	s_waitcnt lgkmcnt(1)
	v_mfma_f32_32x32x16_bf16 v[80:95], v[128:131], v[144:147], v[80:95]
	s_waitcnt lgkmcnt(0)
	v_mfma_f32_32x32x16_bf16 v[64:79], v[128:131], v[148:151], v[64:79]
	v_mfma_f32_32x32x16_bf16 v[48:63], v[132:135], v[136:139], v[48:63]
	v_mfma_f32_32x32x16_bf16 v[32:47], v[132:135], v[140:143], v[32:47]
	v_mfma_f32_32x32x16_bf16 v[16:31], v[132:135], v[144:147], v[16:31]
	v_mfma_f32_32x32x16_bf16 v[0:15], v[132:135], v[148:151], v[0:15]
	ds_read_b128 v[128:131], v199 offset:96
	ds_read_b128 v[132:135], v199 offset:4704
	ds_read_b128 v[136:139], v206 offset:18528
	ds_read_b128 v[140:143], v206 offset:23136
	ds_read_b128 v[144:147], v206 offset:27744
	ds_read_b128 v[148:151], v206 offset:32352
	s_waitcnt lgkmcnt(0)
	s_barrier
	v_mfma_f32_32x32x16_bf16 v[112:127], v[128:131], v[136:139], v[112:127]
	v_mfma_f32_32x32x16_bf16 v[96:111], v[128:131], v[140:143], v[96:111]
	v_mfma_f32_32x32x16_bf16 v[80:95], v[128:131], v[144:147], v[80:95]
	v_mfma_f32_32x32x16_bf16 v[64:79], v[128:131], v[148:151], v[64:79]
	v_mfma_f32_32x32x16_bf16 v[0:15], v[132:135], v[148:151], v[0:15]
	v_mfma_f32_32x32x16_bf16 v[16:31], v[132:135], v[144:147], v[16:31]
	v_mfma_f32_32x32x16_bf16 v[32:47], v[132:135], v[140:143], v[32:47]
	v_mfma_f32_32x32x16_bf16 v[48:63], v[132:135], v[136:139], v[48:63]
	s_cselect_b32 s91, 1, 0
	v_or_b32_e32 v239, s44, v179
	v_lshlrev_b32_e32 v239, 2, v239
	v_add_u32_e32 v239, v239, v188
	s_add_u32 s92, s68, 0x0
	s_addc_u32 s93, s69, 0
	global_load_dword v128, v239, s[92:93]
	s_add_u32 s92, s68, 0x1000
	s_addc_u32 s93, s69, 0
	global_load_dword v129, v239, s[92:93]
	s_add_u32 s92, s68, 0x2000
	s_addc_u32 s93, s69, 0
	global_load_dword v130, v239, s[92:93]
	s_add_u32 s92, s68, 0x3000
	s_addc_u32 s93, s69, 0
	global_load_dword v131, v239, s[92:93]
	s_add_u32 s92, s68, 0x8000
	s_addc_u32 s93, s69, 0
	global_load_dword v132, v239, s[92:93]
	s_add_u32 s92, s68, 0x9000
	s_addc_u32 s93, s69, 0
	global_load_dword v133, v239, s[92:93]
	s_add_u32 s92, s68, 0xa000
	s_addc_u32 s93, s69, 0
	global_load_dword v134, v239, s[92:93]
	s_add_u32 s92, s68, 0xb000
	s_addc_u32 s93, s69, 0
	global_load_dword v135, v239, s[92:93]
	s_add_u32 s92, s68, 0x10000
	s_addc_u32 s93, s69, 0
; DI int crow(int i, int h) { return (i & 3) + 8 * (i >> 2) + 4 * h; }
; template <int NT, class Epi>
; DI void gemm_tile(const u16* __restrict__ A, int lda, const u16* __restrict__ Bt, int ldb, int K, int m0, int n0, const Epi& epi, char* smem) {
;     ...
; #pragma unroll
;   for (int mt = 0; mt < 2; ++mt)
; #pragma unroll
;     for (int nt = 0; nt < NT; ++nt) epi(acc[mt][nt], m0 + wm * 64 + mt * 32, n0 + wn * 32 * NT + nt * 32, lane);
;   DI void operator()(const f32x16& acc, int row0, int col0, int lane) const {
;     const int r = lane & 31, h = lane >> 5, col = col0 + r;
; #pragma unroll
;     for (int i = 0; i < 16; ++i) { float* q = H + (size_t)(row0 + crow(i, h)) * DM + col; *q = *q + acc[i]; }
;   }
	global_load_dword v136, v239, s[92:93]
	s_add_u32 s92, s68, 0x11000
	s_addc_u32 s93, s69, 0
	global_load_dword v137, v239, s[92:93]
	s_add_u32 s92, s68, 0x12000
	s_addc_u32 s93, s69, 0
	global_load_dword v138, v239, s[92:93]
	s_add_u32 s92, s68, 0x13000
	s_addc_u32 s93, s69, 0
	global_load_dword v139, v239, s[92:93]
	s_add_u32 s92, s68, 0x18000
	s_addc_u32 s93, s69, 0
	global_load_dword v140, v239, s[92:93]
	s_add_u32 s92, s68, 0x19000
	s_addc_u32 s93, s69, 0
	global_load_dword v141, v239, s[92:93]
	s_add_u32 s92, s68, 0x1a000
	s_addc_u32 s93, s69, 0
	global_load_dword v142, v239, s[92:93]
	s_add_u32 s92, s68, 0x1b000
	s_addc_u32 s93, s69, 0
	global_load_dword v143, v239, s[92:93]
	s_add_u32 s92, s68, 0x80
	s_addc_u32 s93, s69, 0
	global_load_dword v240, v239, s[92:93]
	s_add_u32 s92, s68, 0x1080
	s_addc_u32 s93, s69, 0
	global_load_dword v241, v239, s[92:93]
	s_add_u32 s92, s68, 0x2080
	s_addc_u32 s93, s69, 0
	global_load_dword v242, v239, s[92:93]
	s_add_u32 s92, s68, 0x3080
	s_addc_u32 s93, s69, 0
	global_load_dword v243, v239, s[92:93]
	s_add_u32 s92, s68, 0x8080
	s_addc_u32 s93, s69, 0
	global_load_dword v244, v239, s[92:93]
	s_add_u32 s92, s68, 0x9080
	s_addc_u32 s93, s69, 0
	global_load_dword v245, v239, s[92:93]
	s_add_u32 s92, s68, 0xa080
	s_addc_u32 s93, s69, 0
	global_load_dword v246, v239, s[92:93]
	s_add_u32 s92, s68, 0xb080
	s_addc_u32 s93, s69, 0
	global_load_dword v247, v239, s[92:93]
	s_add_u32 s92, s68, 0x10080
	s_addc_u32 s93, s69, 0
	global_load_dword v248, v239, s[92:93]
	s_add_u32 s92, s68, 0x11080
	s_addc_u32 s93, s69, 0
	global_load_dword v249, v239, s[92:93]
	s_add_u32 s92, s68, 0x12080
	s_addc_u32 s93, s69, 0
	global_load_dword v250, v239, s[92:93]
	s_add_u32 s92, s68, 0x13080
	s_addc_u32 s93, s69, 0
	global_load_dword v251, v239, s[92:93]
	s_add_u32 s92, s68, 0x18080
	s_addc_u32 s93, s69, 0
	global_load_dword v252, v239, s[92:93]
	s_add_u32 s92, s68, 0x19080
	s_addc_u32 s93, s69, 0
	global_load_dword v253, v239, s[92:93]
	s_add_u32 s92, s68, 0x1a080
	s_addc_u32 s93, s69, 0
	global_load_dword v254, v239, s[92:93]
	s_add_u32 s92, s68, 0x1b080
	s_addc_u32 s93, s69, 0
	global_load_dword v255, v239, s[92:93]
	s_waitcnt vmcnt(16)
	v_add_f32_e32 v112, v112, v128
	v_add_f32_e32 v113, v113, v129
	v_add_f32_e32 v114, v114, v130
	v_add_f32_e32 v115, v115, v131
	v_add_f32_e32 v116, v116, v132
	v_add_f32_e32 v117, v117, v133
	v_add_f32_e32 v118, v118, v134
	v_add_f32_e32 v119, v119, v135
	v_add_f32_e32 v120, v120, v136
	v_add_f32_e32 v121, v121, v137
	v_add_f32_e32 v122, v122, v138
	v_add_f32_e32 v123, v123, v139
	v_add_f32_e32 v124, v124, v140
	v_add_f32_e32 v125, v125, v141
	v_add_f32_e32 v126, v126, v142
	v_add_f32_e32 v127, v127, v143
	s_add_u32 s92, s68, 0x0
	s_addc_u32 s93, s69, 0
	global_store_dword v239, v112, s[92:93]
	s_add_u32 s92, s68, 0x1000
	s_addc_u32 s93, s69, 0
	global_store_dword v239, v113, s[92:93]
	s_add_u32 s92, s68, 0x2000
	s_addc_u32 s93, s69, 0
	global_store_dword v239, v114, s[92:93]
	s_add_u32 s92, s68, 0x3000
	s_addc_u32 s93, s69, 0
	global_store_dword v239, v115, s[92:93]
	s_add_u32 s92, s68, 0x8000
	s_addc_u32 s93, s69, 0
	global_store_dword v239, v116, s[92:93]
	s_add_u32 s92, s68, 0x9000
	s_addc_u32 s93, s69, 0
	global_store_dword v239, v117, s[92:93]
	s_add_u32 s92, s68, 0xa000
	s_addc_u32 s93, s69, 0
	global_store_dword v239, v118, s[92:93]
	s_add_u32 s92, s68, 0xb000
	s_addc_u32 s93, s69, 0
	global_store_dword v239, v119, s[92:93]
	s_add_u32 s92, s68, 0x10000
	s_addc_u32 s93, s69, 0
	global_store_dword v239, v120, s[92:93]
	s_add_u32 s92, s68, 0x11000
	s_addc_u32 s93, s69, 0
	global_store_dword v239, v121, s[92:93]
	s_add_u32 s92, s68, 0x12000
	s_addc_u32 s93, s69, 0
	global_store_dword v239, v122, s[92:93]
	s_add_u32 s92, s68, 0x13000
	s_addc_u32 s93, s69, 0
	global_store_dword v239, v123, s[92:93]
	s_add_u32 s92, s68, 0x18000
	s_addc_u32 s93, s69, 0
	global_store_dword v239, v124, s[92:93]
	s_add_u32 s92, s68, 0x19000
	s_addc_u32 s93, s69, 0
	global_store_dword v239, v125, s[92:93]
	s_add_u32 s92, s68, 0x1a000
	s_addc_u32 s93, s69, 0
	global_store_dword v239, v126, s[92:93]
	s_add_u32 s92, s68, 0x1b000
	s_addc_u32 s93, s69, 0
	global_store_dword v239, v127, s[92:93]
	s_add_u32 s92, s68, 0x100
	s_addc_u32 s93, s69, 0
	global_load_dword v128, v239, s[92:93]
	s_add_u32 s92, s68, 0x1100
	s_addc_u32 s93, s69, 0
	global_load_dword v129, v239, s[92:93]
	s_add_u32 s92, s68, 0x2100
	s_addc_u32 s93, s69, 0
	global_load_dword v130, v239, s[92:93]
	s_add_u32 s92, s68, 0x3100
	s_addc_u32 s93, s69, 0
	global_load_dword v131, v239, s[92:93]
	s_add_u32 s92, s68, 0x8100
	s_addc_u32 s93, s69, 0
	global_load_dword v132, v239, s[92:93]
	s_add_u32 s92, s68, 0x9100
	s_addc_u32 s93, s69, 0
	global_load_dword v133, v239, s[92:93]
	s_add_u32 s92, s68, 0xa100
	s_addc_u32 s93, s69, 0
	global_load_dword v134, v239, s[92:93]
	s_add_u32 s92, s68, 0xb100
	s_addc_u32 s93, s69, 0
	global_load_dword v135, v239, s[92:93]
	s_add_u32 s92, s68, 0x10100
	s_addc_u32 s93, s69, 0
	global_load_dword v136, v239, s[92:93]
	s_add_u32 s92, s68, 0x11100
	s_addc_u32 s93, s69, 0
	global_load_dword v137, v239, s[92:93]
	s_add_u32 s92, s68, 0x12100
	s_addc_u32 s93, s69, 0
	global_load_dword v138, v239, s[92:93]
	s_add_u32 s92, s68, 0x13100
	s_addc_u32 s93, s69, 0
	global_load_dword v139, v239, s[92:93]
	s_add_u32 s92, s68, 0x18100
	s_addc_u32 s93, s69, 0
	global_load_dword v140, v239, s[92:93]
	s_add_u32 s92, s68, 0x19100
	s_addc_u32 s93, s69, 0
	global_load_dword v141, v239, s[92:93]
	s_add_u32 s92, s68, 0x1a100
	s_addc_u32 s93, s69, 0
	global_load_dword v142, v239, s[92:93]
	s_add_u32 s92, s68, 0x1b100
	s_addc_u32 s93, s69, 0
	global_load_dword v143, v239, s[92:93]
	s_waitcnt vmcnt(32)
; DI int crow(int i, int h) { return (i & 3) + 8 * (i >> 2) + 4 * h; }
; template <int NT, class Epi>
; DI void gemm_tile(const u16* __restrict__ A, int lda, const u16* __restrict__ Bt, int ldb, int K, int m0, int n0, const Epi& epi, char* smem) {
;     ...
; #pragma unroll
;   for (int mt = 0; mt < 2; ++mt)
; #pragma unroll
;     for (int nt = 0; nt < NT; ++nt) epi(acc[mt][nt], m0 + wm * 64 + mt * 32, n0 + wn * 32 * NT + nt * 32, lane);
;   DI void operator()(const f32x16& acc, int row0, int col0, int lane) const {
;     const int r = lane & 31, h = lane >> 5, col = col0 + r;
; #pragma unroll
;     for (int i = 0; i < 16; ++i) { float* q = H + (size_t)(row0 + crow(i, h)) * DM + col; *q = *q + acc[i]; }
;   }
	v_add_f32_e32 v96, v96, v240
	v_add_f32_e32 v97, v97, v241
	v_add_f32_e32 v98, v98, v242
	v_add_f32_e32 v99, v99, v243
	v_add_f32_e32 v100, v100, v244
	v_add_f32_e32 v101, v101, v245
	v_add_f32_e32 v102, v102, v246
	v_add_f32_e32 v103, v103, v247
	v_add_f32_e32 v104, v104, v248
	v_add_f32_e32 v105, v105, v249
	v_add_f32_e32 v106, v106, v250
	v_add_f32_e32 v107, v107, v251
	v_add_f32_e32 v108, v108, v252
	v_add_f32_e32 v109, v109, v253
	v_add_f32_e32 v110, v110, v254
	v_add_f32_e32 v111, v111, v255
	s_add_u32 s92, s68, 0x80
	s_addc_u32 s93, s69, 0
	global_store_dword v239, v96, s[92:93]
	s_add_u32 s92, s68, 0x1080
	s_addc_u32 s93, s69, 0
	global_store_dword v239, v97, s[92:93]
	s_add_u32 s92, s68, 0x2080
	s_addc_u32 s93, s69, 0
	global_store_dword v239, v98, s[92:93]
	s_add_u32 s92, s68, 0x3080
	s_addc_u32 s93, s69, 0
	global_store_dword v239, v99, s[92:93]
	s_add_u32 s92, s68, 0x8080
	s_addc_u32 s93, s69, 0
	global_store_dword v239, v100, s[92:93]
	s_add_u32 s92, s68, 0x9080
	s_addc_u32 s93, s69, 0
	global_store_dword v239, v101, s[92:93]
	s_add_u32 s92, s68, 0xa080
	s_addc_u32 s93, s69, 0
	global_store_dword v239, v102, s[92:93]
	s_add_u32 s92, s68, 0xb080
	s_addc_u32 s93, s69, 0
	global_store_dword v239, v103, s[92:93]
	s_add_u32 s92, s68, 0x10080
	s_addc_u32 s93, s69, 0
	global_store_dword v239, v104, s[92:93]
	s_add_u32 s92, s68, 0x11080
	s_addc_u32 s93, s69, 0
	global_store_dword v239, v105, s[92:93]
	s_add_u32 s92, s68, 0x12080
	s_addc_u32 s93, s69, 0
	global_store_dword v239, v106, s[92:93]
	s_add_u32 s92, s68, 0x13080
	s_addc_u32 s93, s69, 0
	global_store_dword v239, v107, s[92:93]
	s_add_u32 s92, s68, 0x18080
	s_addc_u32 s93, s69, 0
	global_store_dword v239, v108, s[92:93]
	s_add_u32 s92, s68, 0x19080
	s_addc_u32 s93, s69, 0
	global_store_dword v239, v109, s[92:93]
	s_add_u32 s92, s68, 0x1a080
	s_addc_u32 s93, s69, 0
	global_store_dword v239, v110, s[92:93]
	s_add_u32 s92, s68, 0x1b080
	s_addc_u32 s93, s69, 0
	global_store_dword v239, v111, s[92:93]
	s_add_u32 s92, s68, 0x180
	s_addc_u32 s93, s69, 0
	global_load_dword v240, v239, s[92:93]
	s_add_u32 s92, s68, 0x1180
	s_addc_u32 s93, s69, 0
	global_load_dword v241, v239, s[92:93]
	s_add_u32 s92, s68, 0x2180
	s_addc_u32 s93, s69, 0
	global_load_dword v242, v239, s[92:93]
	s_add_u32 s92, s68, 0x3180
	s_addc_u32 s93, s69, 0
	global_load_dword v243, v239, s[92:93]
	s_add_u32 s92, s68, 0x8180
	s_addc_u32 s93, s69, 0
	global_load_dword v244, v239, s[92:93]
	s_add_u32 s92, s68, 0x9180
	s_addc_u32 s93, s69, 0
	global_load_dword v245, v239, s[92:93]
	s_add_u32 s92, s68, 0xa180
	s_addc_u32 s93, s69, 0
	global_load_dword v246, v239, s[92:93]
	s_add_u32 s92, s68, 0xb180
	s_addc_u32 s93, s69, 0
	global_load_dword v247, v239, s[92:93]
	s_add_u32 s92, s68, 0x10180
	s_addc_u32 s93, s69, 0
	global_load_dword v248, v239, s[92:93]
	s_add_u32 s92, s68, 0x11180
	s_addc_u32 s93, s69, 0
	global_load_dword v249, v239, s[92:93]
	s_add_u32 s92, s68, 0x12180
	s_addc_u32 s93, s69, 0
	global_load_dword v250, v239, s[92:93]
	s_add_u32 s92, s68, 0x13180
	s_addc_u32 s93, s69, 0
	global_load_dword v251, v239, s[92:93]
	s_add_u32 s92, s68, 0x18180
	s_addc_u32 s93, s69, 0
	global_load_dword v252, v239, s[92:93]
	s_add_u32 s92, s68, 0x19180
	s_addc_u32 s93, s69, 0
	global_load_dword v253, v239, s[92:93]
	s_add_u32 s92, s68, 0x1a180
	s_addc_u32 s93, s69, 0
	global_load_dword v254, v239, s[92:93]
	s_add_u32 s92, s68, 0x1b180
	s_addc_u32 s93, s69, 0
	global_load_dword v255, v239, s[92:93]
	s_waitcnt vmcnt(32)
	v_add_f32_e32 v80, v80, v128
	v_add_f32_e32 v81, v81, v129
	v_add_f32_e32 v82, v82, v130
	v_add_f32_e32 v83, v83, v131
	v_add_f32_e32 v84, v84, v132
	v_add_f32_e32 v85, v85, v133
	v_add_f32_e32 v86, v86, v134
	v_add_f32_e32 v87, v87, v135
	v_add_f32_e32 v88, v88, v136
	v_add_f32_e32 v89, v89, v137
	v_add_f32_e32 v90, v90, v138
	v_add_f32_e32 v91, v91, v139
	v_add_f32_e32 v92, v92, v140
	v_add_f32_e32 v93, v93, v141
	v_add_f32_e32 v94, v94, v142
	v_add_f32_e32 v95, v95, v143
	s_add_u32 s92, s68, 0x100
	s_addc_u32 s93, s69, 0
	global_store_dword v239, v80, s[92:93]
	s_add_u32 s92, s68, 0x1100
	s_addc_u32 s93, s69, 0
	global_store_dword v239, v81, s[92:93]
	s_add_u32 s92, s68, 0x2100
	s_addc_u32 s93, s69, 0
	global_store_dword v239, v82, s[92:93]
	s_add_u32 s92, s68, 0x3100
	s_addc_u32 s93, s69, 0
	global_store_dword v239, v83, s[92:93]
	s_add_u32 s92, s68, 0x8100
	s_addc_u32 s93, s69, 0
	global_store_dword v239, v84, s[92:93]
	s_add_u32 s92, s68, 0x9100
	s_addc_u32 s93, s69, 0
	global_store_dword v239, v85, s[92:93]
	s_add_u32 s92, s68, 0xa100
	s_addc_u32 s93, s69, 0
	global_store_dword v239, v86, s[92:93]
	s_add_u32 s92, s68, 0xb100
	s_addc_u32 s93, s69, 0
	global_store_dword v239, v87, s[92:93]
	s_add_u32 s92, s68, 0x10100
	s_addc_u32 s93, s69, 0
	global_store_dword v239, v88, s[92:93]
	s_add_u32 s92, s68, 0x11100
	s_addc_u32 s93, s69, 0
	global_store_dword v239, v89, s[92:93]
	s_add_u32 s92, s68, 0x12100
	s_addc_u32 s93, s69, 0
	global_store_dword v239, v90, s[92:93]
	s_add_u32 s92, s68, 0x13100
	s_addc_u32 s93, s69, 0
	global_store_dword v239, v91, s[92:93]
	s_add_u32 s92, s68, 0x18100
	s_addc_u32 s93, s69, 0
	global_store_dword v239, v92, s[92:93]
	s_add_u32 s92, s68, 0x19100
	s_addc_u32 s93, s69, 0
	global_store_dword v239, v93, s[92:93]
	s_add_u32 s92, s68, 0x1a100
	s_addc_u32 s93, s69, 0
	global_store_dword v239, v94, s[92:93]
	s_add_u32 s92, s68, 0x1b100
	s_addc_u32 s93, s69, 0
	global_store_dword v239, v95, s[92:93]
	s_add_u32 s92, s68, 0x20000
	s_addc_u32 s93, s69, 0
	global_load_dword v128, v239, s[92:93]
	s_add_u32 s92, s68, 0x21000
	s_addc_u32 s93, s69, 0
	global_load_dword v129, v239, s[92:93]
	s_add_u32 s92, s68, 0x22000
	s_addc_u32 s93, s69, 0
	global_load_dword v130, v239, s[92:93]
	s_add_u32 s92, s68, 0x23000
	s_addc_u32 s93, s69, 0
	global_load_dword v131, v239, s[92:93]
	s_add_u32 s92, s68, 0x28000
	s_addc_u32 s93, s69, 0
	global_load_dword v132, v239, s[92:93]
	s_add_u32 s92, s68, 0x29000
	s_addc_u32 s93, s69, 0
	global_load_dword v133, v239, s[92:93]
	s_add_u32 s92, s68, 0x2a000
	s_addc_u32 s93, s69, 0
	global_load_dword v134, v239, s[92:93]
	s_add_u32 s92, s68, 0x2b000
	s_addc_u32 s93, s69, 0
	global_load_dword v135, v239, s[92:93]
	s_add_u32 s92, s68, 0x30000
	s_addc_u32 s93, s69, 0
	global_load_dword v136, v239, s[92:93]
	s_add_u32 s92, s68, 0x31000
	s_addc_u32 s93, s69, 0
	global_load_dword v137, v239, s[92:93]
	s_add_u32 s92, s68, 0x32000
	s_addc_u32 s93, s69, 0
	global_load_dword v138, v239, s[92:93]
	s_add_u32 s92, s68, 0x33000
	s_addc_u32 s93, s69, 0
	global_load_dword v139, v239, s[92:93]
	s_add_u32 s92, s68, 0x38000
	s_addc_u32 s93, s69, 0
	global_load_dword v140, v239, s[92:93]
	s_add_u32 s92, s68, 0x39000
	s_addc_u32 s93, s69, 0
	global_load_dword v141, v239, s[92:93]
	s_add_u32 s92, s68, 0x3a000
	s_addc_u32 s93, s69, 0
	global_load_dword v142, v239, s[92:93]
	s_add_u32 s92, s68, 0x3b000
	s_addc_u32 s93, s69, 0
	global_load_dword v143, v239, s[92:93]
	s_waitcnt vmcnt(32)
; DI int crow(int i, int h) { return (i & 3) + 8 * (i >> 2) + 4 * h; }
; template <int NT, class Epi>
; DI void gemm_tile(const u16* __restrict__ A, int lda, const u16* __restrict__ Bt, int ldb, int K, int m0, int n0, const Epi& epi, char* smem) {
;     ...
; #pragma unroll
;   for (int mt = 0; mt < 2; ++mt)
; #pragma unroll
;     for (int nt = 0; nt < NT; ++nt) epi(acc[mt][nt], m0 + wm * 64 + mt * 32, n0 + wn * 32 * NT + nt * 32, lane);
;   DI void operator()(const f32x16& acc, int row0, int col0, int lane) const {
;     const int r = lane & 31, h = lane >> 5, col = col0 + r;
; #pragma unroll
;     for (int i = 0; i < 16; ++i) { float* q = H + (size_t)(row0 + crow(i, h)) * DM + col; *q = *q + acc[i]; }
;   }
	v_add_f32_e32 v64, v64, v240
	v_add_f32_e32 v65, v65, v241
	v_add_f32_e32 v66, v66, v242
	v_add_f32_e32 v67, v67, v243
	v_add_f32_e32 v68, v68, v244
	v_add_f32_e32 v69, v69, v245
	v_add_f32_e32 v70, v70, v246
	v_add_f32_e32 v71, v71, v247
	v_add_f32_e32 v72, v72, v248
	v_add_f32_e32 v73, v73, v249
	v_add_f32_e32 v74, v74, v250
	v_add_f32_e32 v75, v75, v251
	v_add_f32_e32 v76, v76, v252
	v_add_f32_e32 v77, v77, v253
	v_add_f32_e32 v78, v78, v254
	v_add_f32_e32 v79, v79, v255
	s_add_u32 s92, s68, 0x180
	s_addc_u32 s93, s69, 0
	global_store_dword v239, v64, s[92:93]
	s_add_u32 s92, s68, 0x1180
	s_addc_u32 s93, s69, 0
	global_store_dword v239, v65, s[92:93]
	s_add_u32 s92, s68, 0x2180
	s_addc_u32 s93, s69, 0
	global_store_dword v239, v66, s[92:93]
	s_add_u32 s92, s68, 0x3180
	s_addc_u32 s93, s69, 0
	global_store_dword v239, v67, s[92:93]
	s_add_u32 s92, s68, 0x8180
	s_addc_u32 s93, s69, 0
	global_store_dword v239, v68, s[92:93]
	s_add_u32 s92, s68, 0x9180
	s_addc_u32 s93, s69, 0
	global_store_dword v239, v69, s[92:93]
	s_add_u32 s92, s68, 0xa180
	s_addc_u32 s93, s69, 0
	global_store_dword v239, v70, s[92:93]
	s_add_u32 s92, s68, 0xb180
	s_addc_u32 s93, s69, 0
	global_store_dword v239, v71, s[92:93]
	s_add_u32 s92, s68, 0x10180
	s_addc_u32 s93, s69, 0
	global_store_dword v239, v72, s[92:93]
	s_add_u32 s92, s68, 0x11180
	s_addc_u32 s93, s69, 0
	global_store_dword v239, v73, s[92:93]
	s_add_u32 s92, s68, 0x12180
	s_addc_u32 s93, s69, 0
	global_store_dword v239, v74, s[92:93]
	s_add_u32 s92, s68, 0x13180
	s_addc_u32 s93, s69, 0
	global_store_dword v239, v75, s[92:93]
	s_add_u32 s92, s68, 0x18180
	s_addc_u32 s93, s69, 0
	global_store_dword v239, v76, s[92:93]
	s_add_u32 s92, s68, 0x19180
	s_addc_u32 s93, s69, 0
	global_store_dword v239, v77, s[92:93]
	s_add_u32 s92, s68, 0x1a180
	s_addc_u32 s93, s69, 0
	global_store_dword v239, v78, s[92:93]
	s_add_u32 s92, s68, 0x1b180
	s_addc_u32 s93, s69, 0
	global_store_dword v239, v79, s[92:93]
	s_add_u32 s92, s68, 0x20080
	s_addc_u32 s93, s69, 0
	global_load_dword v240, v239, s[92:93]
	s_add_u32 s92, s68, 0x21080
	s_addc_u32 s93, s69, 0
	global_load_dword v241, v239, s[92:93]
	s_add_u32 s92, s68, 0x22080
	s_addc_u32 s93, s69, 0
	global_load_dword v242, v239, s[92:93]
	s_add_u32 s92, s68, 0x23080
	s_addc_u32 s93, s69, 0
	global_load_dword v243, v239, s[92:93]
	s_add_u32 s92, s68, 0x28080
	s_addc_u32 s93, s69, 0
	global_load_dword v244, v239, s[92:93]
	s_add_u32 s92, s68, 0x29080
	s_addc_u32 s93, s69, 0
	global_load_dword v245, v239, s[92:93]
	s_add_u32 s92, s68, 0x2a080
	s_addc_u32 s93, s69, 0
	global_load_dword v246, v239, s[92:93]
	s_add_u32 s92, s68, 0x2b080
	s_addc_u32 s93, s69, 0
	global_load_dword v247, v239, s[92:93]
	s_add_u32 s92, s68, 0x30080
	s_addc_u32 s93, s69, 0
	global_load_dword v248, v239, s[92:93]
	s_add_u32 s92, s68, 0x31080
	s_addc_u32 s93, s69, 0
	global_load_dword v249, v239, s[92:93]
	s_add_u32 s92, s68, 0x32080
	s_addc_u32 s93, s69, 0
	global_load_dword v250, v239, s[92:93]
	s_add_u32 s92, s68, 0x33080
	s_addc_u32 s93, s69, 0
	global_load_dword v251, v239, s[92:93]
	s_add_u32 s92, s68, 0x38080
	s_addc_u32 s93, s69, 0
	global_load_dword v252, v239, s[92:93]
	s_add_u32 s92, s68, 0x39080
	s_addc_u32 s93, s69, 0
	global_load_dword v253, v239, s[92:93]
	s_add_u32 s92, s68, 0x3a080
	s_addc_u32 s93, s69, 0
	global_load_dword v254, v239, s[92:93]
	s_add_u32 s92, s68, 0x3b080
	s_addc_u32 s93, s69, 0
	global_load_dword v255, v239, s[92:93]
	s_waitcnt vmcnt(32)
	v_add_f32_e32 v48, v48, v128
	v_add_f32_e32 v49, v49, v129
	v_add_f32_e32 v50, v50, v130
	v_add_f32_e32 v51, v51, v131
	v_add_f32_e32 v52, v52, v132
	v_add_f32_e32 v53, v53, v133
	v_add_f32_e32 v54, v54, v134
	v_add_f32_e32 v55, v55, v135
	v_add_f32_e32 v56, v56, v136
	v_add_f32_e32 v57, v57, v137
	v_add_f32_e32 v58, v58, v138
	v_add_f32_e32 v59, v59, v139
	v_add_f32_e32 v60, v60, v140
	v_add_f32_e32 v61, v61, v141
	v_add_f32_e32 v62, v62, v142
	v_add_f32_e32 v63, v63, v143
	s_add_u32 s92, s68, 0x20000
	s_addc_u32 s93, s69, 0
	global_store_dword v239, v48, s[92:93]
	s_add_u32 s92, s68, 0x21000
	s_addc_u32 s93, s69, 0
	global_store_dword v239, v49, s[92:93]
	s_add_u32 s92, s68, 0x22000
	s_addc_u32 s93, s69, 0
	global_store_dword v239, v50, s[92:93]
	s_add_u32 s92, s68, 0x23000
	s_addc_u32 s93, s69, 0
	global_store_dword v239, v51, s[92:93]
	s_add_u32 s92, s68, 0x28000
	s_addc_u32 s93, s69, 0
	global_store_dword v239, v52, s[92:93]
	s_add_u32 s92, s68, 0x29000
	s_addc_u32 s93, s69, 0
	global_store_dword v239, v53, s[92:93]
	s_add_u32 s92, s68, 0x2a000
	s_addc_u32 s93, s69, 0
	global_store_dword v239, v54, s[92:93]
	s_add_u32 s92, s68, 0x2b000
	s_addc_u32 s93, s69, 0
	global_store_dword v239, v55, s[92:93]
	s_add_u32 s92, s68, 0x30000
	s_addc_u32 s93, s69, 0
	global_store_dword v239, v56, s[92:93]
	s_add_u32 s92, s68, 0x31000
	s_addc_u32 s93, s69, 0
	global_store_dword v239, v57, s[92:93]
	s_add_u32 s92, s68, 0x32000
	s_addc_u32 s93, s69, 0
	global_store_dword v239, v58, s[92:93]
	s_add_u32 s92, s68, 0x33000
	s_addc_u32 s93, s69, 0
	global_store_dword v239, v59, s[92:93]
	s_add_u32 s92, s68, 0x38000
	s_addc_u32 s93, s69, 0
	global_store_dword v239, v60, s[92:93]
	s_add_u32 s92, s68, 0x39000
	s_addc_u32 s93, s69, 0
	global_store_dword v239, v61, s[92:93]
	s_add_u32 s92, s68, 0x3a000
	s_addc_u32 s93, s69, 0
	global_store_dword v239, v62, s[92:93]
	s_add_u32 s92, s68, 0x3b000
	s_addc_u32 s93, s69, 0
	global_store_dword v239, v63, s[92:93]
	s_add_u32 s92, s68, 0x20100
	s_addc_u32 s93, s69, 0
	global_load_dword v128, v239, s[92:93]
	s_add_u32 s92, s68, 0x21100
	s_addc_u32 s93, s69, 0
	global_load_dword v129, v239, s[92:93]
	s_add_u32 s92, s68, 0x22100
	s_addc_u32 s93, s69, 0
	global_load_dword v130, v239, s[92:93]
	s_add_u32 s92, s68, 0x23100
	s_addc_u32 s93, s69, 0
	global_load_dword v131, v239, s[92:93]
	s_add_u32 s92, s68, 0x28100
	s_addc_u32 s93, s69, 0
	global_load_dword v132, v239, s[92:93]
	s_add_u32 s92, s68, 0x29100
	s_addc_u32 s93, s69, 0
	global_load_dword v133, v239, s[92:93]
	s_add_u32 s92, s68, 0x2a100
	s_addc_u32 s93, s69, 0
	global_load_dword v134, v239, s[92:93]
	s_add_u32 s92, s68, 0x2b100
	s_addc_u32 s93, s69, 0
	global_load_dword v135, v239, s[92:93]
	s_add_u32 s92, s68, 0x30100
	s_addc_u32 s93, s69, 0
	global_load_dword v136, v239, s[92:93]
	s_add_u32 s92, s68, 0x31100
	s_addc_u32 s93, s69, 0
	global_load_dword v137, v239, s[92:93]
	s_add_u32 s92, s68, 0x32100
	s_addc_u32 s93, s69, 0
	global_load_dword v138, v239, s[92:93]
	s_add_u32 s92, s68, 0x33100
	s_addc_u32 s93, s69, 0
	global_load_dword v139, v239, s[92:93]
	s_add_u32 s92, s68, 0x38100
	s_addc_u32 s93, s69, 0
	global_load_dword v140, v239, s[92:93]
	s_add_u32 s92, s68, 0x39100
	s_addc_u32 s93, s69, 0
	global_load_dword v141, v239, s[92:93]
	s_add_u32 s92, s68, 0x3a100
	s_addc_u32 s93, s69, 0
	global_load_dword v142, v239, s[92:93]
	s_add_u32 s92, s68, 0x3b100
	s_addc_u32 s93, s69, 0
	global_load_dword v143, v239, s[92:93]
	s_waitcnt vmcnt(32)
; DI int crow(int i, int h) { return (i & 3) + 8 * (i >> 2) + 4 * h; }
; template <int NT, class Epi>
; DI void gemm_tile(const u16* __restrict__ A, int lda, const u16* __restrict__ Bt, int ldb, int K, int m0, int n0, const Epi& epi, char* smem) {
;     ...
; #pragma unroll
;   for (int mt = 0; mt < 2; ++mt)
; #pragma unroll
;     for (int nt = 0; nt < NT; ++nt) epi(acc[mt][nt], m0 + wm * 64 + mt * 32, n0 + wn * 32 * NT + nt * 32, lane);
;   DI void operator()(const f32x16& acc, int row0, int col0, int lane) const {
;     const int r = lane & 31, h = lane >> 5, col = col0 + r;
; #pragma unroll
;     for (int i = 0; i < 16; ++i) { float* q = H + (size_t)(row0 + crow(i, h)) * DM + col; *q = *q + acc[i]; }
;   }
	v_add_f32_e32 v32, v32, v240
	v_add_f32_e32 v33, v33, v241
	v_add_f32_e32 v34, v34, v242
	v_add_f32_e32 v35, v35, v243
	v_add_f32_e32 v36, v36, v244
	v_add_f32_e32 v37, v37, v245
	v_add_f32_e32 v38, v38, v246
	v_add_f32_e32 v39, v39, v247
	v_add_f32_e32 v40, v40, v248
	v_add_f32_e32 v41, v41, v249
	v_add_f32_e32 v42, v42, v250
	v_add_f32_e32 v43, v43, v251
	v_add_f32_e32 v44, v44, v252
	v_add_f32_e32 v45, v45, v253
	v_add_f32_e32 v46, v46, v254
	v_add_f32_e32 v47, v47, v255
	s_add_u32 s92, s68, 0x20080
	s_addc_u32 s93, s69, 0
	global_store_dword v239, v32, s[92:93]
	s_add_u32 s92, s68, 0x21080
	s_addc_u32 s93, s69, 0
	global_store_dword v239, v33, s[92:93]
	s_add_u32 s92, s68, 0x22080
	s_addc_u32 s93, s69, 0
	global_store_dword v239, v34, s[92:93]
	s_add_u32 s92, s68, 0x23080
	s_addc_u32 s93, s69, 0
	global_store_dword v239, v35, s[92:93]
	s_add_u32 s92, s68, 0x28080
	s_addc_u32 s93, s69, 0
	global_store_dword v239, v36, s[92:93]
	s_add_u32 s92, s68, 0x29080
	s_addc_u32 s93, s69, 0
	global_store_dword v239, v37, s[92:93]
	s_add_u32 s92, s68, 0x2a080
	s_addc_u32 s93, s69, 0
	global_store_dword v239, v38, s[92:93]
	s_add_u32 s92, s68, 0x2b080
	s_addc_u32 s93, s69, 0
	global_store_dword v239, v39, s[92:93]
	s_add_u32 s92, s68, 0x30080
	s_addc_u32 s93, s69, 0
	global_store_dword v239, v40, s[92:93]
	s_add_u32 s92, s68, 0x31080
	s_addc_u32 s93, s69, 0
	global_store_dword v239, v41, s[92:93]
	s_add_u32 s92, s68, 0x32080
	s_addc_u32 s93, s69, 0
	global_store_dword v239, v42, s[92:93]
	s_add_u32 s92, s68, 0x33080
	s_addc_u32 s93, s69, 0
	global_store_dword v239, v43, s[92:93]
	s_add_u32 s92, s68, 0x38080
	s_addc_u32 s93, s69, 0
	global_store_dword v239, v44, s[92:93]
	s_add_u32 s92, s68, 0x39080
	s_addc_u32 s93, s69, 0
	global_store_dword v239, v45, s[92:93]
	s_add_u32 s92, s68, 0x3a080
	s_addc_u32 s93, s69, 0
	global_store_dword v239, v46, s[92:93]
	s_add_u32 s92, s68, 0x3b080
	s_addc_u32 s93, s69, 0
	global_store_dword v239, v47, s[92:93]
	s_add_u32 s92, s68, 0x20180
	s_addc_u32 s93, s69, 0
	global_load_dword v240, v239, s[92:93]
	s_add_u32 s92, s68, 0x21180
	s_addc_u32 s93, s69, 0
	global_load_dword v241, v239, s[92:93]
	s_add_u32 s92, s68, 0x22180
	s_addc_u32 s93, s69, 0
	global_load_dword v242, v239, s[92:93]
	s_add_u32 s92, s68, 0x23180
	s_addc_u32 s93, s69, 0
	global_load_dword v243, v239, s[92:93]
	s_add_u32 s92, s68, 0x28180
	s_addc_u32 s93, s69, 0
	global_load_dword v244, v239, s[92:93]
	s_add_u32 s92, s68, 0x29180
	s_addc_u32 s93, s69, 0
	global_load_dword v245, v239, s[92:93]
	s_add_u32 s92, s68, 0x2a180
	s_addc_u32 s93, s69, 0
	global_load_dword v246, v239, s[92:93]
	s_add_u32 s92, s68, 0x2b180
	s_addc_u32 s93, s69, 0
	global_load_dword v247, v239, s[92:93]
	s_add_u32 s92, s68, 0x30180
	s_addc_u32 s93, s69, 0
	global_load_dword v248, v239, s[92:93]
	s_add_u32 s92, s68, 0x31180
	s_addc_u32 s93, s69, 0
	global_load_dword v249, v239, s[92:93]
	s_add_u32 s92, s68, 0x32180
	s_addc_u32 s93, s69, 0
	global_load_dword v250, v239, s[92:93]
	s_add_u32 s92, s68, 0x33180
	s_addc_u32 s93, s69, 0
	global_load_dword v251, v239, s[92:93]
	s_add_u32 s92, s68, 0x38180
	s_addc_u32 s93, s69, 0
	global_load_dword v252, v239, s[92:93]
	s_add_u32 s92, s68, 0x39180
	s_addc_u32 s93, s69, 0
	global_load_dword v253, v239, s[92:93]
	s_add_u32 s92, s68, 0x3a180
	s_addc_u32 s93, s69, 0
	global_load_dword v254, v239, s[92:93]
	s_add_u32 s92, s68, 0x3b180
	s_addc_u32 s93, s69, 0
	global_load_dword v255, v239, s[92:93]
	s_waitcnt vmcnt(32)
; DI int crow(int i, int h) { return (i & 3) + 8 * (i >> 2) + 4 * h; }
; template <int NT, class Epi>
; DI void gemm_tile(const u16* __restrict__ A, int lda, const u16* __restrict__ Bt, int ldb, int K, int m0, int n0, const Epi& epi, char* smem) {
;     ...
; #pragma unroll
;   for (int mt = 0; mt < 2; ++mt)
; #pragma unroll
;     for (int nt = 0; nt < NT; ++nt) epi(acc[mt][nt], m0 + wm * 64 + mt * 32, n0 + wn * 32 * NT + nt * 32, lane);
;   DI void operator()(const f32x16& acc, int row0, int col0, int lane) const {
;     const int r = lane & 31, h = lane >> 5, col = col0 + r;
; #pragma unroll
;     for (int i = 0; i < 16; ++i) { float* q = H + (size_t)(row0 + crow(i, h)) * DM + col; *q = *q + acc[i]; }
;   }
	v_add_f32_e32 v16, v16, v128
	v_add_f32_e32 v17, v17, v129
	v_add_f32_e32 v18, v18, v130
	v_add_f32_e32 v19, v19, v131
	v_add_f32_e32 v20, v20, v132
	v_add_f32_e32 v21, v21, v133
	v_add_f32_e32 v22, v22, v134
	v_add_f32_e32 v23, v23, v135
	v_add_f32_e32 v24, v24, v136
	v_add_f32_e32 v25, v25, v137
	v_add_f32_e32 v26, v26, v138
	v_add_f32_e32 v27, v27, v139
	v_add_f32_e32 v28, v28, v140
	v_add_f32_e32 v29, v29, v141
	v_add_f32_e32 v30, v30, v142
	v_add_f32_e32 v31, v31, v143
	s_add_u32 s92, s68, 0x20100
	s_addc_u32 s93, s69, 0
	global_store_dword v239, v16, s[92:93]
	s_add_u32 s92, s68, 0x21100
	s_addc_u32 s93, s69, 0
	global_store_dword v239, v17, s[92:93]
	s_add_u32 s92, s68, 0x22100
	s_addc_u32 s93, s69, 0
	global_store_dword v239, v18, s[92:93]
	s_add_u32 s92, s68, 0x23100
	s_addc_u32 s93, s69, 0
	global_store_dword v239, v19, s[92:93]
	s_add_u32 s92, s68, 0x28100
	s_addc_u32 s93, s69, 0
	global_store_dword v239, v20, s[92:93]
	s_add_u32 s92, s68, 0x29100
	s_addc_u32 s93, s69, 0
	global_store_dword v239, v21, s[92:93]
	s_add_u32 s92, s68, 0x2a100
	s_addc_u32 s93, s69, 0
	global_store_dword v239, v22, s[92:93]
	s_add_u32 s92, s68, 0x2b100
	s_addc_u32 s93, s69, 0
	global_store_dword v239, v23, s[92:93]
	s_add_u32 s92, s68, 0x30100
	s_addc_u32 s93, s69, 0
	global_store_dword v239, v24, s[92:93]
	s_add_u32 s92, s68, 0x31100
	s_addc_u32 s93, s69, 0
	global_store_dword v239, v25, s[92:93]
	s_add_u32 s92, s68, 0x32100
	s_addc_u32 s93, s69, 0
	global_store_dword v239, v26, s[92:93]
	s_add_u32 s92, s68, 0x33100
	s_addc_u32 s93, s69, 0
	global_store_dword v239, v27, s[92:93]
	s_add_u32 s92, s68, 0x38100
	s_addc_u32 s93, s69, 0
	global_store_dword v239, v28, s[92:93]
	s_add_u32 s92, s68, 0x39100
	s_addc_u32 s93, s69, 0
	global_store_dword v239, v29, s[92:93]
	s_add_u32 s92, s68, 0x3a100
	s_addc_u32 s93, s69, 0
	global_store_dword v239, v30, s[92:93]
	s_add_u32 s92, s68, 0x3b100
	s_addc_u32 s93, s69, 0
	global_store_dword v239, v31, s[92:93]
	s_waitcnt vmcnt(16)
	v_add_f32_e32 v0, v0, v240
	v_add_f32_e32 v1, v1, v241
	v_add_f32_e32 v2, v2, v242
	v_add_f32_e32 v3, v3, v243
	v_add_f32_e32 v4, v4, v244
	v_add_f32_e32 v5, v5, v245
	v_add_f32_e32 v6, v6, v246
	v_add_f32_e32 v7, v7, v247
	v_add_f32_e32 v8, v8, v248
	v_add_f32_e32 v9, v9, v249
	v_add_f32_e32 v10, v10, v250
	v_add_f32_e32 v11, v11, v251
	v_add_f32_e32 v12, v12, v252
	v_add_f32_e32 v13, v13, v253
	v_add_f32_e32 v14, v14, v254
	v_add_f32_e32 v15, v15, v255
	s_add_u32 s92, s68, 0x20180
	s_addc_u32 s93, s69, 0
	global_store_dword v239, v0, s[92:93]
	s_add_u32 s92, s68, 0x21180
	s_addc_u32 s93, s69, 0
	global_store_dword v239, v1, s[92:93]
	s_add_u32 s92, s68, 0x22180
	s_addc_u32 s93, s69, 0
	global_store_dword v239, v2, s[92:93]
	s_add_u32 s92, s68, 0x23180
	s_addc_u32 s93, s69, 0
	global_store_dword v239, v3, s[92:93]
	s_add_u32 s92, s68, 0x28180
	s_addc_u32 s93, s69, 0
	global_store_dword v239, v4, s[92:93]
	s_add_u32 s92, s68, 0x29180
	s_addc_u32 s93, s69, 0
	global_store_dword v239, v5, s[92:93]
	s_add_u32 s92, s68, 0x2a180
	s_addc_u32 s93, s69, 0
	global_store_dword v239, v6, s[92:93]
	s_add_u32 s92, s68, 0x2b180
	s_addc_u32 s93, s69, 0
	global_store_dword v239, v7, s[92:93]
	s_add_u32 s92, s68, 0x30180
	s_addc_u32 s93, s69, 0
	global_store_dword v239, v8, s[92:93]
	s_add_u32 s92, s68, 0x31180
	s_addc_u32 s93, s69, 0
	global_store_dword v239, v9, s[92:93]
	s_add_u32 s92, s68, 0x32180
	s_addc_u32 s93, s69, 0
	global_store_dword v239, v10, s[92:93]
	s_add_u32 s92, s68, 0x33180
	s_addc_u32 s93, s69, 0
	global_store_dword v239, v11, s[92:93]
	s_add_u32 s92, s68, 0x38180
	s_addc_u32 s93, s69, 0
	global_store_dword v239, v12, s[92:93]
	s_add_u32 s92, s68, 0x39180
	s_addc_u32 s93, s69, 0
	global_store_dword v239, v13, s[92:93]
	s_add_u32 s92, s68, 0x3a180
	s_addc_u32 s93, s69, 0
	global_store_dword v239, v14, s[92:93]
	s_add_u32 s92, s68, 0x3b180
	s_addc_u32 s93, s69, 0
	global_store_dword v239, v15, s[92:93]
	s_cmp_lg_u32 s91, 0
	s_cbranch_scc1 .LBB0_642

; DI f32x16 mfma32(bf16x8 a, bf16x8 b, f32x16 c) { return __builtin_amdgcn_mfma_f32_32x32x16_bf16(a, b, c, 0, 0, 0); }
; template <int NT, class Epi>
; DI void gemm_tile(const u16* __restrict__ A, int lda, const u16* __restrict__ Bt, int ldb, int K, int m0, int n0, const Epi& epi, char* smem) {
;     ...
;   for (int kt = 0; kt < nk; ++kt) {
; #pragma unroll
;     for (int i = 0; i < 4; ++i) *(u32x4*)(As + (lrow + 32 * i) * 72 + lch * 8) = ra[i];
; #pragma unroll
;     for (int i = 0; i < NB8; ++i) *(u32x4*)(Bs + (lrow + 32 * i) * 72 + lch * 8) = rb[i];
;     __syncthreads();
;     if (kt + 1 < nk) {
;       const int k0 = (kt + 1) * 64;
; #pragma unroll
;       for (int i = 0; i < 4; ++i) ra[i] = *(const u32x4*)(Ap + (size_t)(32 * i) * lda + k0);
; #pragma unroll
;       for (int i = 0; i < NB8; ++i) rb[i] = *(const u32x4*)(Bp + (size_t)(32 * i) * ldb + k0);
;     }
; #pragma unroll
;     for (int ks = 0; ks < 4; ++ks) {
;       bf16x8 a[2], b[NT];
; #pragma unroll
;       for (int mt = 0; mt < 2; ++mt) a[mt] = *(const bf16x8*)(As + (wm * 64 + mt * 32 + r) * 72 + ks * 16 + h * 8);
; #pragma unroll
;       for (int nt = 0; nt < NT; ++nt) b[nt] = *(const bf16x8*)(Bs + (wn * 32 * NT + nt * 32 + r) * 72 + ks * 16 + h * 8);
; #pragma unroll
;       for (int mt = 0; mt < 2; ++mt)
; #pragma unroll
;         for (int nt = 0; nt < NT; ++nt) acc[mt][nt] = mfma32(a[mt], b[nt], acc[mt][nt]);
;     }
.LBB0_676:
	s_waitcnt vmcnt(11)
	ds_write_b128 v202, v[128:131]
	s_waitcnt vmcnt(10)
	ds_write_b128 v202, v[132:135] offset:4608
	s_waitcnt vmcnt(9)
	ds_write_b128 v202, v[136:139] offset:9216
	s_waitcnt vmcnt(8)
	ds_write_b128 v202, v[140:143] offset:13824
	s_waitcnt vmcnt(7)
	ds_write_b128 v202, v[144:147] offset:18432
	s_waitcnt vmcnt(6)
	ds_write_b128 v202, v[148:151] offset:23040
	s_waitcnt vmcnt(5)
	ds_write_b128 v202, v[152:155] offset:27648
	s_waitcnt vmcnt(4)
	ds_write_b128 v202, v[156:159] offset:32256
	s_waitcnt vmcnt(3)
	ds_write_b128 v202, v[160:163] offset:36864
	s_waitcnt vmcnt(2)
	ds_write_b128 v202, v[164:167] offset:41472
	s_waitcnt vmcnt(1)
	ds_write_b128 v202, v[168:171] offset:46080
	s_waitcnt vmcnt(0)
	ds_write_b128 v202, v[172:175] offset:50688
	s_waitcnt lgkmcnt(0)
	s_barrier
	s_add_u32 s92, s14, s22
	s_addc_u32 s93, s15, 0
	v_lshl_add_u64 v[238:239], v[194:195], 0, s[92:93]
	global_load_dwordx4 v[128:131], v[238:239], off offset:128
	s_add_u32 s92, s14, s23
	s_addc_u32 s93, s15, 0
	v_lshl_add_u64 v[238:239], v[194:195], 0, s[92:93]
	global_load_dwordx4 v[132:135], v[238:239], off offset:128
	s_add_u32 s92, s14, s24
	s_addc_u32 s93, s15, 0
	v_lshl_add_u64 v[238:239], v[194:195], 0, s[92:93]
	global_load_dwordx4 v[136:139], v[238:239], off offset:128
	s_add_u32 s92, s14, s25
	s_addc_u32 s93, s15, 0
	v_lshl_add_u64 v[238:239], v[194:195], 0, s[92:93]
	global_load_dwordx4 v[140:143], v[238:239], off offset:128
	s_add_u32 s92, s14, s26
	s_addc_u32 s93, s15, 0
	v_lshl_add_u64 v[238:239], v[200:201], 0, s[92:93]
	global_load_dwordx4 v[144:147], v[238:239], off offset:128
	s_add_u32 s92, s14, s27
	s_addc_u32 s93, s15, 0
	v_lshl_add_u64 v[238:239], v[200:201], 0, s[92:93]
	global_load_dwordx4 v[148:151], v[238:239], off offset:128
	s_add_u32 s92, s14, s28
	s_addc_u32 s93, s15, 0
	v_lshl_add_u64 v[238:239], v[200:201], 0, s[92:93]
	global_load_dwordx4 v[152:155], v[238:239], off offset:128
	s_add_u32 s92, s14, s29
	s_addc_u32 s93, s15, 0
	v_lshl_add_u64 v[238:239], v[200:201], 0, s[92:93]
	global_load_dwordx4 v[156:159], v[238:239], off offset:128
	s_add_u32 s92, s14, s30
	s_addc_u32 s93, s15, 0
	v_lshl_add_u64 v[238:239], v[200:201], 0, s[92:93]
	global_load_dwordx4 v[160:163], v[238:239], off offset:128
	s_add_u32 s92, s14, s31
	s_addc_u32 s93, s15, 0
	v_lshl_add_u64 v[238:239], v[200:201], 0, s[92:93]
	global_load_dwordx4 v[164:167], v[238:239], off offset:128
	s_add_u32 s92, s14, s34
	s_addc_u32 s93, s15, 0
	v_lshl_add_u64 v[238:239], v[200:201], 0, s[92:93]
	global_load_dwordx4 v[168:171], v[238:239], off offset:128
	s_add_u32 s92, s14, s35
	s_addc_u32 s93, s15, 0
	v_lshl_add_u64 v[238:239], v[200:201], 0, s[92:93]
	global_load_dwordx4 v[172:175], v[238:239], off offset:128
	s_add_u32 s14, s14, 0x80
	s_addc_u32 s15, s15, 0
	s_cmpk_lg_i32 s14, 0x780
	ds_read_b128 v[206:209], v203
	ds_read_b128 v[252:255], v204 offset:18432
	ds_read_b128 v[248:251], v204 offset:23040
	ds_read_b128 v[244:247], v204 offset:27648
	ds_read_b128 v[240:243], v204 offset:32256
	ds_read_b128 v[230:233], v203 offset:4608
	s_waitcnt lgkmcnt(4)
	v_mfma_f32_32x32x16_bf16 v[112:127], v[206:209], v[252:255], v[112:127]
	s_waitcnt lgkmcnt(3)
	v_mfma_f32_32x32x16_bf16 v[96:111], v[206:209], v[248:251], v[96:111]
	s_waitcnt lgkmcnt(2)
	v_mfma_f32_32x32x16_bf16 v[80:95], v[206:209], v[244:247], v[80:95]
	s_waitcnt lgkmcnt(1)
	v_mfma_f32_32x32x16_bf16 v[64:79], v[206:209], v[240:243], v[64:79]
	ds_read_b128 v[206:209], v203 offset:32
	s_waitcnt lgkmcnt(1)
	v_mfma_f32_32x32x16_bf16 v[48:63], v[230:233], v[252:255], v[48:63]
	ds_read_b128 v[252:255], v204 offset:18464
	v_mfma_f32_32x32x16_bf16 v[32:47], v[230:233], v[248:251], v[32:47]
	ds_read_b128 v[248:251], v204 offset:23072
	v_mfma_f32_32x32x16_bf16 v[16:31], v[230:233], v[244:247], v[16:31]
	ds_read_b128 v[244:247], v204 offset:27680
	v_mfma_f32_32x32x16_bf16 v[0:15], v[230:233], v[240:243], v[0:15]
	ds_read_b128 v[240:243], v204 offset:32288
	ds_read_b128 v[230:233], v203 offset:4640
	s_waitcnt lgkmcnt(4)
	v_mfma_f32_32x32x16_bf16 v[112:127], v[206:209], v[252:255], v[112:127]
	s_waitcnt lgkmcnt(3)
	v_mfma_f32_32x32x16_bf16 v[96:111], v[206:209], v[248:251], v[96:111]
	s_waitcnt lgkmcnt(2)
	v_mfma_f32_32x32x16_bf16 v[80:95], v[206:209], v[244:247], v[80:95]
	s_waitcnt lgkmcnt(1)
	v_mfma_f32_32x32x16_bf16 v[64:79], v[206:209], v[240:243], v[64:79]
	ds_read_b128 v[206:209], v203 offset:64
	s_waitcnt lgkmcnt(1)
	v_mfma_f32_32x32x16_bf16 v[48:63], v[230:233], v[252:255], v[48:63]
	ds_read_b128 v[252:255], v204 offset:18496
	v_mfma_f32_32x32x16_bf16 v[32:47], v[230:233], v[248:251], v[32:47]
	ds_read_b128 v[248:251], v204 offset:23104
	v_mfma_f32_32x32x16_bf16 v[16:31], v[230:233], v[244:247], v[16:31]
	ds_read_b128 v[244:247], v204 offset:27712
	v_mfma_f32_32x32x16_bf16 v[0:15], v[230:233], v[240:243], v[0:15]
	ds_read_b128 v[240:243], v204 offset:32320
	ds_read_b128 v[230:233], v203 offset:4672
	s_waitcnt lgkmcnt(4)
	v_mfma_f32_32x32x16_bf16 v[112:127], v[206:209], v[252:255], v[112:127]
	s_waitcnt lgkmcnt(3)
	v_mfma_f32_32x32x16_bf16 v[96:111], v[206:209], v[248:251], v[96:111]
	s_waitcnt lgkmcnt(2)
	v_mfma_f32_32x32x16_bf16 v[80:95], v[206:209], v[244:247], v[80:95]
	s_waitcnt lgkmcnt(1)
	v_mfma_f32_32x32x16_bf16 v[64:79], v[206:209], v[240:243], v[64:79]
	ds_read_b128 v[206:209], v203 offset:96
	s_waitcnt lgkmcnt(1)
	v_mfma_f32_32x32x16_bf16 v[48:63], v[230:233], v[252:255], v[48:63]
	ds_read_b128 v[252:255], v204 offset:18528
	v_mfma_f32_32x32x16_bf16 v[32:47], v[230:233], v[248:251], v[32:47]
	ds_read_b128 v[248:251], v204 offset:23136
	v_mfma_f32_32x32x16_bf16 v[16:31], v[230:233], v[244:247], v[16:31]
	ds_read_b128 v[244:247], v204 offset:27744
	v_mfma_f32_32x32x16_bf16 v[0:15], v[230:233], v[240:243], v[0:15]
	ds_read_b128 v[240:243], v204 offset:32352
	ds_read_b128 v[230:233], v203 offset:4704
	s_waitcnt lgkmcnt(4)
	v_mfma_f32_32x32x16_bf16 v[112:127], v[206:209], v[252:255], v[112:127]
	s_waitcnt lgkmcnt(3)
	v_mfma_f32_32x32x16_bf16 v[96:111], v[206:209], v[248:251], v[96:111]
	s_waitcnt lgkmcnt(2)
	v_mfma_f32_32x32x16_bf16 v[80:95], v[206:209], v[244:247], v[80:95]
	s_waitcnt lgkmcnt(1)
	v_mfma_f32_32x32x16_bf16 v[64:79], v[206:209], v[240:243], v[64:79]
	s_waitcnt lgkmcnt(0)
	v_mfma_f32_32x32x16_bf16 v[48:63], v[230:233], v[252:255], v[48:63]
	v_mfma_f32_32x32x16_bf16 v[32:47], v[230:233], v[248:251], v[32:47]
	v_mfma_f32_32x32x16_bf16 v[16:31], v[230:233], v[244:247], v[16:31]
	s_barrier
; DI int crow(int i, int h) { return (i & 3) + 8 * (i >> 2) + 4 * h; }
; DI f32x16 mfma32(bf16x8 a, bf16x8 b, f32x16 c) { return __builtin_amdgcn_mfma_f32_32x32x16_bf16(a, b, c, 0, 0, 0); }
; template <int NT, class Epi>
; DI void gemm_tile(const u16* __restrict__ A, int lda, const u16* __restrict__ Bt, int ldb, int K, int m0, int n0, const Epi& epi, char* smem) {
;     ...
; #pragma unroll
;     for (int i = 0; i < 4; ++i) *(u32x4*)(As + (lrow + 32 * i) * 72 + lch * 8) = ra[i];
; #pragma unroll
;     for (int i = 0; i < NB8; ++i) *(u32x4*)(Bs + (lrow + 32 * i) * 72 + lch * 8) = rb[i];
;     __syncthreads();
;     if (kt + 1 < nk) {
;       const int k0 = (kt + 1) * 64;
; #pragma unroll
;       for (int i = 0; i < 4; ++i) ra[i] = *(const u32x4*)(Ap + (size_t)(32 * i) * lda + k0);
; #pragma unroll
;       for (int i = 0; i < NB8; ++i) rb[i] = *(const u32x4*)(Bp + (size_t)(32 * i) * ldb + k0);
;     }
; #pragma unroll
;     for (int ks = 0; ks < 4; ++ks) {
;       bf16x8 a[2], b[NT];
; #pragma unroll
;       for (int mt = 0; mt < 2; ++mt) a[mt] = *(const bf16x8*)(As + (wm * 64 + mt * 32 + r) * 72 + ks * 16 + h * 8);
; #pragma unroll
;       for (int nt = 0; nt < NT; ++nt) b[nt] = *(const bf16x8*)(Bs + (wn * 32 * NT + nt * 32 + r) * 72 + ks * 16 + h * 8);
; #pragma unroll
;       for (int mt = 0; mt < 2; ++mt)
; #pragma unroll
;         for (int nt = 0; nt < NT; ++nt) acc[mt][nt] = mfma32(a[mt], b[nt], acc[mt][nt]);
;     }
;   DI void operator()(const f32x16& acc, int row0, int col0, int lane) const {
;     const int r = lane & 31, h = lane >> 5, col = col0 + r;
;     if (col >= N) return;
; #pragma unroll
;     for (int i = 0; i < 16; ++i) C[(size_t)(row0 + crow(i, h)) * ldc + col] = f2bf(acc[i]);
	v_mfma_f32_32x32x16_bf16 v[0:15], v[230:233], v[240:243], v[0:15]
	s_cbranch_scc1 .LBB0_676
	s_waitcnt vmcnt(11)
	ds_write_b128 v202, v[128:131]
	s_waitcnt vmcnt(10)
	ds_write_b128 v202, v[132:135] offset:4608
	s_waitcnt vmcnt(9)
	ds_write_b128 v202, v[136:139] offset:9216
	s_waitcnt vmcnt(8)
	ds_write_b128 v202, v[140:143] offset:13824
	s_waitcnt vmcnt(7)
	ds_write_b128 v202, v[144:147] offset:18432
	s_waitcnt vmcnt(6)
	ds_write_b128 v202, v[148:151] offset:23040
	s_waitcnt vmcnt(5)
	ds_write_b128 v202, v[152:155] offset:27648
	s_waitcnt vmcnt(4)
	ds_write_b128 v202, v[156:159] offset:32256
	s_waitcnt vmcnt(3)
	ds_write_b128 v202, v[160:163] offset:36864
	s_waitcnt vmcnt(2)
	ds_write_b128 v202, v[164:167] offset:41472
	s_waitcnt vmcnt(1)
	ds_write_b128 v202, v[168:171] offset:46080
	s_waitcnt vmcnt(0)
	ds_write_b128 v202, v[172:175] offset:50688
	s_waitcnt lgkmcnt(0)
	s_barrier
	ds_read_b128 v[128:131], v203 offset:4608
	ds_read_b128 v[132:135], v204 offset:23040
	ds_read_b128 v[136:139], v204 offset:27648
	ds_read_b128 v[140:143], v204 offset:32256
	ds_read_b128 v[144:147], v203
	ds_read_b128 v[148:151], v203 offset:32
	ds_read_b128 v[152:155], v204 offset:18432
	ds_read_b128 v[156:159], v204 offset:18464
	s_waitcnt lgkmcnt(1)
	v_mfma_f32_32x32x16_bf16 v[112:127], v[144:147], v[152:155], v[112:127]
	s_add_i32 s33, s33, s78
	s_add_i32 s16, s16, s17
	s_cmpk_lt_u32 s33, 0x100
	v_mfma_f32_32x32x16_bf16 v[96:111], v[144:147], v[132:135], v[96:111]
	v_mfma_f32_32x32x16_bf16 v[80:95], v[144:147], v[136:139], v[80:95]
	v_mfma_f32_32x32x16_bf16 v[64:79], v[144:147], v[140:143], v[64:79]
	v_mfma_f32_32x32x16_bf16 v[48:63], v[128:131], v[152:155], v[48:63]
	v_mfma_f32_32x32x16_bf16 v[32:47], v[128:131], v[132:135], v[32:47]
	v_mfma_f32_32x32x16_bf16 v[16:31], v[128:131], v[136:139], v[16:31]
	v_mfma_f32_32x32x16_bf16 v[0:15], v[128:131], v[140:143], v[0:15]
	ds_read_b128 v[128:131], v203 offset:4640
	ds_read_b128 v[132:135], v204 offset:23072
	ds_read_b128 v[136:139], v204 offset:27680
	ds_read_b128 v[140:143], v204 offset:32288
	s_waitcnt lgkmcnt(4)
	v_mfma_f32_32x32x16_bf16 v[112:127], v[148:151], v[156:159], v[112:127]
	s_waitcnt lgkmcnt(2)
	v_mfma_f32_32x32x16_bf16 v[96:111], v[148:151], v[132:135], v[96:111]
	s_waitcnt lgkmcnt(1)
	v_mfma_f32_32x32x16_bf16 v[80:95], v[148:151], v[136:139], v[80:95]
	s_waitcnt lgkmcnt(0)
	v_mfma_f32_32x32x16_bf16 v[64:79], v[148:151], v[140:143], v[64:79]
	v_mfma_f32_32x32x16_bf16 v[48:63], v[128:131], v[156:159], v[48:63]
	v_mfma_f32_32x32x16_bf16 v[32:47], v[128:131], v[132:135], v[32:47]
	v_mfma_f32_32x32x16_bf16 v[16:31], v[128:131], v[136:139], v[16:31]
	v_mfma_f32_32x32x16_bf16 v[0:15], v[128:131], v[140:143], v[0:15]
	ds_read_b128 v[128:131], v203 offset:64
	ds_read_b128 v[132:135], v203 offset:4672
	ds_read_b128 v[136:139], v204 offset:18496
	ds_read_b128 v[140:143], v204 offset:23104
	ds_read_b128 v[144:147], v204 offset:27712
	ds_read_b128 v[148:151], v204 offset:32320
	s_waitcnt lgkmcnt(3)
	v_mfma_f32_32x32x16_bf16 v[112:127], v[128:131], v[136:139], v[112:127]
	s_waitcnt lgkmcnt(2)
	v_mfma_f32_32x32x16_bf16 v[96:111], v[128:131], v[140:143], v[96:111]
	s_waitcnt lgkmcnt(1)
	v_mfma_f32_32x32x16_bf16 v[80:95], v[128:131], v[144:147], v[80:95]
	s_waitcnt lgkmcnt(0)
	v_mfma_f32_32x32x16_bf16 v[64:79], v[128:131], v[148:151], v[64:79]
	v_mfma_f32_32x32x16_bf16 v[48:63], v[132:135], v[136:139], v[48:63]
	v_mfma_f32_32x32x16_bf16 v[32:47], v[132:135], v[140:143], v[32:47]
	v_mfma_f32_32x32x16_bf16 v[16:31], v[132:135], v[144:147], v[16:31]
	v_mfma_f32_32x32x16_bf16 v[0:15], v[132:135], v[148:151], v[0:15]
	ds_read_b128 v[128:131], v203 offset:96
	ds_read_b128 v[132:135], v203 offset:4704
	ds_read_b128 v[136:139], v204 offset:18528
	ds_read_b128 v[140:143], v204 offset:23136
	ds_read_b128 v[144:147], v204 offset:27744
	ds_read_b128 v[148:151], v204 offset:32352
	s_waitcnt lgkmcnt(0)
	s_barrier
	v_mfma_f32_32x32x16_bf16 v[112:127], v[128:131], v[136:139], v[112:127]
	v_mfma_f32_32x32x16_bf16 v[96:111], v[128:131], v[140:143], v[96:111]
	s_nop 10
	v_cvt_pk_bf16_f32 v112, v112, s0
	v_cvt_pk_bf16_f32 v114, v114, s0
	v_cvt_pk_bf16_f32 v116, v116, s0
	v_cvt_pk_bf16_f32 v118, v118, s0
	v_cvt_pk_bf16_f32 v120, v120, s0
	v_cvt_pk_bf16_f32 v122, v122, s0
	v_cvt_pk_bf16_f32 v124, v124, s0
	v_mfma_f32_32x32x16_bf16 v[80:95], v[128:131], v[144:147], v[80:95]
	v_cvt_pk_bf16_f32 v126, v126, s0
	v_cvt_pk_bf16_f32 v96, v96, s0
	v_cvt_pk_bf16_f32 v98, v98, s0
	v_mfma_f32_32x32x16_bf16 v[64:79], v[128:131], v[148:151], v[64:79]
	v_or_b32_e32 v128, s37, v179
	v_lshlrev_b32_e32 v182, 1, v128
	v_lshl_add_u64 v[128:129], s[52:53], 0, v[182:183]
	v_add_lshl_u32 v182, v181, s36, 11
	v_lshl_add_u64 v[130:131], v[128:129], 0, v[182:183]
	global_store_short v[130:131], v112, off
	v_cvt_pk_bf16_f32 v112, v113, s0
	v_mfma_f32_32x32x16_bf16 v[48:63], v[132:135], v[136:139], v[48:63]
	global_store_short v[130:131], v112, off offset:2048
	v_cvt_pk_bf16_f32 v136, v117, s0
	v_mov_b32_e32 v117, v183
	v_mov_b32_e32 v137, v183
	v_cvt_pk_bf16_f32 v138, v119, s0
	v_mov_b32_e32 v119, v183
	v_mov_b32_e32 v139, v183
	v_mfma_f32_32x32x16_bf16 v[32:47], v[132:135], v[140:143], v[32:47]
	v_cvt_pk_bf16_f32 v140, v121, s0
	v_mov_b32_e32 v121, v183
	v_mov_b32_e32 v141, v183
	v_cvt_pk_bf16_f32 v142, v123, s0
	v_mov_b32_e32 v123, v183
	v_mov_b32_e32 v143, v183
	global_store_short v[130:131], v96, off offset:64
	v_mfma_f32_32x32x16_bf16 v[16:31], v[132:135], v[144:147], v[16:31]
	v_cvt_pk_bf16_f32 v144, v125, s0
	v_mov_b32_e32 v125, v183
	v_mov_b32_e32 v145, v183
	v_cvt_pk_bf16_f32 v146, v127, s0
	v_mov_b32_e32 v127, v183
	v_cvt_pk_bf16_f32 v96, v97, s0
; DI int crow(int i, int h) { return (i & 3) + 8 * (i >> 2) + 4 * h; }
;   DI void operator()(const f32x16& acc, int row0, int col0, int lane) const {
;     const int r = lane & 31, h = lane >> 5, col = col0 + r;
;     if (col >= N) return;
; #pragma unroll
;     for (int i = 0; i < 16; ++i) C[(size_t)(row0 + crow(i, h)) * ldc + col] = f2bf(acc[i]);
	global_store_short v[130:131], v96, off offset:2112
	v_mfma_f32_32x32x16_bf16 v[0:15], v[132:135], v[148:151], v[0:15]
	v_or_b32_e32 v132, 0x1000, v182
	v_mov_b32_e32 v133, v183
	v_lshl_add_u64 v[112:113], v[128:129], 0, v[132:133]
	global_store_short v[112:113], v114, off
	v_cvt_pk_bf16_f32 v134, v115, s0
	v_or_b32_e32 v114, 0x1800, v182
	v_mov_b32_e32 v115, v183
	v_lshl_add_u64 v[112:113], v[128:129], 0, v[114:115]
	global_store_short v[112:113], v134, off
	v_or_b32_e32 v134, 0x4000, v182
	v_mov_b32_e32 v135, v183
	v_lshl_add_u64 v[112:113], v[128:129], 0, v[134:135]
	global_store_short v[112:113], v116, off
	v_or_b32_e32 v116, 0x4800, v182
	v_lshl_add_u64 v[112:113], v[128:129], 0, v[116:117]
	global_store_short v[112:113], v136, off
	v_or_b32_e32 v136, 0x5000, v182
	v_lshl_add_u64 v[112:113], v[128:129], 0, v[136:137]
	global_store_short v[112:113], v118, off
	v_or_b32_e32 v118, 0x5800, v182
	v_lshl_add_u64 v[112:113], v[128:129], 0, v[118:119]
	global_store_short v[112:113], v138, off
	v_or_b32_e32 v138, 0x8000, v182
	v_lshl_add_u64 v[112:113], v[128:129], 0, v[138:139]
	global_store_short v[112:113], v120, off
	v_or_b32_e32 v120, 0x8800, v182
	v_lshl_add_u64 v[112:113], v[128:129], 0, v[120:121]
	global_store_short v[112:113], v140, off
	v_or_b32_e32 v140, 0x9000, v182
	v_lshl_add_u64 v[112:113], v[128:129], 0, v[140:141]
	global_store_short v[112:113], v122, off
	v_or_b32_e32 v122, 0x9800, v182
	v_lshl_add_u64 v[112:113], v[128:129], 0, v[122:123]
	global_store_short v[112:113], v142, off
	v_or_b32_e32 v142, 0xc000, v182
	v_lshl_add_u64 v[112:113], v[128:129], 0, v[142:143]
	global_store_short v[112:113], v124, off
	v_or_b32_e32 v124, 0xc800, v182
	v_lshl_add_u64 v[112:113], v[128:129], 0, v[124:125]
	global_store_short v[112:113], v144, off
	v_or_b32_e32 v144, 0xd000, v182
	v_lshl_add_u64 v[112:113], v[128:129], 0, v[144:145]
	global_store_short v[112:113], v126, off
	v_or_b32_e32 v126, 0xd800, v182
	v_lshl_add_u64 v[112:113], v[128:129], 0, v[126:127]
	global_store_short v[112:113], v146, off
	v_lshl_add_u64 v[112:113], v[128:129], 0, 64
	v_lshl_add_u64 v[96:97], v[112:113], 0, v[132:133]
	global_store_short v[96:97], v98, off
	v_cvt_pk_bf16_f32 v98, v99, s0
	v_lshl_add_u64 v[96:97], v[112:113], 0, v[114:115]
	global_store_short v[96:97], v98, off
	v_cvt_pk_bf16_f32 v98, v100, s0
	v_lshl_add_u64 v[96:97], v[112:113], 0, v[134:135]
	global_store_short v[96:97], v98, off
	v_cvt_pk_bf16_f32 v98, v101, s0
	v_lshl_add_u64 v[96:97], v[112:113], 0, v[116:117]
	global_store_short v[96:97], v98, off
	v_cvt_pk_bf16_f32 v98, v102, s0
	v_lshl_add_u64 v[96:97], v[112:113], 0, v[136:137]
	global_store_short v[96:97], v98, off
	v_cvt_pk_bf16_f32 v98, v103, s0
	v_lshl_add_u64 v[96:97], v[112:113], 0, v[118:119]
	global_store_short v[96:97], v98, off
	v_cvt_pk_bf16_f32 v98, v104, s0
	v_lshl_add_u64 v[96:97], v[112:113], 0, v[138:139]
	global_store_short v[96:97], v98, off
	v_cvt_pk_bf16_f32 v98, v105, s0
	v_lshl_add_u64 v[96:97], v[112:113], 0, v[120:121]
	global_store_short v[96:97], v98, off
	v_cvt_pk_bf16_f32 v98, v106, s0
	v_lshl_add_u64 v[96:97], v[112:113], 0, v[140:141]
	global_store_short v[96:97], v98, off
	v_cvt_pk_bf16_f32 v98, v107, s0
	v_lshl_add_u64 v[96:97], v[112:113], 0, v[122:123]
	global_store_short v[96:97], v98, off
	v_cvt_pk_bf16_f32 v98, v108, s0
	v_lshl_add_u64 v[96:97], v[112:113], 0, v[142:143]
	global_store_short v[96:97], v98, off
	v_cvt_pk_bf16_f32 v98, v109, s0
	v_lshl_add_u64 v[96:97], v[112:113], 0, v[124:125]
	global_store_short v[96:97], v98, off
	v_cvt_pk_bf16_f32 v98, v110, s0
	v_lshl_add_u64 v[96:97], v[112:113], 0, v[144:145]
	global_store_short v[96:97], v98, off
	v_cvt_pk_bf16_f32 v98, v111, s0
	v_lshl_add_u64 v[96:97], v[112:113], 0, v[126:127]
	v_cvt_pk_bf16_f32 v80, v80, s0
	global_store_short v[96:97], v98, off
	v_lshl_add_u64 v[96:97], v[128:129], 0, s[6:7]
	global_store_short v[130:131], v80, off offset:128
	v_cvt_pk_bf16_f32 v80, v81, s0
	global_store_short v[130:131], v80, off offset:2176
	v_cvt_pk_bf16_f32 v82, v82, s0
	v_lshl_add_u64 v[80:81], v[96:97], 0, v[132:133]
	global_store_short v[80:81], v82, off
	v_cvt_pk_bf16_f32 v82, v83, s0
	v_lshl_add_u64 v[80:81], v[96:97], 0, v[114:115]
	global_store_short v[80:81], v82, off
	v_cvt_pk_bf16_f32 v82, v84, s0
	v_lshl_add_u64 v[80:81], v[96:97], 0, v[134:135]
	global_store_short v[80:81], v82, off
	v_cvt_pk_bf16_f32 v82, v85, s0
	v_lshl_add_u64 v[80:81], v[96:97], 0, v[116:117]
	global_store_short v[80:81], v82, off
	v_cvt_pk_bf16_f32 v82, v86, s0
	v_lshl_add_u64 v[80:81], v[96:97], 0, v[136:137]
	global_store_short v[80:81], v82, off
	v_cvt_pk_bf16_f32 v82, v87, s0
	v_lshl_add_u64 v[80:81], v[96:97], 0, v[118:119]
	global_store_short v[80:81], v82, off
	v_cvt_pk_bf16_f32 v82, v88, s0
	v_lshl_add_u64 v[80:81], v[96:97], 0, v[138:139]
	global_store_short v[80:81], v82, off
	v_cvt_pk_bf16_f32 v82, v89, s0
	v_lshl_add_u64 v[80:81], v[96:97], 0, v[120:121]
	global_store_short v[80:81], v82, off
	v_cvt_pk_bf16_f32 v82, v90, s0
	v_lshl_add_u64 v[80:81], v[96:97], 0, v[140:141]
	global_store_short v[80:81], v82, off
	v_cvt_pk_bf16_f32 v82, v91, s0
	v_lshl_add_u64 v[80:81], v[96:97], 0, v[122:123]
	global_store_short v[80:81], v82, off
	v_cvt_pk_bf16_f32 v82, v92, s0
	v_lshl_add_u64 v[80:81], v[96:97], 0, v[142:143]
	global_store_short v[80:81], v82, off
	v_cvt_pk_bf16_f32 v82, v93, s0
	v_lshl_add_u64 v[80:81], v[96:97], 0, v[124:125]
	global_store_short v[80:81], v82, off
	v_cvt_pk_bf16_f32 v82, v94, s0
	v_lshl_add_u64 v[80:81], v[96:97], 0, v[144:145]
	global_store_short v[80:81], v82, off
	v_cvt_pk_bf16_f32 v82, v95, s0
	v_lshl_add_u64 v[80:81], v[96:97], 0, v[126:127]
; DI int crow(int i, int h) { return (i & 3) + 8 * (i >> 2) + 4 * h; }
;   DI void operator()(const f32x16& acc, int row0, int col0, int lane) const {
;     const int r = lane & 31, h = lane >> 5, col = col0 + r;
;     if (col >= N) return;
; #pragma unroll
;     for (int i = 0; i < 16; ++i) C[(size_t)(row0 + crow(i, h)) * ldc + col] = f2bf(acc[i]);
	v_cvt_pk_bf16_f32 v64, v64, s0
	global_store_short v[80:81], v82, off
	v_lshl_add_u64 v[80:81], v[128:129], 0, s[12:13]
	global_store_short v[130:131], v64, off offset:192
	v_cvt_pk_bf16_f32 v64, v65, s0
	global_store_short v[130:131], v64, off offset:2240
	v_cvt_pk_bf16_f32 v66, v66, s0
	v_lshl_add_u64 v[64:65], v[80:81], 0, v[132:133]
	global_store_short v[64:65], v66, off
	v_cvt_pk_bf16_f32 v66, v67, s0
	v_lshl_add_u64 v[64:65], v[80:81], 0, v[114:115]
	global_store_short v[64:65], v66, off
	v_cvt_pk_bf16_f32 v66, v68, s0
	v_lshl_add_u64 v[64:65], v[80:81], 0, v[134:135]
	global_store_short v[64:65], v66, off
	v_cvt_pk_bf16_f32 v66, v69, s0
	v_lshl_add_u64 v[64:65], v[80:81], 0, v[116:117]
	global_store_short v[64:65], v66, off
	v_cvt_pk_bf16_f32 v66, v70, s0
	v_lshl_add_u64 v[64:65], v[80:81], 0, v[136:137]
	global_store_short v[64:65], v66, off
	v_cvt_pk_bf16_f32 v66, v71, s0
	v_lshl_add_u64 v[64:65], v[80:81], 0, v[118:119]
	global_store_short v[64:65], v66, off
	v_cvt_pk_bf16_f32 v66, v72, s0
	v_lshl_add_u64 v[64:65], v[80:81], 0, v[138:139]
	global_store_short v[64:65], v66, off
	v_cvt_pk_bf16_f32 v66, v73, s0
	v_lshl_add_u64 v[64:65], v[80:81], 0, v[120:121]
	global_store_short v[64:65], v66, off
	v_cvt_pk_bf16_f32 v66, v74, s0
	v_lshl_add_u64 v[64:65], v[80:81], 0, v[140:141]
	global_store_short v[64:65], v66, off
	v_cvt_pk_bf16_f32 v66, v75, s0
	v_lshl_add_u64 v[64:65], v[80:81], 0, v[122:123]
	global_store_short v[64:65], v66, off
	v_cvt_pk_bf16_f32 v66, v76, s0
	v_lshl_add_u64 v[64:65], v[80:81], 0, v[142:143]
	global_store_short v[64:65], v66, off
	v_cvt_pk_bf16_f32 v66, v77, s0
	v_lshl_add_u64 v[64:65], v[80:81], 0, v[124:125]
	global_store_short v[64:65], v66, off
	v_cvt_pk_bf16_f32 v66, v78, s0
	v_lshl_add_u64 v[64:65], v[80:81], 0, v[144:145]
	global_store_short v[64:65], v66, off
	v_cvt_pk_bf16_f32 v66, v79, s0
	v_lshl_add_u64 v[64:65], v[80:81], 0, v[126:127]
	global_store_short v[64:65], v66, off
	v_or_b32_e32 v64, 0x10000, v182
	v_mov_b32_e32 v65, v183
	v_cvt_pk_bf16_f32 v48, v48, s0
	v_lshl_add_u64 v[66:67], v[128:129], 0, v[64:65]
	global_store_short v[66:67], v48, off
	v_cvt_pk_bf16_f32 v68, v49, s0
	v_or_b32_e32 v48, 0x10800, v182
	v_mov_b32_e32 v49, v183
	v_lshl_add_u64 v[66:67], v[128:129], 0, v[48:49]
	global_store_short v[66:67], v68, off
	v_or_b32_e32 v66, 0x11000, v182
	v_mov_b32_e32 v67, v183
	v_cvt_pk_bf16_f32 v50, v50, s0
	v_lshl_add_u64 v[68:69], v[128:129], 0, v[66:67]
	global_store_short v[68:69], v50, off
	v_cvt_pk_bf16_f32 v70, v51, s0
	v_or_b32_e32 v50, 0x11800, v182
	v_mov_b32_e32 v51, v183
	v_lshl_add_u64 v[68:69], v[128:129], 0, v[50:51]
	global_store_short v[68:69], v70, off
	v_or_b32_e32 v68, 0x14000, v182
	v_mov_b32_e32 v69, v183
	v_cvt_pk_bf16_f32 v52, v52, s0
	v_lshl_add_u64 v[70:71], v[128:129], 0, v[68:69]
	global_store_short v[70:71], v52, off
	v_cvt_pk_bf16_f32 v72, v53, s0
	v_or_b32_e32 v52, 0x14800, v182
	v_mov_b32_e32 v53, v183
	v_lshl_add_u64 v[70:71], v[128:129], 0, v[52:53]
	global_store_short v[70:71], v72, off
	v_or_b32_e32 v70, 0x15000, v182
	v_mov_b32_e32 v71, v183
	v_cvt_pk_bf16_f32 v54, v54, s0
	v_lshl_add_u64 v[72:73], v[128:129], 0, v[70:71]
	global_store_short v[72:73], v54, off
	v_cvt_pk_bf16_f32 v74, v55, s0
	v_or_b32_e32 v54, 0x15800, v182
	v_mov_b32_e32 v55, v183
	v_lshl_add_u64 v[72:73], v[128:129], 0, v[54:55]
	global_store_short v[72:73], v74, off
	v_or_b32_e32 v72, 0x18000, v182
	v_mov_b32_e32 v73, v183
	v_cvt_pk_bf16_f32 v56, v56, s0
	v_lshl_add_u64 v[74:75], v[128:129], 0, v[72:73]
	global_store_short v[74:75], v56, off
	v_cvt_pk_bf16_f32 v76, v57, s0
	v_or_b32_e32 v56, 0x18800, v182
	v_mov_b32_e32 v57, v183
	v_lshl_add_u64 v[74:75], v[128:129], 0, v[56:57]
	global_store_short v[74:75], v76, off
	v_or_b32_e32 v74, 0x19000, v182
	v_mov_b32_e32 v75, v183
	v_cvt_pk_bf16_f32 v58, v58, s0
	v_lshl_add_u64 v[76:77], v[128:129], 0, v[74:75]
	global_store_short v[76:77], v58, off
	v_cvt_pk_bf16_f32 v78, v59, s0
	v_or_b32_e32 v58, 0x19800, v182
	v_mov_b32_e32 v59, v183
	v_lshl_add_u64 v[76:77], v[128:129], 0, v[58:59]
	global_store_short v[76:77], v78, off
	v_or_b32_e32 v76, 0x1c000, v182
	v_mov_b32_e32 v77, v183
	v_cvt_pk_bf16_f32 v60, v60, s0
	v_lshl_add_u64 v[78:79], v[128:129], 0, v[76:77]
	global_store_short v[78:79], v60, off
	v_cvt_pk_bf16_f32 v82, v61, s0
	v_or_b32_e32 v60, 0x1c800, v182
	v_mov_b32_e32 v61, v183
	v_lshl_add_u64 v[78:79], v[128:129], 0, v[60:61]
	global_store_short v[78:79], v82, off
	v_or_b32_e32 v78, 0x1d000, v182
	v_mov_b32_e32 v79, v183
	v_cvt_pk_bf16_f32 v62, v62, s0
	v_lshl_add_u64 v[82:83], v[128:129], 0, v[78:79]
	v_or_b32_e32 v182, 0x1d800, v182
	global_store_short v[82:83], v62, off
	v_cvt_pk_bf16_f32 v82, v63, s0
	v_lshl_add_u64 v[62:63], v[128:129], 0, v[182:183]
	global_store_short v[62:63], v82, off
	v_cvt_pk_bf16_f32 v32, v32, s0
	v_lshl_add_u64 v[62:63], v[112:113], 0, v[64:65]
	global_store_short v[62:63], v32, off
	v_cvt_pk_bf16_f32 v62, v33, s0
	v_lshl_add_u64 v[32:33], v[112:113], 0, v[48:49]
	global_store_short v[32:33], v62, off
	v_cvt_pk_bf16_f32 v34, v34, s0
	v_lshl_add_u64 v[32:33], v[112:113], 0, v[66:67]
	global_store_short v[32:33], v34, off
	v_cvt_pk_bf16_f32 v34, v35, s0
	v_lshl_add_u64 v[32:33], v[112:113], 0, v[50:51]
; DI int crow(int i, int h) { return (i & 3) + 8 * (i >> 2) + 4 * h; }
;   DI void operator()(const f32x16& acc, int row0, int col0, int lane) const {
;     const int r = lane & 31, h = lane >> 5, col = col0 + r;
;     if (col >= N) return;
; #pragma unroll
;     for (int i = 0; i < 16; ++i) C[(size_t)(row0 + crow(i, h)) * ldc + col] = f2bf(acc[i]);
;     ...
;       for (int q = lb; q < 64 * ntn; q += nlb) {
;         const int tm = x * 64 + q / ntn, tn = q % ntn;
;         gemm_tile<NTM>(A, lda, Bt, ldb, K, tm * 128, tn * (64 * NTM), epi, smem);
;       }
	global_store_short v[32:33], v34, off
	v_cvt_pk_bf16_f32 v34, v36, s0
	v_lshl_add_u64 v[32:33], v[112:113], 0, v[68:69]
	global_store_short v[32:33], v34, off
	v_cvt_pk_bf16_f32 v34, v37, s0
	v_lshl_add_u64 v[32:33], v[112:113], 0, v[52:53]
	global_store_short v[32:33], v34, off
	v_cvt_pk_bf16_f32 v34, v38, s0
	v_lshl_add_u64 v[32:33], v[112:113], 0, v[70:71]
	global_store_short v[32:33], v34, off
	v_cvt_pk_bf16_f32 v34, v39, s0
	v_lshl_add_u64 v[32:33], v[112:113], 0, v[54:55]
	global_store_short v[32:33], v34, off
	v_cvt_pk_bf16_f32 v34, v40, s0
	v_lshl_add_u64 v[32:33], v[112:113], 0, v[72:73]
	global_store_short v[32:33], v34, off
	v_cvt_pk_bf16_f32 v34, v41, s0
	v_lshl_add_u64 v[32:33], v[112:113], 0, v[56:57]
	global_store_short v[32:33], v34, off
	v_cvt_pk_bf16_f32 v34, v42, s0
	v_lshl_add_u64 v[32:33], v[112:113], 0, v[74:75]
	global_store_short v[32:33], v34, off
	v_cvt_pk_bf16_f32 v34, v43, s0
	v_lshl_add_u64 v[32:33], v[112:113], 0, v[58:59]
	global_store_short v[32:33], v34, off
	v_cvt_pk_bf16_f32 v34, v44, s0
	v_lshl_add_u64 v[32:33], v[112:113], 0, v[76:77]
	global_store_short v[32:33], v34, off
	v_cvt_pk_bf16_f32 v34, v45, s0
	v_lshl_add_u64 v[32:33], v[112:113], 0, v[60:61]
	global_store_short v[32:33], v34, off
	v_cvt_pk_bf16_f32 v34, v46, s0
	v_lshl_add_u64 v[32:33], v[112:113], 0, v[78:79]
	global_store_short v[32:33], v34, off
	v_cvt_pk_bf16_f32 v34, v47, s0
	v_lshl_add_u64 v[32:33], v[112:113], 0, v[182:183]
	global_store_short v[32:33], v34, off
	v_cvt_pk_bf16_f32 v16, v16, s0
	v_lshl_add_u64 v[32:33], v[96:97], 0, v[64:65]
	global_store_short v[32:33], v16, off
	v_cvt_pk_bf16_f32 v32, v17, s0
	v_lshl_add_u64 v[16:17], v[96:97], 0, v[48:49]
	global_store_short v[16:17], v32, off
	v_cvt_pk_bf16_f32 v18, v18, s0
	v_lshl_add_u64 v[16:17], v[96:97], 0, v[66:67]
	global_store_short v[16:17], v18, off
	v_cvt_pk_bf16_f32 v18, v19, s0
	v_lshl_add_u64 v[16:17], v[96:97], 0, v[50:51]
	global_store_short v[16:17], v18, off
	v_cvt_pk_bf16_f32 v18, v20, s0
	v_lshl_add_u64 v[16:17], v[96:97], 0, v[68:69]
	global_store_short v[16:17], v18, off
	v_cvt_pk_bf16_f32 v18, v21, s0
	v_lshl_add_u64 v[16:17], v[96:97], 0, v[52:53]
	global_store_short v[16:17], v18, off
	v_cvt_pk_bf16_f32 v18, v22, s0
	v_lshl_add_u64 v[16:17], v[96:97], 0, v[70:71]
	global_store_short v[16:17], v18, off
	v_cvt_pk_bf16_f32 v18, v23, s0
	v_lshl_add_u64 v[16:17], v[96:97], 0, v[54:55]
	global_store_short v[16:17], v18, off
	v_cvt_pk_bf16_f32 v18, v24, s0
	v_lshl_add_u64 v[16:17], v[96:97], 0, v[72:73]
	global_store_short v[16:17], v18, off
	v_cvt_pk_bf16_f32 v18, v25, s0
	v_lshl_add_u64 v[16:17], v[96:97], 0, v[56:57]
	global_store_short v[16:17], v18, off
	v_cvt_pk_bf16_f32 v18, v26, s0
	v_lshl_add_u64 v[16:17], v[96:97], 0, v[74:75]
	global_store_short v[16:17], v18, off
	v_cvt_pk_bf16_f32 v18, v27, s0
	v_lshl_add_u64 v[16:17], v[96:97], 0, v[58:59]
	global_store_short v[16:17], v18, off
	v_cvt_pk_bf16_f32 v18, v28, s0
	v_lshl_add_u64 v[16:17], v[96:97], 0, v[76:77]
	global_store_short v[16:17], v18, off
	v_cvt_pk_bf16_f32 v18, v29, s0
	v_lshl_add_u64 v[16:17], v[96:97], 0, v[60:61]
	global_store_short v[16:17], v18, off
	v_cvt_pk_bf16_f32 v18, v30, s0
	v_lshl_add_u64 v[16:17], v[96:97], 0, v[78:79]
	global_store_short v[16:17], v18, off
	v_cvt_pk_bf16_f32 v18, v31, s0
	v_lshl_add_u64 v[16:17], v[96:97], 0, v[182:183]
	global_store_short v[16:17], v18, off
	v_cvt_pk_bf16_f32 v0, v0, s0
	v_lshl_add_u64 v[16:17], v[80:81], 0, v[64:65]
	global_store_short v[16:17], v0, off
	v_cvt_pk_bf16_f32 v16, v1, s0
	v_lshl_add_u64 v[0:1], v[80:81], 0, v[48:49]
	global_store_short v[0:1], v16, off
	v_cvt_pk_bf16_f32 v2, v2, s0
	v_lshl_add_u64 v[0:1], v[80:81], 0, v[66:67]
	global_store_short v[0:1], v2, off
	v_cvt_pk_bf16_f32 v2, v3, s0
	v_lshl_add_u64 v[0:1], v[80:81], 0, v[50:51]
	global_store_short v[0:1], v2, off
	v_cvt_pk_bf16_f32 v2, v4, s0
	v_lshl_add_u64 v[0:1], v[80:81], 0, v[68:69]
	global_store_short v[0:1], v2, off
	v_cvt_pk_bf16_f32 v2, v5, s0
	v_lshl_add_u64 v[0:1], v[80:81], 0, v[52:53]
	global_store_short v[0:1], v2, off
	v_cvt_pk_bf16_f32 v2, v6, s0
	v_lshl_add_u64 v[0:1], v[80:81], 0, v[70:71]
	global_store_short v[0:1], v2, off
	v_cvt_pk_bf16_f32 v2, v7, s0
	v_lshl_add_u64 v[0:1], v[80:81], 0, v[54:55]
	global_store_short v[0:1], v2, off
	v_cvt_pk_bf16_f32 v2, v8, s0
	v_lshl_add_u64 v[0:1], v[80:81], 0, v[72:73]
	global_store_short v[0:1], v2, off
	v_cvt_pk_bf16_f32 v2, v9, s0
	v_lshl_add_u64 v[0:1], v[80:81], 0, v[56:57]
	global_store_short v[0:1], v2, off
	v_cvt_pk_bf16_f32 v2, v10, s0
	v_lshl_add_u64 v[0:1], v[80:81], 0, v[74:75]
	global_store_short v[0:1], v2, off
	v_cvt_pk_bf16_f32 v2, v11, s0
	v_lshl_add_u64 v[0:1], v[80:81], 0, v[58:59]
	global_store_short v[0:1], v2, off
	v_cvt_pk_bf16_f32 v2, v12, s0
	v_lshl_add_u64 v[0:1], v[80:81], 0, v[76:77]
	global_store_short v[0:1], v2, off
	v_cvt_pk_bf16_f32 v2, v13, s0
	v_lshl_add_u64 v[0:1], v[80:81], 0, v[60:61]
	global_store_short v[0:1], v2, off
	v_cvt_pk_bf16_f32 v2, v14, s0
	v_lshl_add_u64 v[0:1], v[80:81], 0, v[78:79]
	global_store_short v[0:1], v2, off
	v_cvt_pk_bf16_f32 v2, v15, s0
	v_lshl_add_u64 v[0:1], v[80:81], 0, v[182:183]
	global_store_short v[0:1], v2, off
	s_cbranch_scc1 .LBB0_675
